# E23 variant: alternate chains issue their second k-half first, so the weight fragment register is reused by adjacent MFMAs at every chain boundary (f32 accumulation, order of the two k-halves swapped
# speedup vs baseline: 1.0027x; 1.0027x over previous
;     __device__ __forceinline__ int nt(const Unit& u) const { return (u.pn >> 1) < 2 ? 22 : 20; }
; #define PG8_STAGE(bufoff, gbase, voff) do { _Pragma("unroll") for (int _i = 0; _i < 2; ++_i) \
;         __builtin_amdgcn_global_load_lds((const unsigned*)((const char*)(gbase) + (voff)[_i]), (LAS unsigned*)(lds + (bufoff) + ldsw + _i * 8192), 16, 0, 0); } while (0)
; #define PG8_LDA(dst, b, h) do { _Pragma("unroll") for (int m = 0; m < 4; ++m) _Pragma("unroll") for (int k = 0; k < 2; ++k) dst[m][k] = *(const LAS bf16x8*)(pA + PG8_SA(b, h) + m * 2048 + k * 1024); } while (0)
; #define PG8_LDB(dst, b, h) do { _Pragma("unroll") for (int n = 0; n < 2; ++n) _Pragma("unroll") for (int k = 0; k < 2; ++k) dst[n][k] = *(const LAS bf16x8*)(pB + (PG8_SB(b, h) - 4 * HTB) + n * 2048 + k * 1024); } while (0)
; #define PG8_MMA(ai, bj, At, Bt) do { __builtin_amdgcn_s_setprio(1); _Pragma("unroll") for (int m = 0; m < 4; ++m) _Pragma("unroll") for (int n = 0; n < 2; ++n) _Pragma("unroll") for (int k = 0; k < 2; ++k) \
;         acc[ai][bj][m][n] = __builtin_amdgcn_mfma_f32_16x16x32_bf16(Bt[n][k], At[m][k], acc[ai][bj][m][n], 0, 0, 0); __builtin_amdgcn_s_setprio(0); } while (0)
; #define PG8_WAIT_V(n) asm volatile("s_waitcnt vmcnt(" #n ")" ::: "memory")
; #define PG8_WAIT_L(n) asm volatile("s_waitcnt lgkmcnt(" #n ")" ::: "memory")
; template <class Desc, class Epi, bool ALIGN_EPI>
; __device__ __forceinline__ void gemm_phase(LAS unsigned char* lds, const Desc& D, const Epi& E, int G, int c) {
;     ...
;             const bool last = (t == nt - 2);
;             if (last && has_next) PG8_AWAIT(nxt);
;             const char* a1 = cA + (size_t)(t + 1) * kstep;
;             const char* a2 = last ? nA : cA + (size_t)(t + 2) * kstep; const char* b2 = last ? nB : cB + (size_t)(t + 2) * kstep;
;             const char* a3 = a2 + kstep; const char* b3 = b2 + kstep;
;             PG8_LDB(B0, 0, 0); PG8_LDB(B1, 0, 1); PG8_SCHED; PG8_LDA(At, 0, 0); PG8_STAGE(PG8_SA(1, 1), a1 + hstepA, voffA);
;             PG8_WAIT_V(8); PG8_WAIT_L(0); PG8_BAR; PG8_MMA(0, 0, At, B0); PG8_MMA(0, 1, At, B1); PG8_BAR; PG8_SCHED;
;             PG8_LDA(At, 0, 1); PG8_STAGE(PG8_SB(0, 0), b2, voffB); PG8_STAGE(PG8_SB(0, 1), b2 + hstepB, voffB); PG8_STAGE(PG8_SA(0, 0), a2, voffA);
;             PG8_WAIT_V(8); PG8_WAIT_L(0); PG8_BAR; PG8_MMA(1, 0, At, B0); PG8_MMA(1, 1, At, B1); PG8_BAR; PG8_SCHED;
.LBB0_172:
	s_or_b32 s14, s17, 1
	s_lshl_b64 s[26:27], s[14:15], 7
	s_add_i32 s14, s17, 2
	s_lshl_b64 s[40:41], s[14:15], 7
	s_add_u32 s17, s12, s40
	ds_read_b128 v[134:137], v169
	ds_read_b128 v[138:141], v169 offset:1024
	ds_read_b128 v[142:145], v169 offset:2048
	ds_read_b128 v[146:149], v169 offset:3072
	ds_read_b128 v[160:163], v169 offset:16384
	ds_read_b128 v[164:167], v169 offset:17408
	ds_read_b128 v[174:177], v169 offset:18432
	ds_read_b128 v[178:181], v169 offset:19456
	s_addc_u32 s21, s13, s41
	s_and_b64 s[38:39], s[30:31], exec
	s_cselect_b32 s39, s61, s21
	s_cselect_b32 s38, s60, s17
	s_add_u32 s17, s18, s40
	s_addc_u32 s21, s19, s41
	s_and_b64 s[30:31], s[30:31], exec
	s_cselect_b32 s31, s63, s21
	s_cselect_b32 s30, s62, s17
	s_add_u32 s17, s12, s26
	s_addc_u32 s21, s13, s27
	s_add_u32 s26, s17, 0x100000
	s_addc_u32 s27, s21, 0
	s_mov_b32 m0, s50
	v_lshl_add_u64 v[150:151], s[26:27], 0, v[152:153]
	ds_read_b128 v[182:185], v168
	ds_read_b128 v[186:189], v168 offset:1024
	ds_read_b128 v[190:193], v168 offset:2048
	ds_read_b128 v[194:197], v168 offset:3072
	ds_read_b128 v[198:201], v168 offset:4096
	ds_read_b128 v[202:205], v168 offset:5120
	ds_read_b128 v[206:209], v168 offset:6144
	ds_read_b128 v[210:213], v168 offset:7168
	global_load_lds_dwordx4 v[150:151], off
	v_lshl_add_u64 v[150:151], s[26:27], 0, v[156:157]
	s_mov_b32 m0, s51
	s_nop 0
	global_load_lds_dwordx4 v[150:151], off
	s_waitcnt vmcnt(8)
	s_waitcnt lgkmcnt(0)
	s_barrier
	v_mfma_f32_16x16x32_bf16 v[128:131], v[134:137], v[182:185], v[128:131]
	v_mfma_f32_16x16x32_bf16 v[128:131], v[138:141], v[186:189], v[128:131]
	v_mfma_f32_16x16x32_bf16 v[120:123], v[138:141], v[194:197], v[120:123]
	v_mfma_f32_16x16x32_bf16 v[120:123], v[134:137], v[190:193], v[120:123]
	v_mfma_f32_16x16x32_bf16 v[112:115], v[134:137], v[198:201], v[112:115]
	v_mfma_f32_16x16x32_bf16 v[112:115], v[138:141], v[202:205], v[112:115]
	v_mfma_f32_16x16x32_bf16 v[104:107], v[138:141], v[210:213], v[104:107]
	v_mfma_f32_16x16x32_bf16 v[104:107], v[134:137], v[206:209], v[104:107]
	v_mfma_f32_16x16x32_bf16 v[100:103], v[142:145], v[206:209], v[100:103]
	v_mfma_f32_16x16x32_bf16 v[100:103], v[146:149], v[210:213], v[100:103]
	v_mfma_f32_16x16x32_bf16 v[108:111], v[146:149], v[202:205], v[108:111]
	v_mfma_f32_16x16x32_bf16 v[108:111], v[142:145], v[198:201], v[108:111]
	v_mfma_f32_16x16x32_bf16 v[116:119], v[142:145], v[190:193], v[116:119]
	v_mfma_f32_16x16x32_bf16 v[116:119], v[146:149], v[194:197], v[116:119]
	v_mfma_f32_16x16x32_bf16 v[124:127], v[146:149], v[186:189], v[124:127]
	v_mfma_f32_16x16x32_bf16 v[124:127], v[142:145], v[182:185], v[124:127]
	v_mfma_f32_16x16x32_bf16 v[96:99], v[160:163], v[182:185], v[96:99]
	v_mfma_f32_16x16x32_bf16 v[96:99], v[164:167], v[186:189], v[96:99]
	v_mfma_f32_16x16x32_bf16 v[88:91], v[164:167], v[194:197], v[88:91]
	v_mfma_f32_16x16x32_bf16 v[88:91], v[160:163], v[190:193], v[88:91]
	v_mfma_f32_16x16x32_bf16 v[80:83], v[160:163], v[198:201], v[80:83]
	v_mfma_f32_16x16x32_bf16 v[80:83], v[164:167], v[202:205], v[80:83]
	v_mfma_f32_16x16x32_bf16 v[72:75], v[164:167], v[210:213], v[72:75]
	v_mfma_f32_16x16x32_bf16 v[72:75], v[160:163], v[206:209], v[72:75]
	v_mfma_f32_16x16x32_bf16 v[68:71], v[174:177], v[206:209], v[68:71]
	v_mfma_f32_16x16x32_bf16 v[68:71], v[178:181], v[210:213], v[68:71]
	v_mfma_f32_16x16x32_bf16 v[76:79], v[178:181], v[202:205], v[76:79]
	v_mfma_f32_16x16x32_bf16 v[76:79], v[174:177], v[198:201], v[76:79]
	v_mfma_f32_16x16x32_bf16 v[84:87], v[174:177], v[190:193], v[84:87]
	v_mfma_f32_16x16x32_bf16 v[84:87], v[178:181], v[194:197], v[84:87]
	v_mfma_f32_16x16x32_bf16 v[92:95], v[178:181], v[186:189], v[92:95]
	v_mfma_f32_16x16x32_bf16 v[92:95], v[174:177], v[182:185], v[92:95]
	s_barrier
	s_mov_b32 m0, s84
	v_lshl_add_u64 v[150:151], s[30:31], 0, v[154:155]
	s_add_u32 s26, s30, 0x100000
	ds_read_b128 v[182:185], v168 offset:16384
	ds_read_b128 v[186:189], v168 offset:17408
	ds_read_b128 v[190:193], v168 offset:18432
	ds_read_b128 v[194:197], v168 offset:19456
	ds_read_b128 v[198:201], v168 offset:20480
	ds_read_b128 v[202:205], v168 offset:21504
	ds_read_b128 v[206:209], v168 offset:22528
	ds_read_b128 v[210:213], v168 offset:23552
	global_load_lds_dwordx4 v[150:151], off
	v_lshl_add_u64 v[214:215], s[30:31], 0, v[158:159]
	s_mov_b32 m0, s85
	s_addc_u32 s27, s31, 0
	global_load_lds_dwordx4 v[214:215], off
	v_lshl_add_u64 v[216:217], s[26:27], 0, v[154:155]
	s_mov_b32 m0, s86
	v_lshl_add_u64 v[218:219], s[38:39], 0, v[156:157]
	global_load_lds_dwordx4 v[216:217], off
	v_lshl_add_u64 v[216:217], s[26:27], 0, v[158:159]
	s_mov_b32 m0, s87
	s_nop 0
	global_load_lds_dwordx4 v[216:217], off
	v_lshl_add_u64 v[216:217], s[38:39], 0, v[152:153]
	s_mov_b32 m0, s83
	s_nop 0
	global_load_lds_dwordx4 v[216:217], off
	s_mov_b32 m0, s88
	s_nop 0
	global_load_lds_dwordx4 v[218:219], off
	s_waitcnt vmcnt(8)
	s_waitcnt lgkmcnt(0)
	s_barrier
; #define PG8_STAGE(bufoff, gbase, voff) do { _Pragma("unroll") for (int _i = 0; _i < 2; ++_i) \
;         __builtin_amdgcn_global_load_lds((const unsigned*)((const char*)(gbase) + (voff)[_i]), (LAS unsigned*)(lds + (bufoff) + ldsw + _i * 8192), 16, 0, 0); } while (0)
; #define PG8_LDA(dst, b, h) do { _Pragma("unroll") for (int m = 0; m < 4; ++m) _Pragma("unroll") for (int k = 0; k < 2; ++k) dst[m][k] = *(const LAS bf16x8*)(pA + PG8_SA(b, h) + m * 2048 + k * 1024); } while (0)
; #define PG8_LDB(dst, b, h) do { _Pragma("unroll") for (int n = 0; n < 2; ++n) _Pragma("unroll") for (int k = 0; k < 2; ++k) dst[n][k] = *(const LAS bf16x8*)(pB + (PG8_SB(b, h) - 4 * HTB) + n * 2048 + k * 1024); } while (0)
; #define PG8_MMA(ai, bj, At, Bt) do { __builtin_amdgcn_s_setprio(1); _Pragma("unroll") for (int m = 0; m < 4; ++m) _Pragma("unroll") for (int n = 0; n < 2; ++n) _Pragma("unroll") for (int k = 0; k < 2; ++k) \
;         acc[ai][bj][m][n] = __builtin_amdgcn_mfma_f32_16x16x32_bf16(Bt[n][k], At[m][k], acc[ai][bj][m][n], 0, 0, 0); __builtin_amdgcn_s_setprio(0); } while (0)
; #define PG8_WAIT_V(n) asm volatile("s_waitcnt vmcnt(" #n ")" ::: "memory")
; #define PG8_WAIT_L(n) asm volatile("s_waitcnt lgkmcnt(" #n ")" ::: "memory")
; #define PG8_BAR __builtin_amdgcn_s_barrier()
; #define PG8_SCHED __builtin_amdgcn_sched_barrier(0)
; template <class Desc, class Epi, bool ALIGN_EPI>
; __device__ __forceinline__ void gemm_phase(LAS unsigned char* lds, const Desc& D, const Epi& E, int G, int c) {
;     ...
;             PG8_WAIT_V(8); PG8_WAIT_L(0); PG8_BAR; PG8_MMA(1, 0, At, B0); PG8_MMA(1, 1, At, B1); PG8_BAR; PG8_SCHED;
;             PG8_LDB(B0, 1, 0); PG8_LDB(B1, 1, 1); PG8_SCHED; PG8_LDA(At, 1, 0); PG8_STAGE(PG8_SA(0, 1), a2 + hstepA, voffA);
;             PG8_WAIT_V(8); PG8_WAIT_L(0); PG8_BAR; PG8_MMA(0, 0, At, B0); PG8_MMA(0, 1, At, B1); PG8_BAR; PG8_SCHED;
	v_mfma_f32_16x16x32_bf16 v[64:67], v[134:137], v[182:185], v[64:67]
	v_mfma_f32_16x16x32_bf16 v[64:67], v[138:141], v[186:189], v[64:67]
	v_mfma_f32_16x16x32_bf16 v[32:35], v[138:141], v[194:197], v[32:35]
	v_mfma_f32_16x16x32_bf16 v[32:35], v[134:137], v[190:193], v[32:35]
	v_mfma_f32_16x16x32_bf16 v[16:19], v[134:137], v[198:201], v[16:19]
	v_mfma_f32_16x16x32_bf16 v[16:19], v[138:141], v[202:205], v[16:19]
	v_mfma_f32_16x16x32_bf16 v[8:11], v[138:141], v[210:213], v[8:11]
	v_mfma_f32_16x16x32_bf16 v[8:11], v[134:137], v[206:209], v[8:11]
	v_mfma_f32_16x16x32_bf16 v[4:7], v[142:145], v[206:209], v[4:7]
	v_mfma_f32_16x16x32_bf16 v[4:7], v[146:149], v[210:213], v[4:7]
	v_mfma_f32_16x16x32_bf16 v[12:15], v[146:149], v[202:205], v[12:15]
	v_mfma_f32_16x16x32_bf16 v[12:15], v[142:145], v[198:201], v[12:15]
	v_mfma_f32_16x16x32_bf16 v[20:23], v[142:145], v[190:193], v[20:23]
	v_mfma_f32_16x16x32_bf16 v[20:23], v[146:149], v[194:197], v[20:23]
	v_mfma_f32_16x16x32_bf16 v[52:55], v[146:149], v[186:189], v[52:55]
	v_mfma_f32_16x16x32_bf16 v[52:55], v[142:145], v[182:185], v[52:55]
	v_mfma_f32_16x16x32_bf16 v[60:63], v[160:163], v[182:185], v[60:63]
	v_mfma_f32_16x16x32_bf16 v[60:63], v[164:167], v[186:189], v[60:63]
	v_mfma_f32_16x16x32_bf16 v[48:51], v[164:167], v[194:197], v[48:51]
	v_mfma_f32_16x16x32_bf16 v[48:51], v[160:163], v[190:193], v[48:51]
	v_mfma_f32_16x16x32_bf16 v[40:43], v[160:163], v[198:201], v[40:43]
	v_mfma_f32_16x16x32_bf16 v[40:43], v[164:167], v[202:205], v[40:43]
	v_mfma_f32_16x16x32_bf16 v[28:31], v[164:167], v[210:213], v[28:31]
	v_mfma_f32_16x16x32_bf16 v[28:31], v[160:163], v[206:209], v[28:31]
	v_mfma_f32_16x16x32_bf16 v[24:27], v[174:177], v[206:209], v[24:27]
	v_mfma_f32_16x16x32_bf16 v[24:27], v[178:181], v[210:213], v[24:27]
	v_mfma_f32_16x16x32_bf16 v[36:39], v[178:181], v[202:205], v[36:39]
	v_mfma_f32_16x16x32_bf16 v[36:39], v[174:177], v[198:201], v[36:39]
	v_mfma_f32_16x16x32_bf16 v[44:47], v[174:177], v[190:193], v[44:47]
	v_mfma_f32_16x16x32_bf16 v[44:47], v[178:181], v[194:197], v[44:47]
	v_mfma_f32_16x16x32_bf16 v[56:59], v[178:181], v[186:189], v[56:59]
	v_mfma_f32_16x16x32_bf16 v[56:59], v[174:177], v[182:185], v[56:59]
	s_barrier
	ds_read_b128 v[134:137], v169 offset:32768
	ds_read_b128 v[138:141], v169 offset:33792
	ds_read_b128 v[142:145], v169 offset:34816
	ds_read_b128 v[146:149], v169 offset:35840
	ds_read_b128 v[160:163], v169 offset:49152
	ds_read_b128 v[164:167], v169 offset:50176
	ds_read_b128 v[174:177], v169 offset:51200
	ds_read_b128 v[178:181], v169 offset:52224
	s_add_u32 s26, s38, 0x100000
	s_addc_u32 s27, s39, 0
	s_mov_b32 m0, s89
	v_lshl_add_u64 v[220:221], s[26:27], 0, v[152:153]
	ds_read_b128 v[182:185], v168 offset:32768
	ds_read_b128 v[186:189], v168 offset:33792
	ds_read_b128 v[190:193], v168 offset:34816
	ds_read_b128 v[194:197], v168 offset:35840
	ds_read_b128 v[198:201], v168 offset:36864
	ds_read_b128 v[202:205], v168 offset:37888
	ds_read_b128 v[206:209], v168 offset:38912
	ds_read_b128 v[210:213], v168 offset:39936
	global_load_lds_dwordx4 v[220:221], off
	v_lshl_add_u64 v[220:221], s[26:27], 0, v[156:157]
	s_mov_b32 m0, s90
	s_nop 0
	global_load_lds_dwordx4 v[220:221], off
	s_waitcnt vmcnt(8)
	s_waitcnt lgkmcnt(0)
	s_barrier
	v_mfma_f32_16x16x32_bf16 v[128:131], v[134:137], v[182:185], v[128:131]
	v_mfma_f32_16x16x32_bf16 v[128:131], v[138:141], v[186:189], v[128:131]
	v_mfma_f32_16x16x32_bf16 v[120:123], v[138:141], v[194:197], v[120:123]
	v_mfma_f32_16x16x32_bf16 v[120:123], v[134:137], v[190:193], v[120:123]
	v_mfma_f32_16x16x32_bf16 v[112:115], v[134:137], v[198:201], v[112:115]
	v_mfma_f32_16x16x32_bf16 v[112:115], v[138:141], v[202:205], v[112:115]
	v_mfma_f32_16x16x32_bf16 v[104:107], v[138:141], v[210:213], v[104:107]
	v_mfma_f32_16x16x32_bf16 v[104:107], v[134:137], v[206:209], v[104:107]
	v_mfma_f32_16x16x32_bf16 v[100:103], v[142:145], v[206:209], v[100:103]
	v_mfma_f32_16x16x32_bf16 v[100:103], v[146:149], v[210:213], v[100:103]
	v_mfma_f32_16x16x32_bf16 v[108:111], v[146:149], v[202:205], v[108:111]
	v_mfma_f32_16x16x32_bf16 v[108:111], v[142:145], v[198:201], v[108:111]
	v_mfma_f32_16x16x32_bf16 v[116:119], v[142:145], v[190:193], v[116:119]
	v_mfma_f32_16x16x32_bf16 v[116:119], v[146:149], v[194:197], v[116:119]
	v_mfma_f32_16x16x32_bf16 v[124:127], v[146:149], v[186:189], v[124:127]
	v_mfma_f32_16x16x32_bf16 v[124:127], v[142:145], v[182:185], v[124:127]
	v_mfma_f32_16x16x32_bf16 v[96:99], v[160:163], v[182:185], v[96:99]
	v_mfma_f32_16x16x32_bf16 v[96:99], v[164:167], v[186:189], v[96:99]
	v_mfma_f32_16x16x32_bf16 v[88:91], v[164:167], v[194:197], v[88:91]
	v_mfma_f32_16x16x32_bf16 v[88:91], v[160:163], v[190:193], v[88:91]
	v_mfma_f32_16x16x32_bf16 v[80:83], v[160:163], v[198:201], v[80:83]
	v_mfma_f32_16x16x32_bf16 v[80:83], v[164:167], v[202:205], v[80:83]
	v_mfma_f32_16x16x32_bf16 v[72:75], v[164:167], v[210:213], v[72:75]
	v_mfma_f32_16x16x32_bf16 v[72:75], v[160:163], v[206:209], v[72:75]
	v_mfma_f32_16x16x32_bf16 v[68:71], v[174:177], v[206:209], v[68:71]
	v_mfma_f32_16x16x32_bf16 v[68:71], v[178:181], v[210:213], v[68:71]
	v_mfma_f32_16x16x32_bf16 v[76:79], v[178:181], v[202:205], v[76:79]
	v_mfma_f32_16x16x32_bf16 v[76:79], v[174:177], v[198:201], v[76:79]
	v_mfma_f32_16x16x32_bf16 v[84:87], v[174:177], v[190:193], v[84:87]
	v_mfma_f32_16x16x32_bf16 v[84:87], v[178:181], v[194:197], v[84:87]
	v_mfma_f32_16x16x32_bf16 v[92:95], v[178:181], v[186:189], v[92:95]
	v_mfma_f32_16x16x32_bf16 v[92:95], v[174:177], v[182:185], v[92:95]
	s_barrier
; #define PG8_STAGE(bufoff, gbase, voff) do { _Pragma("unroll") for (int _i = 0; _i < 2; ++_i) \
;         __builtin_amdgcn_global_load_lds((const unsigned*)((const char*)(gbase) + (voff)[_i]), (LAS unsigned*)(lds + (bufoff) + ldsw + _i * 8192), 16, 0, 0); } while (0)
; #define PG8_LDA(dst, b, h) do { _Pragma("unroll") for (int m = 0; m < 4; ++m) _Pragma("unroll") for (int k = 0; k < 2; ++k) dst[m][k] = *(const LAS bf16x8*)(pA + PG8_SA(b, h) + m * 2048 + k * 1024); } while (0)
; #define PG8_MMA(ai, bj, At, Bt) do { __builtin_amdgcn_s_setprio(1); _Pragma("unroll") for (int m = 0; m < 4; ++m) _Pragma("unroll") for (int n = 0; n < 2; ++n) _Pragma("unroll") for (int k = 0; k < 2; ++k) \
;         acc[ai][bj][m][n] = __builtin_amdgcn_mfma_f32_16x16x32_bf16(Bt[n][k], At[m][k], acc[ai][bj][m][n], 0, 0, 0); __builtin_amdgcn_s_setprio(0); } while (0)
; #define PG8_WAIT_V(n) asm volatile("s_waitcnt vmcnt(" #n ")" ::: "memory")
; #define PG8_WAIT_L(n) asm volatile("s_waitcnt lgkmcnt(" #n ")" ::: "memory")
; #define PG8_BAR __builtin_amdgcn_s_barrier()
; #define PG8_SCHED __builtin_amdgcn_sched_barrier(0)
; template <class Desc, class Epi, bool ALIGN_EPI>
; __device__ __forceinline__ void gemm_phase(LAS unsigned char* lds, const Desc& D, const Epi& E, int G, int c) {
;     ...
;             PG8_LDA(At, 1, 1); PG8_STAGE(PG8_SB(1, 0), b3, voffB); PG8_STAGE(PG8_SB(1, 1), b3 + hstepB, voffB); PG8_STAGE(PG8_SA(1, 0), a3, voffA);
;             PG8_WAIT_V(8); PG8_WAIT_L(0); PG8_BAR; PG8_MMA(1, 0, At, B0); PG8_MMA(1, 1, At, B1); PG8_BAR; PG8_SCHED;
;         }
	s_mov_b32 m0, s92
	v_lshl_add_u64 v[150:151], v[150:151], 0, s[76:77]
	s_add_u32 s26, s30, 0x100080
	ds_read_b128 v[182:185], v168 offset:49152
	ds_read_b128 v[186:189], v168 offset:50176
	ds_read_b128 v[190:193], v168 offset:51200
	ds_read_b128 v[194:197], v168 offset:52224
	ds_read_b128 v[198:201], v168 offset:53248
	ds_read_b128 v[202:205], v168 offset:54272
	ds_read_b128 v[206:209], v168 offset:55296
	ds_read_b128 v[210:213], v168 offset:56320
	global_load_lds_dwordx4 v[150:151], off
	v_lshl_add_u64 v[150:151], v[214:215], 0, s[76:77]
	s_mov_b32 m0, s93
	s_addc_u32 s27, s31, 0
	global_load_lds_dwordx4 v[150:151], off
	v_lshl_add_u64 v[150:151], s[26:27], 0, v[154:155]
	s_mov_b32 m0, s97
	s_nop 0
	global_load_lds_dwordx4 v[150:151], off
	v_lshl_add_u64 v[150:151], s[26:27], 0, v[158:159]
	s_mov_b32 m0, s82
	s_nop 0
	global_load_lds_dwordx4 v[150:151], off
	v_lshl_add_u64 v[150:151], v[216:217], 0, s[76:77]
	s_mov_b32 m0, s94
	s_nop 0
	global_load_lds_dwordx4 v[150:151], off
	v_lshl_add_u64 v[150:151], v[218:219], 0, s[76:77]
	s_mov_b32 m0, s95
	s_nop 0
	global_load_lds_dwordx4 v[150:151], off
	s_waitcnt vmcnt(8)
	s_waitcnt lgkmcnt(0)
	s_barrier
	v_mfma_f32_16x16x32_bf16 v[64:67], v[134:137], v[182:185], v[64:67]
	v_mfma_f32_16x16x32_bf16 v[64:67], v[138:141], v[186:189], v[64:67]
	v_mfma_f32_16x16x32_bf16 v[32:35], v[138:141], v[194:197], v[32:35]
	v_mfma_f32_16x16x32_bf16 v[32:35], v[134:137], v[190:193], v[32:35]
	v_mfma_f32_16x16x32_bf16 v[16:19], v[134:137], v[198:201], v[16:19]
	v_mfma_f32_16x16x32_bf16 v[16:19], v[138:141], v[202:205], v[16:19]
	v_mfma_f32_16x16x32_bf16 v[8:11], v[138:141], v[210:213], v[8:11]
	v_mfma_f32_16x16x32_bf16 v[8:11], v[134:137], v[206:209], v[8:11]
	v_mfma_f32_16x16x32_bf16 v[4:7], v[142:145], v[206:209], v[4:7]
	v_mfma_f32_16x16x32_bf16 v[4:7], v[146:149], v[210:213], v[4:7]
	v_mfma_f32_16x16x32_bf16 v[12:15], v[146:149], v[202:205], v[12:15]
	v_mfma_f32_16x16x32_bf16 v[12:15], v[142:145], v[198:201], v[12:15]
	v_mfma_f32_16x16x32_bf16 v[20:23], v[142:145], v[190:193], v[20:23]
	v_mfma_f32_16x16x32_bf16 v[20:23], v[146:149], v[194:197], v[20:23]
	v_mfma_f32_16x16x32_bf16 v[52:55], v[146:149], v[186:189], v[52:55]
	v_mfma_f32_16x16x32_bf16 v[52:55], v[142:145], v[182:185], v[52:55]
	v_mfma_f32_16x16x32_bf16 v[60:63], v[160:163], v[182:185], v[60:63]
	v_mfma_f32_16x16x32_bf16 v[60:63], v[164:167], v[186:189], v[60:63]
	v_mfma_f32_16x16x32_bf16 v[48:51], v[164:167], v[194:197], v[48:51]
	v_mfma_f32_16x16x32_bf16 v[48:51], v[160:163], v[190:193], v[48:51]
	v_mfma_f32_16x16x32_bf16 v[40:43], v[160:163], v[198:201], v[40:43]
	v_mfma_f32_16x16x32_bf16 v[40:43], v[164:167], v[202:205], v[40:43]
	v_mfma_f32_16x16x32_bf16 v[28:31], v[164:167], v[210:213], v[28:31]
	v_mfma_f32_16x16x32_bf16 v[28:31], v[160:163], v[206:209], v[28:31]
	v_mfma_f32_16x16x32_bf16 v[24:27], v[174:177], v[206:209], v[24:27]
	v_mfma_f32_16x16x32_bf16 v[24:27], v[178:181], v[210:213], v[24:27]
	v_mfma_f32_16x16x32_bf16 v[36:39], v[178:181], v[202:205], v[36:39]
	v_mfma_f32_16x16x32_bf16 v[36:39], v[174:177], v[198:201], v[36:39]
	v_mfma_f32_16x16x32_bf16 v[44:47], v[174:177], v[190:193], v[44:47]
	v_mfma_f32_16x16x32_bf16 v[44:47], v[178:181], v[194:197], v[44:47]
	v_mfma_f32_16x16x32_bf16 v[56:59], v[178:181], v[186:189], v[56:59]
	v_mfma_f32_16x16x32_bf16 v[56:59], v[174:177], v[182:185], v[56:59]
	s_barrier
	s_cmp_ge_u32 s14, s3
	s_mov_b32 s17, s14
	s_cbranch_scc1 .LBB0_183

;     __device__ __forceinline__ int nt(const Unit& u) const { return (u.pn >> 1) < 2 ? 22 : 20; }
; #define PG8_STAGE(bufoff, gbase, voff) do { _Pragma("unroll") for (int _i = 0; _i < 2; ++_i) \
;         __builtin_amdgcn_global_load_lds((const unsigned*)((const char*)(gbase) + (voff)[_i]), (LAS unsigned*)(lds + (bufoff) + ldsw + _i * 8192), 16, 0, 0); } while (0)
; #define PG8_LDA(dst, b, h) do { _Pragma("unroll") for (int m = 0; m < 4; ++m) _Pragma("unroll") for (int k = 0; k < 2; ++k) dst[m][k] = *(const LAS bf16x8*)(pA + PG8_SA(b, h) + m * 2048 + k * 1024); } while (0)
; #define PG8_LDB(dst, b, h) do { _Pragma("unroll") for (int n = 0; n < 2; ++n) _Pragma("unroll") for (int k = 0; k < 2; ++k) dst[n][k] = *(const LAS bf16x8*)(pB + (PG8_SB(b, h) - 4 * HTB) + n * 2048 + k * 1024); } while (0)
; #define PG8_MMA(ai, bj, At, Bt) do { __builtin_amdgcn_s_setprio(1); _Pragma("unroll") for (int m = 0; m < 4; ++m) _Pragma("unroll") for (int n = 0; n < 2; ++n) _Pragma("unroll") for (int k = 0; k < 2; ++k) \
;         acc[ai][bj][m][n] = __builtin_amdgcn_mfma_f32_16x16x32_bf16(Bt[n][k], At[m][k], acc[ai][bj][m][n], 0, 0, 0); __builtin_amdgcn_s_setprio(0); } while (0)
; #define PG8_WAIT_V(n) asm volatile("s_waitcnt vmcnt(" #n ")" ::: "memory")
; #define PG8_WAIT_L(n) asm volatile("s_waitcnt lgkmcnt(" #n ")" ::: "memory")
; template <class Desc, class Epi, bool ALIGN_EPI>
; __device__ __forceinline__ void gemm_phase(LAS unsigned char* lds, const Desc& D, const Epi& E, int G, int c) {
;     ...
;             const bool last = (t == nt - 2);
;             if (last && has_next) PG8_AWAIT(nxt);
;             const char* a1 = cA + (size_t)(t + 1) * kstep;
;             const char* a2 = last ? nA : cA + (size_t)(t + 2) * kstep; const char* b2 = last ? nB : cB + (size_t)(t + 2) * kstep;
;             const char* a3 = a2 + kstep; const char* b3 = b2 + kstep;
;             PG8_LDB(B0, 0, 0); PG8_LDB(B1, 0, 1); PG8_SCHED; PG8_LDA(At, 0, 0); PG8_STAGE(PG8_SA(1, 1), a1 + hstepA, voffA);
;             PG8_WAIT_V(8); PG8_WAIT_L(0); PG8_BAR; PG8_MMA(0, 0, At, B0); PG8_MMA(0, 1, At, B1); PG8_BAR; PG8_SCHED;
;             PG8_LDA(At, 0, 1); PG8_STAGE(PG8_SB(0, 0), b2, voffB); PG8_STAGE(PG8_SB(0, 1), b2 + hstepB, voffB); PG8_STAGE(PG8_SA(0, 0), a2, voffA);
;             PG8_WAIT_V(8); PG8_WAIT_L(0); PG8_BAR; PG8_MMA(1, 0, At, B0); PG8_MMA(1, 1, At, B1); PG8_BAR; PG8_SCHED;
.LBB0_603:
	ds_read_b128 v[144:147], v149
	ds_read_b128 v[152:155], v149 offset:1024
	ds_read_b128 v[156:159], v149 offset:2048
	ds_read_b128 v[160:163], v149 offset:3072
	ds_read_b128 v[164:167], v149 offset:16384
	ds_read_b128 v[168:171], v149 offset:17408
	ds_read_b128 v[172:175], v149 offset:18432
	ds_read_b128 v[176:179], v149 offset:19456
	s_add_u32 s16, s12, 0xfff80080
	s_addc_u32 s17, s13, -1
	s_cmp_eq_u32 s46, 4
	s_cselect_b32 s19, s9, s17
	s_cselect_b32 s18, s8, s16
	s_cselect_b32 s17, s11, s45
	s_cselect_b32 s16, s10, s7
	v_lshl_add_u64 v[212:213], s[12:13], 0, v[140:141]
	s_add_i32 m0, s20, 0xc000
	ds_read_b128 v[180:183], v148
	ds_read_b128 v[184:187], v148 offset:1024
	ds_read_b128 v[188:191], v148 offset:2048
	ds_read_b128 v[192:195], v148 offset:3072
	ds_read_b128 v[196:199], v148 offset:4096
	ds_read_b128 v[200:203], v148 offset:5120
	ds_read_b128 v[204:207], v148 offset:6144
	ds_read_b128 v[208:211], v148 offset:7168
	global_load_lds_dwordx4 v[212:213], off
	v_lshl_add_u64 v[212:213], s[12:13], 0, v[142:143]
	s_add_i32 m0, s20, 0xe000
	s_nop 0
	global_load_lds_dwordx4 v[212:213], off
	s_waitcnt vmcnt(8)
	s_waitcnt lgkmcnt(0)
	s_barrier
	v_mfma_f32_16x16x32_bf16 v[128:131], v[144:147], v[180:183], v[128:131]
	v_mfma_f32_16x16x32_bf16 v[128:131], v[152:155], v[184:187], v[128:131]
	v_mfma_f32_16x16x32_bf16 v[116:119], v[152:155], v[192:195], v[116:119]
	v_mfma_f32_16x16x32_bf16 v[116:119], v[144:147], v[188:191], v[116:119]
	v_mfma_f32_16x16x32_bf16 v[100:103], v[144:147], v[196:199], v[100:103]
	v_mfma_f32_16x16x32_bf16 v[100:103], v[152:155], v[200:203], v[100:103]
	v_mfma_f32_16x16x32_bf16 v[84:87], v[152:155], v[208:211], v[84:87]
	v_mfma_f32_16x16x32_bf16 v[84:87], v[144:147], v[204:207], v[84:87]
	v_mfma_f32_16x16x32_bf16 v[76:79], v[156:159], v[204:207], v[76:79]
	v_mfma_f32_16x16x32_bf16 v[76:79], v[160:163], v[208:211], v[76:79]
	v_mfma_f32_16x16x32_bf16 v[92:95], v[160:163], v[200:203], v[92:95]
	v_mfma_f32_16x16x32_bf16 v[92:95], v[156:159], v[196:199], v[92:95]
	v_mfma_f32_16x16x32_bf16 v[108:111], v[156:159], v[188:191], v[108:111]
	v_mfma_f32_16x16x32_bf16 v[108:111], v[160:163], v[192:195], v[108:111]
	v_mfma_f32_16x16x32_bf16 v[124:127], v[160:163], v[184:187], v[124:127]
	v_mfma_f32_16x16x32_bf16 v[124:127], v[156:159], v[180:183], v[124:127]
	v_mfma_f32_16x16x32_bf16 v[120:123], v[164:167], v[180:183], v[120:123]
	v_mfma_f32_16x16x32_bf16 v[120:123], v[168:171], v[184:187], v[120:123]
	v_mfma_f32_16x16x32_bf16 v[104:107], v[168:171], v[192:195], v[104:107]
	v_mfma_f32_16x16x32_bf16 v[104:107], v[164:167], v[188:191], v[104:107]
	v_mfma_f32_16x16x32_bf16 v[88:91], v[164:167], v[196:199], v[88:91]
	v_mfma_f32_16x16x32_bf16 v[88:91], v[168:171], v[200:203], v[88:91]
	v_mfma_f32_16x16x32_bf16 v[72:75], v[168:171], v[208:211], v[72:75]
	v_mfma_f32_16x16x32_bf16 v[72:75], v[164:167], v[204:207], v[72:75]
	v_mfma_f32_16x16x32_bf16 v[68:71], v[172:175], v[204:207], v[68:71]
	v_mfma_f32_16x16x32_bf16 v[68:71], v[176:179], v[208:211], v[68:71]
	v_mfma_f32_16x16x32_bf16 v[80:83], v[176:179], v[200:203], v[80:83]
	v_mfma_f32_16x16x32_bf16 v[80:83], v[172:175], v[196:199], v[80:83]
	v_mfma_f32_16x16x32_bf16 v[96:99], v[172:175], v[188:191], v[96:99]
	v_mfma_f32_16x16x32_bf16 v[96:99], v[176:179], v[192:195], v[96:99]
	v_mfma_f32_16x16x32_bf16 v[112:115], v[176:179], v[184:187], v[112:115]
	v_mfma_f32_16x16x32_bf16 v[112:115], v[172:175], v[180:183], v[112:115]
	s_barrier
	s_mov_b32 m0, s21
	v_lshl_add_u64 v[212:213], s[16:17], 0, v[136:137]
	s_add_u32 s48, s16, 0x20000
	ds_read_b128 v[180:183], v148 offset:16384
	ds_read_b128 v[184:187], v148 offset:17408
	ds_read_b128 v[188:191], v148 offset:18432
	ds_read_b128 v[192:195], v148 offset:19456
	ds_read_b128 v[196:199], v148 offset:20480
	ds_read_b128 v[200:203], v148 offset:21504
	ds_read_b128 v[204:207], v148 offset:22528
	ds_read_b128 v[208:211], v148 offset:23552
	global_load_lds_dwordx4 v[212:213], off
	v_lshl_add_u64 v[214:215], s[16:17], 0, v[132:133]
	s_mov_b32 m0, s23
	s_addc_u32 s49, s17, 0
	global_load_lds_dwordx4 v[214:215], off
	v_lshl_add_u64 v[216:217], s[48:49], 0, v[136:137]
	s_mov_b32 m0, s24
	v_lshl_add_u64 v[218:219], s[18:19], 0, v[134:135]
	global_load_lds_dwordx4 v[216:217], off
	v_lshl_add_u64 v[216:217], s[48:49], 0, v[132:133]
	s_mov_b32 m0, s25
	s_nop 0
	global_load_lds_dwordx4 v[216:217], off
	v_lshl_add_u64 v[216:217], s[18:19], 0, v[138:139]
	s_mov_b32 m0, s20
	s_nop 0
	global_load_lds_dwordx4 v[216:217], off
	s_mov_b32 m0, s26
	s_nop 0
	global_load_lds_dwordx4 v[218:219], off
	s_waitcnt vmcnt(8)
	s_waitcnt lgkmcnt(0)
	s_barrier
; #define PG8_STAGE(bufoff, gbase, voff) do { _Pragma("unroll") for (int _i = 0; _i < 2; ++_i) \
;         __builtin_amdgcn_global_load_lds((const unsigned*)((const char*)(gbase) + (voff)[_i]), (LAS unsigned*)(lds + (bufoff) + ldsw + _i * 8192), 16, 0, 0); } while (0)
; #define PG8_LDA(dst, b, h) do { _Pragma("unroll") for (int m = 0; m < 4; ++m) _Pragma("unroll") for (int k = 0; k < 2; ++k) dst[m][k] = *(const LAS bf16x8*)(pA + PG8_SA(b, h) + m * 2048 + k * 1024); } while (0)
; #define PG8_LDB(dst, b, h) do { _Pragma("unroll") for (int n = 0; n < 2; ++n) _Pragma("unroll") for (int k = 0; k < 2; ++k) dst[n][k] = *(const LAS bf16x8*)(pB + (PG8_SB(b, h) - 4 * HTB) + n * 2048 + k * 1024); } while (0)
; #define PG8_MMA(ai, bj, At, Bt) do { __builtin_amdgcn_s_setprio(1); _Pragma("unroll") for (int m = 0; m < 4; ++m) _Pragma("unroll") for (int n = 0; n < 2; ++n) _Pragma("unroll") for (int k = 0; k < 2; ++k) \
;         acc[ai][bj][m][n] = __builtin_amdgcn_mfma_f32_16x16x32_bf16(Bt[n][k], At[m][k], acc[ai][bj][m][n], 0, 0, 0); __builtin_amdgcn_s_setprio(0); } while (0)
; #define PG8_WAIT_V(n) asm volatile("s_waitcnt vmcnt(" #n ")" ::: "memory")
; #define PG8_WAIT_L(n) asm volatile("s_waitcnt lgkmcnt(" #n ")" ::: "memory")
; #define PG8_BAR __builtin_amdgcn_s_barrier()
; #define PG8_SCHED __builtin_amdgcn_sched_barrier(0)
; template <class Desc, class Epi, bool ALIGN_EPI>
; __device__ __forceinline__ void gemm_phase(LAS unsigned char* lds, const Desc& D, const Epi& E, int G, int c) {
;     ...
;             PG8_WAIT_V(8); PG8_WAIT_L(0); PG8_BAR; PG8_MMA(1, 0, At, B0); PG8_MMA(1, 1, At, B1); PG8_BAR; PG8_SCHED;
;             PG8_LDB(B0, 1, 0); PG8_LDB(B1, 1, 1); PG8_SCHED; PG8_LDA(At, 1, 0); PG8_STAGE(PG8_SA(0, 1), a2 + hstepA, voffA);
;             PG8_WAIT_V(8); PG8_WAIT_L(0); PG8_BAR; PG8_MMA(0, 0, At, B0); PG8_MMA(0, 1, At, B1); PG8_BAR; PG8_SCHED;
	v_mfma_f32_16x16x32_bf16 v[64:67], v[144:147], v[180:183], v[64:67]
	v_mfma_f32_16x16x32_bf16 v[64:67], v[152:155], v[184:187], v[64:67]
	v_mfma_f32_16x16x32_bf16 v[52:55], v[152:155], v[192:195], v[52:55]
	v_mfma_f32_16x16x32_bf16 v[52:55], v[144:147], v[188:191], v[52:55]
	v_mfma_f32_16x16x32_bf16 v[36:39], v[144:147], v[196:199], v[36:39]
	v_mfma_f32_16x16x32_bf16 v[36:39], v[152:155], v[200:203], v[36:39]
	v_mfma_f32_16x16x32_bf16 v[20:23], v[152:155], v[208:211], v[20:23]
	v_mfma_f32_16x16x32_bf16 v[20:23], v[144:147], v[204:207], v[20:23]
	v_mfma_f32_16x16x32_bf16 v[12:15], v[156:159], v[204:207], v[12:15]
	v_mfma_f32_16x16x32_bf16 v[12:15], v[160:163], v[208:211], v[12:15]
	v_mfma_f32_16x16x32_bf16 v[28:31], v[160:163], v[200:203], v[28:31]
	v_mfma_f32_16x16x32_bf16 v[28:31], v[156:159], v[196:199], v[28:31]
	v_mfma_f32_16x16x32_bf16 v[44:47], v[156:159], v[188:191], v[44:47]
	v_mfma_f32_16x16x32_bf16 v[44:47], v[160:163], v[192:195], v[44:47]
	v_mfma_f32_16x16x32_bf16 v[60:63], v[160:163], v[184:187], v[60:63]
	v_mfma_f32_16x16x32_bf16 v[60:63], v[156:159], v[180:183], v[60:63]
	v_mfma_f32_16x16x32_bf16 v[56:59], v[164:167], v[180:183], v[56:59]
	v_mfma_f32_16x16x32_bf16 v[56:59], v[168:171], v[184:187], v[56:59]
	v_mfma_f32_16x16x32_bf16 v[40:43], v[168:171], v[192:195], v[40:43]
	v_mfma_f32_16x16x32_bf16 v[40:43], v[164:167], v[188:191], v[40:43]
	v_mfma_f32_16x16x32_bf16 v[24:27], v[164:167], v[196:199], v[24:27]
	v_mfma_f32_16x16x32_bf16 v[24:27], v[168:171], v[200:203], v[24:27]
	v_mfma_f32_16x16x32_bf16 v[8:11], v[168:171], v[208:211], v[8:11]
	v_mfma_f32_16x16x32_bf16 v[8:11], v[164:167], v[204:207], v[8:11]
	v_mfma_f32_16x16x32_bf16 v[4:7], v[172:175], v[204:207], v[4:7]
	v_mfma_f32_16x16x32_bf16 v[4:7], v[176:179], v[208:211], v[4:7]
	v_mfma_f32_16x16x32_bf16 v[16:19], v[176:179], v[200:203], v[16:19]
	v_mfma_f32_16x16x32_bf16 v[16:19], v[172:175], v[196:199], v[16:19]
	v_mfma_f32_16x16x32_bf16 v[32:35], v[172:175], v[188:191], v[32:35]
	v_mfma_f32_16x16x32_bf16 v[32:35], v[176:179], v[192:195], v[32:35]
	v_mfma_f32_16x16x32_bf16 v[48:51], v[176:179], v[184:187], v[48:51]
	v_mfma_f32_16x16x32_bf16 v[48:51], v[172:175], v[180:183], v[48:51]
	s_barrier
	ds_read_b128 v[144:147], v149 offset:32768
	ds_read_b128 v[152:155], v149 offset:33792
	ds_read_b128 v[156:159], v149 offset:34816
	ds_read_b128 v[160:163], v149 offset:35840
	ds_read_b128 v[164:167], v149 offset:49152
	ds_read_b128 v[168:171], v149 offset:50176
	ds_read_b128 v[172:175], v149 offset:51200
	ds_read_b128 v[176:179], v149 offset:52224
	s_add_u32 s18, s18, 0x80000
	s_addc_u32 s19, s19, 0
	s_mov_b32 m0, s27
	v_lshl_add_u64 v[220:221], s[18:19], 0, v[138:139]
	ds_read_b128 v[180:183], v148 offset:32768
	ds_read_b128 v[184:187], v148 offset:33792
	ds_read_b128 v[188:191], v148 offset:34816
	ds_read_b128 v[192:195], v148 offset:35840
	ds_read_b128 v[196:199], v148 offset:36864
	ds_read_b128 v[200:203], v148 offset:37888
	ds_read_b128 v[204:207], v148 offset:38912
	ds_read_b128 v[208:211], v148 offset:39936
	global_load_lds_dwordx4 v[220:221], off
	v_lshl_add_u64 v[220:221], s[18:19], 0, v[134:135]
	s_mov_b32 m0, s30
	s_nop 0
	global_load_lds_dwordx4 v[220:221], off
	s_waitcnt vmcnt(8)
	s_waitcnt lgkmcnt(0)
	s_barrier
	v_mfma_f32_16x16x32_bf16 v[128:131], v[144:147], v[180:183], v[128:131]
	v_mfma_f32_16x16x32_bf16 v[128:131], v[152:155], v[184:187], v[128:131]
	v_mfma_f32_16x16x32_bf16 v[116:119], v[152:155], v[192:195], v[116:119]
	v_mfma_f32_16x16x32_bf16 v[116:119], v[144:147], v[188:191], v[116:119]
	v_mfma_f32_16x16x32_bf16 v[100:103], v[144:147], v[196:199], v[100:103]
	v_mfma_f32_16x16x32_bf16 v[100:103], v[152:155], v[200:203], v[100:103]
	v_mfma_f32_16x16x32_bf16 v[84:87], v[152:155], v[208:211], v[84:87]
	v_mfma_f32_16x16x32_bf16 v[84:87], v[144:147], v[204:207], v[84:87]
	v_mfma_f32_16x16x32_bf16 v[76:79], v[156:159], v[204:207], v[76:79]
	v_mfma_f32_16x16x32_bf16 v[76:79], v[160:163], v[208:211], v[76:79]
	v_mfma_f32_16x16x32_bf16 v[92:95], v[160:163], v[200:203], v[92:95]
	v_mfma_f32_16x16x32_bf16 v[92:95], v[156:159], v[196:199], v[92:95]
	v_mfma_f32_16x16x32_bf16 v[108:111], v[156:159], v[188:191], v[108:111]
	v_mfma_f32_16x16x32_bf16 v[108:111], v[160:163], v[192:195], v[108:111]
	v_mfma_f32_16x16x32_bf16 v[124:127], v[160:163], v[184:187], v[124:127]
	v_mfma_f32_16x16x32_bf16 v[124:127], v[156:159], v[180:183], v[124:127]
	v_mfma_f32_16x16x32_bf16 v[120:123], v[164:167], v[180:183], v[120:123]
	v_mfma_f32_16x16x32_bf16 v[120:123], v[168:171], v[184:187], v[120:123]
	v_mfma_f32_16x16x32_bf16 v[104:107], v[168:171], v[192:195], v[104:107]
	v_mfma_f32_16x16x32_bf16 v[104:107], v[164:167], v[188:191], v[104:107]
	v_mfma_f32_16x16x32_bf16 v[88:91], v[164:167], v[196:199], v[88:91]
	v_mfma_f32_16x16x32_bf16 v[88:91], v[168:171], v[200:203], v[88:91]
	v_mfma_f32_16x16x32_bf16 v[72:75], v[168:171], v[208:211], v[72:75]
	v_mfma_f32_16x16x32_bf16 v[72:75], v[164:167], v[204:207], v[72:75]
	v_mfma_f32_16x16x32_bf16 v[68:71], v[172:175], v[204:207], v[68:71]
	v_mfma_f32_16x16x32_bf16 v[68:71], v[176:179], v[208:211], v[68:71]
	v_mfma_f32_16x16x32_bf16 v[80:83], v[176:179], v[200:203], v[80:83]
	v_mfma_f32_16x16x32_bf16 v[80:83], v[172:175], v[196:199], v[80:83]
	v_mfma_f32_16x16x32_bf16 v[96:99], v[172:175], v[188:191], v[96:99]
	v_mfma_f32_16x16x32_bf16 v[96:99], v[176:179], v[192:195], v[96:99]
	v_mfma_f32_16x16x32_bf16 v[112:115], v[176:179], v[184:187], v[112:115]
	v_mfma_f32_16x16x32_bf16 v[112:115], v[172:175], v[180:183], v[112:115]
	s_barrier
; #define PG8_STAGE(bufoff, gbase, voff) do { _Pragma("unroll") for (int _i = 0; _i < 2; ++_i) \
;         __builtin_amdgcn_global_load_lds((const unsigned*)((const char*)(gbase) + (voff)[_i]), (LAS unsigned*)(lds + (bufoff) + ldsw + _i * 8192), 16, 0, 0); } while (0)
; #define PG8_LDA(dst, b, h) do { _Pragma("unroll") for (int m = 0; m < 4; ++m) _Pragma("unroll") for (int k = 0; k < 2; ++k) dst[m][k] = *(const LAS bf16x8*)(pA + PG8_SA(b, h) + m * 2048 + k * 1024); } while (0)
; #define PG8_MMA(ai, bj, At, Bt) do { __builtin_amdgcn_s_setprio(1); _Pragma("unroll") for (int m = 0; m < 4; ++m) _Pragma("unroll") for (int n = 0; n < 2; ++n) _Pragma("unroll") for (int k = 0; k < 2; ++k) \
;         acc[ai][bj][m][n] = __builtin_amdgcn_mfma_f32_16x16x32_bf16(Bt[n][k], At[m][k], acc[ai][bj][m][n], 0, 0, 0); __builtin_amdgcn_s_setprio(0); } while (0)
; #define PG8_WAIT_V(n) asm volatile("s_waitcnt vmcnt(" #n ")" ::: "memory")
; #define PG8_WAIT_L(n) asm volatile("s_waitcnt lgkmcnt(" #n ")" ::: "memory")
; #define PG8_BAR __builtin_amdgcn_s_barrier()
; #define PG8_SCHED __builtin_amdgcn_sched_barrier(0)
; template <class Desc, class Epi, bool ALIGN_EPI>
; __device__ __forceinline__ void gemm_phase(LAS unsigned char* lds, const Desc& D, const Epi& E, int G, int c) {
;     ...
;             PG8_LDA(At, 1, 1); PG8_STAGE(PG8_SB(1, 0), b3, voffB); PG8_STAGE(PG8_SB(1, 1), b3 + hstepB, voffB); PG8_STAGE(PG8_SA(1, 0), a3, voffA);
;             PG8_WAIT_V(8); PG8_WAIT_L(0); PG8_BAR; PG8_MMA(1, 0, At, B0); PG8_MMA(1, 1, At, B1); PG8_BAR; PG8_SCHED;
;         }
;         if constexpr (ALIGN_EPI) { if (wr == 0) PG8_BAR; }
	s_mov_b32 m0, s31
	v_lshl_add_u64 v[212:213], v[212:213], 0, s[76:77]
	s_add_u32 s16, s16, 0x20080
	ds_read_b128 v[180:183], v148 offset:49152
	ds_read_b128 v[184:187], v148 offset:50176
	ds_read_b128 v[188:191], v148 offset:51200
	ds_read_b128 v[192:195], v148 offset:52224
	ds_read_b128 v[196:199], v148 offset:53248
	ds_read_b128 v[200:203], v148 offset:54272
	ds_read_b128 v[204:207], v148 offset:55296
	ds_read_b128 v[208:211], v148 offset:56320
	global_load_lds_dwordx4 v[212:213], off
	v_lshl_add_u64 v[212:213], v[214:215], 0, s[76:77]
	s_mov_b32 m0, s33
	s_addc_u32 s17, s17, 0
	global_load_lds_dwordx4 v[212:213], off
	v_lshl_add_u64 v[212:213], s[16:17], 0, v[136:137]
	s_mov_b32 m0, s38
	s_nop 0
	global_load_lds_dwordx4 v[212:213], off
	v_lshl_add_u64 v[212:213], s[16:17], 0, v[132:133]
	s_mov_b32 m0, s39
	s_nop 0
	global_load_lds_dwordx4 v[212:213], off
	v_lshl_add_u64 v[212:213], v[216:217], 0, s[76:77]
	s_mov_b32 m0, s34
	s_nop 0
	global_load_lds_dwordx4 v[212:213], off
	v_lshl_add_u64 v[212:213], v[218:219], 0, s[76:77]
	s_mov_b32 m0, s35
	s_nop 0
	global_load_lds_dwordx4 v[212:213], off
	s_waitcnt vmcnt(8)
	s_waitcnt lgkmcnt(0)
	s_barrier
	v_mfma_f32_16x16x32_bf16 v[64:67], v[144:147], v[180:183], v[64:67]
	v_mfma_f32_16x16x32_bf16 v[64:67], v[152:155], v[184:187], v[64:67]
	v_mfma_f32_16x16x32_bf16 v[52:55], v[152:155], v[192:195], v[52:55]
	v_mfma_f32_16x16x32_bf16 v[52:55], v[144:147], v[188:191], v[52:55]
	v_mfma_f32_16x16x32_bf16 v[36:39], v[144:147], v[196:199], v[36:39]
	v_mfma_f32_16x16x32_bf16 v[36:39], v[152:155], v[200:203], v[36:39]
	v_mfma_f32_16x16x32_bf16 v[20:23], v[152:155], v[208:211], v[20:23]
	v_mfma_f32_16x16x32_bf16 v[20:23], v[144:147], v[204:207], v[20:23]
	v_mfma_f32_16x16x32_bf16 v[12:15], v[156:159], v[204:207], v[12:15]
	v_mfma_f32_16x16x32_bf16 v[12:15], v[160:163], v[208:211], v[12:15]
	v_mfma_f32_16x16x32_bf16 v[28:31], v[160:163], v[200:203], v[28:31]
	v_mfma_f32_16x16x32_bf16 v[28:31], v[156:159], v[196:199], v[28:31]
	v_mfma_f32_16x16x32_bf16 v[44:47], v[156:159], v[188:191], v[44:47]
	v_mfma_f32_16x16x32_bf16 v[44:47], v[160:163], v[192:195], v[44:47]
	v_mfma_f32_16x16x32_bf16 v[60:63], v[160:163], v[184:187], v[60:63]
	v_mfma_f32_16x16x32_bf16 v[60:63], v[156:159], v[180:183], v[60:63]
	v_mfma_f32_16x16x32_bf16 v[56:59], v[164:167], v[180:183], v[56:59]
	v_mfma_f32_16x16x32_bf16 v[56:59], v[168:171], v[184:187], v[56:59]
	v_mfma_f32_16x16x32_bf16 v[40:43], v[168:171], v[192:195], v[40:43]
	v_mfma_f32_16x16x32_bf16 v[40:43], v[164:167], v[188:191], v[40:43]
	v_mfma_f32_16x16x32_bf16 v[24:27], v[164:167], v[196:199], v[24:27]
	v_mfma_f32_16x16x32_bf16 v[24:27], v[168:171], v[200:203], v[24:27]
	v_mfma_f32_16x16x32_bf16 v[8:11], v[168:171], v[208:211], v[8:11]
	v_mfma_f32_16x16x32_bf16 v[8:11], v[164:167], v[204:207], v[8:11]
	v_mfma_f32_16x16x32_bf16 v[4:7], v[172:175], v[204:207], v[4:7]
	v_mfma_f32_16x16x32_bf16 v[4:7], v[176:179], v[208:211], v[4:7]
	v_mfma_f32_16x16x32_bf16 v[16:19], v[176:179], v[200:203], v[16:19]
	v_mfma_f32_16x16x32_bf16 v[16:19], v[172:175], v[196:199], v[16:19]
	v_mfma_f32_16x16x32_bf16 v[32:35], v[172:175], v[188:191], v[32:35]
	v_mfma_f32_16x16x32_bf16 v[32:35], v[176:179], v[192:195], v[32:35]
	v_mfma_f32_16x16x32_bf16 v[48:51], v[176:179], v[184:187], v[48:51]
	v_mfma_f32_16x16x32_bf16 v[48:51], v[172:175], v[180:183], v[48:51]
	s_barrier
	s_add_i32 s46, s46, 2
	s_add_u32 s12, s12, 0x100
	s_addc_u32 s13, s13, 0
	s_add_u32 s7, s7, 0x100
	s_addc_u32 s45, s45, 0
	s_cmp_gt_u32 s46, 5
	s_cbranch_scc0 .LBB0_603
	v_readlane_b32 s46, v255, 36
	s_and_b64 vcc, exec, s[4:5]
	v_readlane_b32 s47, v255, 37
	s_cbranch_vccz .LBB0_606
	s_barrier

;     __device__ __forceinline__ int nt(const Unit& u) const { return (u.pn >> 1) < 2 ? 22 : 20; }
; #define PG8_STAGE(bufoff, gbase, voff) do { _Pragma("unroll") for (int _i = 0; _i < 2; ++_i) \
;         __builtin_amdgcn_global_load_lds((const unsigned*)((const char*)(gbase) + (voff)[_i]), (LAS unsigned*)(lds + (bufoff) + ldsw + _i * 8192), 16, 0, 0); } while (0)
; #define PG8_LDA(dst, b, h) do { _Pragma("unroll") for (int m = 0; m < 4; ++m) _Pragma("unroll") for (int k = 0; k < 2; ++k) dst[m][k] = *(const LAS bf16x8*)(pA + PG8_SA(b, h) + m * 2048 + k * 1024); } while (0)
; #define PG8_LDB(dst, b, h) do { _Pragma("unroll") for (int n = 0; n < 2; ++n) _Pragma("unroll") for (int k = 0; k < 2; ++k) dst[n][k] = *(const LAS bf16x8*)(pB + (PG8_SB(b, h) - 4 * HTB) + n * 2048 + k * 1024); } while (0)
; #define PG8_MMA(ai, bj, At, Bt) do { __builtin_amdgcn_s_setprio(1); _Pragma("unroll") for (int m = 0; m < 4; ++m) _Pragma("unroll") for (int n = 0; n < 2; ++n) _Pragma("unroll") for (int k = 0; k < 2; ++k) \
;         acc[ai][bj][m][n] = __builtin_amdgcn_mfma_f32_16x16x32_bf16(Bt[n][k], At[m][k], acc[ai][bj][m][n], 0, 0, 0); __builtin_amdgcn_s_setprio(0); } while (0)
; #define PG8_WAIT_V(n) asm volatile("s_waitcnt vmcnt(" #n ")" ::: "memory")
; #define PG8_WAIT_L(n) asm volatile("s_waitcnt lgkmcnt(" #n ")" ::: "memory")
; template <class Desc, class Epi, bool ALIGN_EPI>
; __device__ __forceinline__ void gemm_phase(LAS unsigned char* lds, const Desc& D, const Epi& E, int G, int c) {
;     ...
;             const bool last = (t == nt - 2);
;             if (last && has_next) PG8_AWAIT(nxt);
;             const char* a1 = cA + (size_t)(t + 1) * kstep;
;             const char* a2 = last ? nA : cA + (size_t)(t + 2) * kstep; const char* b2 = last ? nB : cB + (size_t)(t + 2) * kstep;
;             const char* a3 = a2 + kstep; const char* b3 = b2 + kstep;
;             PG8_LDB(B0, 0, 0); PG8_LDB(B1, 0, 1); PG8_SCHED; PG8_LDA(At, 0, 0); PG8_STAGE(PG8_SA(1, 1), a1 + hstepA, voffA);
;             PG8_WAIT_V(8); PG8_WAIT_L(0); PG8_BAR; PG8_MMA(0, 0, At, B0); PG8_MMA(0, 1, At, B1); PG8_BAR; PG8_SCHED;
;             PG8_LDA(At, 0, 1); PG8_STAGE(PG8_SB(0, 0), b2, voffB); PG8_STAGE(PG8_SB(0, 1), b2 + hstepB, voffB); PG8_STAGE(PG8_SA(0, 0), a2, voffA);
;             PG8_WAIT_V(8); PG8_WAIT_L(0); PG8_BAR; PG8_MMA(1, 0, At, B0); PG8_MMA(1, 1, At, B1); PG8_BAR; PG8_SCHED;
.LBB0_1164:
	s_waitcnt lgkmcnt(0)
	ds_read_b128 v[132:135], v229
	ds_read_b128 v[136:139], v229 offset:1024
	ds_read_b128 v[140:143], v229 offset:2048
	ds_read_b128 v[144:147], v229 offset:3072
	ds_read_b128 v[148:151], v229 offset:16384
	ds_read_b128 v[152:155], v229 offset:17408
	ds_read_b128 v[156:159], v229 offset:18432
	ds_read_b128 v[160:163], v229 offset:19456
	s_add_i32 s20, s14, 2
	s_add_u32 s16, s12, 0xfff00080
	s_addc_u32 s17, s13, -1
	s_cmp_eq_u32 s1, s14
	s_cselect_b32 s19, s39, s17
	s_cselect_b32 s18, s38, s16
	s_cselect_b32 s17, s41, s11
	s_cselect_b32 s16, s40, s3
	v_lshl_add_u64 v[208:209], s[12:13], 0, v[204:205]
	s_add_i32 m0, s35, 0xc000
	ds_read_b128 v[164:167], v228
	ds_read_b128 v[168:171], v228 offset:1024
	ds_read_b128 v[172:175], v228 offset:2048
	ds_read_b128 v[176:179], v228 offset:3072
	ds_read_b128 v[180:183], v228 offset:4096
	ds_read_b128 v[184:187], v228 offset:5120
	ds_read_b128 v[188:191], v228 offset:6144
	ds_read_b128 v[192:195], v228 offset:7168
	global_load_lds_dwordx4 v[208:209], off
	v_lshl_add_u64 v[208:209], s[12:13], 0, v[206:207]
	s_add_i32 m0, s35, 0xe000
	s_nop 0
	global_load_lds_dwordx4 v[208:209], off
	s_waitcnt vmcnt(8)
	s_waitcnt lgkmcnt(0)
	s_barrier
	v_mfma_f32_16x16x32_bf16 v[128:131], v[132:135], v[164:167], v[128:131]
	v_mfma_f32_16x16x32_bf16 v[128:131], v[136:139], v[168:171], v[128:131]
	v_mfma_f32_16x16x32_bf16 v[120:123], v[136:139], v[176:179], v[120:123]
	v_mfma_f32_16x16x32_bf16 v[120:123], v[132:135], v[172:175], v[120:123]
	v_mfma_f32_16x16x32_bf16 v[112:115], v[132:135], v[180:183], v[112:115]
	v_mfma_f32_16x16x32_bf16 v[112:115], v[136:139], v[184:187], v[112:115]
	v_mfma_f32_16x16x32_bf16 v[104:107], v[136:139], v[192:195], v[104:107]
	v_mfma_f32_16x16x32_bf16 v[104:107], v[132:135], v[188:191], v[104:107]
	v_mfma_f32_16x16x32_bf16 v[100:103], v[140:143], v[188:191], v[100:103]
	v_mfma_f32_16x16x32_bf16 v[100:103], v[144:147], v[192:195], v[100:103]
	v_mfma_f32_16x16x32_bf16 v[108:111], v[144:147], v[184:187], v[108:111]
	v_mfma_f32_16x16x32_bf16 v[108:111], v[140:143], v[180:183], v[108:111]
	v_mfma_f32_16x16x32_bf16 v[116:119], v[140:143], v[172:175], v[116:119]
	v_mfma_f32_16x16x32_bf16 v[116:119], v[144:147], v[176:179], v[116:119]
	v_mfma_f32_16x16x32_bf16 v[124:127], v[144:147], v[168:171], v[124:127]
	v_mfma_f32_16x16x32_bf16 v[124:127], v[140:143], v[164:167], v[124:127]
	v_mfma_f32_16x16x32_bf16 v[96:99], v[148:151], v[164:167], v[96:99]
	v_mfma_f32_16x16x32_bf16 v[96:99], v[152:155], v[168:171], v[96:99]
	v_mfma_f32_16x16x32_bf16 v[88:91], v[152:155], v[176:179], v[88:91]
	v_mfma_f32_16x16x32_bf16 v[88:91], v[148:151], v[172:175], v[88:91]
	v_mfma_f32_16x16x32_bf16 v[64:67], v[148:151], v[180:183], v[64:67]
	v_mfma_f32_16x16x32_bf16 v[64:67], v[152:155], v[184:187], v[64:67]
	v_mfma_f32_16x16x32_bf16 v[32:35], v[152:155], v[192:195], v[32:35]
	v_mfma_f32_16x16x32_bf16 v[32:35], v[148:151], v[188:191], v[32:35]
	v_mfma_f32_16x16x32_bf16 v[20:23], v[156:159], v[188:191], v[20:23]
	v_mfma_f32_16x16x32_bf16 v[20:23], v[160:163], v[192:195], v[20:23]
	v_mfma_f32_16x16x32_bf16 v[52:55], v[160:163], v[184:187], v[52:55]
	v_mfma_f32_16x16x32_bf16 v[52:55], v[156:159], v[180:183], v[52:55]
	v_mfma_f32_16x16x32_bf16 v[80:83], v[156:159], v[172:175], v[80:83]
	v_mfma_f32_16x16x32_bf16 v[80:83], v[160:163], v[176:179], v[80:83]
	v_mfma_f32_16x16x32_bf16 v[92:95], v[160:163], v[168:171], v[92:95]
	v_mfma_f32_16x16x32_bf16 v[92:95], v[156:159], v[164:167], v[92:95]
	s_barrier
	s_mov_b32 m0, s44
	v_lshl_add_u64 v[208:209], s[16:17], 0, v[198:199]
	s_add_u32 s62, s16, 0x100000
	ds_read_b128 v[164:167], v228 offset:16384
	ds_read_b128 v[168:171], v228 offset:17408
	ds_read_b128 v[172:175], v228 offset:18432
	ds_read_b128 v[176:179], v228 offset:19456
	ds_read_b128 v[180:183], v228 offset:20480
	ds_read_b128 v[184:187], v228 offset:21504
	ds_read_b128 v[188:191], v228 offset:22528
	ds_read_b128 v[192:195], v228 offset:23552
	global_load_lds_dwordx4 v[208:209], off
	v_lshl_add_u64 v[210:211], s[16:17], 0, v[202:203]
	s_mov_b32 m0, s45
	s_addc_u32 s63, s17, 0
	global_load_lds_dwordx4 v[210:211], off
	v_lshl_add_u64 v[212:213], s[62:63], 0, v[198:199]
	s_mov_b32 m0, s46
	v_lshl_add_u64 v[214:215], s[18:19], 0, v[200:201]
	global_load_lds_dwordx4 v[212:213], off
	v_lshl_add_u64 v[212:213], s[62:63], 0, v[202:203]
	s_mov_b32 m0, s47
	s_nop 0
	global_load_lds_dwordx4 v[212:213], off
	v_lshl_add_u64 v[212:213], s[18:19], 0, v[196:197]
	s_mov_b32 m0, s35
	s_nop 0
	global_load_lds_dwordx4 v[212:213], off
	s_mov_b32 m0, s48
	s_nop 0
	global_load_lds_dwordx4 v[214:215], off
	s_waitcnt vmcnt(8)
	s_waitcnt lgkmcnt(0)
	s_barrier
; #define PG8_STAGE(bufoff, gbase, voff) do { _Pragma("unroll") for (int _i = 0; _i < 2; ++_i) \
;         __builtin_amdgcn_global_load_lds((const unsigned*)((const char*)(gbase) + (voff)[_i]), (LAS unsigned*)(lds + (bufoff) + ldsw + _i * 8192), 16, 0, 0); } while (0)
; #define PG8_LDA(dst, b, h) do { _Pragma("unroll") for (int m = 0; m < 4; ++m) _Pragma("unroll") for (int k = 0; k < 2; ++k) dst[m][k] = *(const LAS bf16x8*)(pA + PG8_SA(b, h) + m * 2048 + k * 1024); } while (0)
; #define PG8_LDB(dst, b, h) do { _Pragma("unroll") for (int n = 0; n < 2; ++n) _Pragma("unroll") for (int k = 0; k < 2; ++k) dst[n][k] = *(const LAS bf16x8*)(pB + (PG8_SB(b, h) - 4 * HTB) + n * 2048 + k * 1024); } while (0)
; #define PG8_MMA(ai, bj, At, Bt) do { __builtin_amdgcn_s_setprio(1); _Pragma("unroll") for (int m = 0; m < 4; ++m) _Pragma("unroll") for (int n = 0; n < 2; ++n) _Pragma("unroll") for (int k = 0; k < 2; ++k) \
;         acc[ai][bj][m][n] = __builtin_amdgcn_mfma_f32_16x16x32_bf16(Bt[n][k], At[m][k], acc[ai][bj][m][n], 0, 0, 0); __builtin_amdgcn_s_setprio(0); } while (0)
; #define PG8_WAIT_V(n) asm volatile("s_waitcnt vmcnt(" #n ")" ::: "memory")
; #define PG8_WAIT_L(n) asm volatile("s_waitcnt lgkmcnt(" #n ")" ::: "memory")
; #define PG8_BAR __builtin_amdgcn_s_barrier()
; #define PG8_SCHED __builtin_amdgcn_sched_barrier(0)
; template <class Desc, class Epi, bool ALIGN_EPI>
; __device__ __forceinline__ void gemm_phase(LAS unsigned char* lds, const Desc& D, const Epi& E, int G, int c) {
;     ...
;             PG8_WAIT_V(8); PG8_WAIT_L(0); PG8_BAR; PG8_MMA(0, 0, At, B0); PG8_MMA(0, 1, At, B1); PG8_BAR; PG8_SCHED;
;             PG8_LDA(At, 0, 1); PG8_STAGE(PG8_SB(0, 0), b2, voffB); PG8_STAGE(PG8_SB(0, 1), b2 + hstepB, voffB); PG8_STAGE(PG8_SA(0, 0), a2, voffA);
;             PG8_WAIT_V(8); PG8_WAIT_L(0); PG8_BAR; PG8_MMA(1, 0, At, B0); PG8_MMA(1, 1, At, B1); PG8_BAR; PG8_SCHED;
;             PG8_LDB(B0, 1, 0); PG8_LDB(B1, 1, 1); PG8_SCHED; PG8_LDA(At, 1, 0); PG8_STAGE(PG8_SA(0, 1), a2 + hstepA, voffA);
;             PG8_WAIT_V(8); PG8_WAIT_L(0); PG8_BAR; PG8_MMA(0, 0, At, B0); PG8_MMA(0, 1, At, B1); PG8_BAR; PG8_SCHED;
	v_mfma_f32_16x16x32_bf16 v[84:87], v[132:135], v[164:167], v[84:87]
	v_mfma_f32_16x16x32_bf16 v[84:87], v[136:139], v[168:171], v[84:87]
	v_mfma_f32_16x16x32_bf16 v[72:75], v[136:139], v[176:179], v[72:75]
	v_mfma_f32_16x16x32_bf16 v[72:75], v[132:135], v[172:175], v[72:75]
	v_mfma_f32_16x16x32_bf16 v[60:63], v[132:135], v[180:183], v[60:63]
	v_mfma_f32_16x16x32_bf16 v[60:63], v[136:139], v[184:187], v[60:63]
	v_mfma_f32_16x16x32_bf16 v[48:51], v[136:139], v[192:195], v[48:51]
	v_mfma_f32_16x16x32_bf16 v[48:51], v[132:135], v[188:191], v[48:51]
	v_mfma_f32_16x16x32_bf16 v[44:47], v[140:143], v[188:191], v[44:47]
	v_mfma_f32_16x16x32_bf16 v[44:47], v[144:147], v[192:195], v[44:47]
	v_mfma_f32_16x16x32_bf16 v[56:59], v[144:147], v[184:187], v[56:59]
	v_mfma_f32_16x16x32_bf16 v[56:59], v[140:143], v[180:183], v[56:59]
	v_mfma_f32_16x16x32_bf16 v[68:71], v[140:143], v[172:175], v[68:71]
	v_mfma_f32_16x16x32_bf16 v[68:71], v[144:147], v[176:179], v[68:71]
	v_mfma_f32_16x16x32_bf16 v[76:79], v[144:147], v[168:171], v[76:79]
	v_mfma_f32_16x16x32_bf16 v[76:79], v[140:143], v[164:167], v[76:79]
	v_mfma_f32_16x16x32_bf16 v[40:43], v[148:151], v[164:167], v[40:43]
	v_mfma_f32_16x16x32_bf16 v[40:43], v[152:155], v[168:171], v[40:43]
	v_mfma_f32_16x16x32_bf16 v[28:31], v[152:155], v[176:179], v[28:31]
	v_mfma_f32_16x16x32_bf16 v[28:31], v[148:151], v[172:175], v[28:31]
	v_mfma_f32_16x16x32_bf16 v[16:19], v[148:151], v[180:183], v[16:19]
	v_mfma_f32_16x16x32_bf16 v[16:19], v[152:155], v[184:187], v[16:19]
	v_mfma_f32_16x16x32_bf16 v[8:11], v[152:155], v[192:195], v[8:11]
	v_mfma_f32_16x16x32_bf16 v[8:11], v[148:151], v[188:191], v[8:11]
	v_mfma_f32_16x16x32_bf16 v[4:7], v[156:159], v[188:191], v[4:7]
	v_mfma_f32_16x16x32_bf16 v[4:7], v[160:163], v[192:195], v[4:7]
	v_mfma_f32_16x16x32_bf16 v[12:15], v[160:163], v[184:187], v[12:15]
	v_mfma_f32_16x16x32_bf16 v[12:15], v[156:159], v[180:183], v[12:15]
	v_mfma_f32_16x16x32_bf16 v[24:27], v[156:159], v[172:175], v[24:27]
	v_mfma_f32_16x16x32_bf16 v[24:27], v[160:163], v[176:179], v[24:27]
	v_mfma_f32_16x16x32_bf16 v[36:39], v[160:163], v[168:171], v[36:39]
	v_mfma_f32_16x16x32_bf16 v[36:39], v[156:159], v[164:167], v[36:39]
	s_barrier
	ds_read_b128 v[132:135], v229 offset:32768
	ds_read_b128 v[136:139], v229 offset:33792
	ds_read_b128 v[140:143], v229 offset:34816
	ds_read_b128 v[144:147], v229 offset:35840
	ds_read_b128 v[148:151], v229 offset:49152
	ds_read_b128 v[152:155], v229 offset:50176
	ds_read_b128 v[156:159], v229 offset:51200
	ds_read_b128 v[160:163], v229 offset:52224
	s_add_u32 s18, s18, 0x100000
	s_addc_u32 s19, s19, 0
	s_mov_b32 m0, s49
	v_lshl_add_u64 v[216:217], s[18:19], 0, v[196:197]
	ds_read_b128 v[164:167], v228 offset:32768
	ds_read_b128 v[168:171], v228 offset:33792
	ds_read_b128 v[172:175], v228 offset:34816
	ds_read_b128 v[176:179], v228 offset:35840
	ds_read_b128 v[180:183], v228 offset:36864
	ds_read_b128 v[184:187], v228 offset:37888
	ds_read_b128 v[188:191], v228 offset:38912
	ds_read_b128 v[192:195], v228 offset:39936
	global_load_lds_dwordx4 v[216:217], off
	v_lshl_add_u64 v[216:217], s[18:19], 0, v[200:201]
	s_mov_b32 m0, s50
	s_nop 0
	global_load_lds_dwordx4 v[216:217], off
	s_waitcnt vmcnt(8)
	s_waitcnt lgkmcnt(0)
	s_barrier
	v_mfma_f32_16x16x32_bf16 v[128:131], v[132:135], v[164:167], v[128:131]
	v_mfma_f32_16x16x32_bf16 v[128:131], v[136:139], v[168:171], v[128:131]
	v_mfma_f32_16x16x32_bf16 v[120:123], v[136:139], v[176:179], v[120:123]
	v_mfma_f32_16x16x32_bf16 v[120:123], v[132:135], v[172:175], v[120:123]
	v_mfma_f32_16x16x32_bf16 v[112:115], v[132:135], v[180:183], v[112:115]
	v_mfma_f32_16x16x32_bf16 v[112:115], v[136:139], v[184:187], v[112:115]
	v_mfma_f32_16x16x32_bf16 v[104:107], v[136:139], v[192:195], v[104:107]
	v_mfma_f32_16x16x32_bf16 v[104:107], v[132:135], v[188:191], v[104:107]
	v_mfma_f32_16x16x32_bf16 v[100:103], v[140:143], v[188:191], v[100:103]
	v_mfma_f32_16x16x32_bf16 v[100:103], v[144:147], v[192:195], v[100:103]
	v_mfma_f32_16x16x32_bf16 v[108:111], v[144:147], v[184:187], v[108:111]
	v_mfma_f32_16x16x32_bf16 v[108:111], v[140:143], v[180:183], v[108:111]
	v_mfma_f32_16x16x32_bf16 v[116:119], v[140:143], v[172:175], v[116:119]
	v_mfma_f32_16x16x32_bf16 v[116:119], v[144:147], v[176:179], v[116:119]
	v_mfma_f32_16x16x32_bf16 v[124:127], v[144:147], v[168:171], v[124:127]
	v_mfma_f32_16x16x32_bf16 v[124:127], v[140:143], v[164:167], v[124:127]
	v_mfma_f32_16x16x32_bf16 v[96:99], v[148:151], v[164:167], v[96:99]
	v_mfma_f32_16x16x32_bf16 v[96:99], v[152:155], v[168:171], v[96:99]
	v_mfma_f32_16x16x32_bf16 v[88:91], v[152:155], v[176:179], v[88:91]
	v_mfma_f32_16x16x32_bf16 v[88:91], v[148:151], v[172:175], v[88:91]
	v_mfma_f32_16x16x32_bf16 v[64:67], v[148:151], v[180:183], v[64:67]
	v_mfma_f32_16x16x32_bf16 v[64:67], v[152:155], v[184:187], v[64:67]
	v_mfma_f32_16x16x32_bf16 v[32:35], v[152:155], v[192:195], v[32:35]
	v_mfma_f32_16x16x32_bf16 v[32:35], v[148:151], v[188:191], v[32:35]
	v_mfma_f32_16x16x32_bf16 v[20:23], v[156:159], v[188:191], v[20:23]
	v_mfma_f32_16x16x32_bf16 v[20:23], v[160:163], v[192:195], v[20:23]
	v_mfma_f32_16x16x32_bf16 v[52:55], v[160:163], v[184:187], v[52:55]
	v_mfma_f32_16x16x32_bf16 v[52:55], v[156:159], v[180:183], v[52:55]
	v_mfma_f32_16x16x32_bf16 v[80:83], v[156:159], v[172:175], v[80:83]
	v_mfma_f32_16x16x32_bf16 v[80:83], v[160:163], v[176:179], v[80:83]
	v_mfma_f32_16x16x32_bf16 v[92:95], v[160:163], v[168:171], v[92:95]
	v_mfma_f32_16x16x32_bf16 v[92:95], v[156:159], v[164:167], v[92:95]
	s_barrier
; #define PG8_STAGE(bufoff, gbase, voff) do { _Pragma("unroll") for (int _i = 0; _i < 2; ++_i) \
;         __builtin_amdgcn_global_load_lds((const unsigned*)((const char*)(gbase) + (voff)[_i]), (LAS unsigned*)(lds + (bufoff) + ldsw + _i * 8192), 16, 0, 0); } while (0)
; #define PG8_LDA(dst, b, h) do { _Pragma("unroll") for (int m = 0; m < 4; ++m) _Pragma("unroll") for (int k = 0; k < 2; ++k) dst[m][k] = *(const LAS bf16x8*)(pA + PG8_SA(b, h) + m * 2048 + k * 1024); } while (0)
; #define PG8_MMA(ai, bj, At, Bt) do { __builtin_amdgcn_s_setprio(1); _Pragma("unroll") for (int m = 0; m < 4; ++m) _Pragma("unroll") for (int n = 0; n < 2; ++n) _Pragma("unroll") for (int k = 0; k < 2; ++k) \
;         acc[ai][bj][m][n] = __builtin_amdgcn_mfma_f32_16x16x32_bf16(Bt[n][k], At[m][k], acc[ai][bj][m][n], 0, 0, 0); __builtin_amdgcn_s_setprio(0); } while (0)
; #define PG8_WAIT_V(n) asm volatile("s_waitcnt vmcnt(" #n ")" ::: "memory")
; #define PG8_WAIT_L(n) asm volatile("s_waitcnt lgkmcnt(" #n ")" ::: "memory")
; #define PG8_BAR __builtin_amdgcn_s_barrier()
; #define PG8_SCHED __builtin_amdgcn_sched_barrier(0)
; template <class Desc, class Epi, bool ALIGN_EPI>
; __device__ __forceinline__ void gemm_phase(LAS unsigned char* lds, const Desc& D, const Epi& E, int G, int c) {
;     ...
;             PG8_LDA(At, 1, 1); PG8_STAGE(PG8_SB(1, 0), b3, voffB); PG8_STAGE(PG8_SB(1, 1), b3 + hstepB, voffB); PG8_STAGE(PG8_SA(1, 0), a3, voffA);
;             PG8_WAIT_V(8); PG8_WAIT_L(0); PG8_BAR; PG8_MMA(1, 0, At, B0); PG8_MMA(1, 1, At, B1); PG8_BAR; PG8_SCHED;
;         }
;         if constexpr (ALIGN_EPI) { if (wr == 0) PG8_BAR; }
	s_mov_b32 m0, s52
	v_lshl_add_u64 v[208:209], v[208:209], 0, s[76:77]
	s_add_u32 s16, s16, 0x100080
	ds_read_b128 v[164:167], v228 offset:49152
	ds_read_b128 v[168:171], v228 offset:50176
	ds_read_b128 v[172:175], v228 offset:51200
	ds_read_b128 v[176:179], v228 offset:52224
	ds_read_b128 v[180:183], v228 offset:53248
	ds_read_b128 v[184:187], v228 offset:54272
	ds_read_b128 v[188:191], v228 offset:55296
	ds_read_b128 v[192:195], v228 offset:56320
	global_load_lds_dwordx4 v[208:209], off
	v_lshl_add_u64 v[208:209], v[210:211], 0, s[76:77]
	s_mov_b32 m0, s53
	s_addc_u32 s17, s17, 0
	global_load_lds_dwordx4 v[208:209], off
	v_lshl_add_u64 v[208:209], s[16:17], 0, v[198:199]
	s_mov_b32 m0, s56
	s_nop 0
	global_load_lds_dwordx4 v[208:209], off
	v_lshl_add_u64 v[208:209], s[16:17], 0, v[202:203]
	s_mov_b32 m0, s57
	s_nop 0
	global_load_lds_dwordx4 v[208:209], off
	v_lshl_add_u64 v[208:209], v[212:213], 0, s[76:77]
	s_mov_b32 m0, s54
	s_nop 0
	global_load_lds_dwordx4 v[208:209], off
	v_lshl_add_u64 v[208:209], v[214:215], 0, s[76:77]
	s_mov_b32 m0, s55
	s_nop 0
	global_load_lds_dwordx4 v[208:209], off
	s_waitcnt vmcnt(8)
	s_waitcnt lgkmcnt(0)
	s_barrier
	v_mfma_f32_16x16x32_bf16 v[84:87], v[132:135], v[164:167], v[84:87]
	v_mfma_f32_16x16x32_bf16 v[84:87], v[136:139], v[168:171], v[84:87]
	v_mfma_f32_16x16x32_bf16 v[72:75], v[136:139], v[176:179], v[72:75]
	v_mfma_f32_16x16x32_bf16 v[72:75], v[132:135], v[172:175], v[72:75]
	v_mfma_f32_16x16x32_bf16 v[60:63], v[132:135], v[180:183], v[60:63]
	v_mfma_f32_16x16x32_bf16 v[60:63], v[136:139], v[184:187], v[60:63]
	v_mfma_f32_16x16x32_bf16 v[48:51], v[136:139], v[192:195], v[48:51]
	v_mfma_f32_16x16x32_bf16 v[48:51], v[132:135], v[188:191], v[48:51]
	v_mfma_f32_16x16x32_bf16 v[44:47], v[140:143], v[188:191], v[44:47]
	v_mfma_f32_16x16x32_bf16 v[44:47], v[144:147], v[192:195], v[44:47]
	v_mfma_f32_16x16x32_bf16 v[56:59], v[144:147], v[184:187], v[56:59]
	v_mfma_f32_16x16x32_bf16 v[56:59], v[140:143], v[180:183], v[56:59]
	v_mfma_f32_16x16x32_bf16 v[68:71], v[140:143], v[172:175], v[68:71]
	v_mfma_f32_16x16x32_bf16 v[68:71], v[144:147], v[176:179], v[68:71]
	v_mfma_f32_16x16x32_bf16 v[76:79], v[144:147], v[168:171], v[76:79]
	v_mfma_f32_16x16x32_bf16 v[76:79], v[140:143], v[164:167], v[76:79]
	v_mfma_f32_16x16x32_bf16 v[40:43], v[148:151], v[164:167], v[40:43]
	v_mfma_f32_16x16x32_bf16 v[40:43], v[152:155], v[168:171], v[40:43]
	v_mfma_f32_16x16x32_bf16 v[28:31], v[152:155], v[176:179], v[28:31]
	v_mfma_f32_16x16x32_bf16 v[28:31], v[148:151], v[172:175], v[28:31]
	v_mfma_f32_16x16x32_bf16 v[16:19], v[148:151], v[180:183], v[16:19]
	v_mfma_f32_16x16x32_bf16 v[16:19], v[152:155], v[184:187], v[16:19]
	v_mfma_f32_16x16x32_bf16 v[8:11], v[152:155], v[192:195], v[8:11]
	v_mfma_f32_16x16x32_bf16 v[8:11], v[148:151], v[188:191], v[8:11]
	v_mfma_f32_16x16x32_bf16 v[4:7], v[156:159], v[188:191], v[4:7]
	v_mfma_f32_16x16x32_bf16 v[4:7], v[160:163], v[192:195], v[4:7]
	v_mfma_f32_16x16x32_bf16 v[12:15], v[160:163], v[184:187], v[12:15]
	v_mfma_f32_16x16x32_bf16 v[12:15], v[156:159], v[180:183], v[12:15]
	v_mfma_f32_16x16x32_bf16 v[24:27], v[156:159], v[172:175], v[24:27]
	v_mfma_f32_16x16x32_bf16 v[24:27], v[160:163], v[176:179], v[24:27]
	v_mfma_f32_16x16x32_bf16 v[36:39], v[160:163], v[168:171], v[36:39]
	v_mfma_f32_16x16x32_bf16 v[36:39], v[156:159], v[164:167], v[36:39]
	s_barrier
	s_add_u32 s12, s12, 0x100
	s_addc_u32 s13, s13, 0
	s_add_u32 s3, s3, 0x100
	s_addc_u32 s11, s11, 0
	s_cmp_ge_u32 s20, s2
	s_mov_b32 s14, s20
	s_cbranch_scc0 .LBB0_1164
	s_and_b64 vcc, exec, s[8:9]
	s_cbranch_vccz .LBB0_1167
	s_barrier

;     __device__ __forceinline__ int nt(const Unit& u) const { return (u.pn >> 1) < 2 ? 22 : 20; }
; #define PG8_STAGE(bufoff, gbase, voff) do { _Pragma("unroll") for (int _i = 0; _i < 2; ++_i) \
;         __builtin_amdgcn_global_load_lds((const unsigned*)((const char*)(gbase) + (voff)[_i]), (LAS unsigned*)(lds + (bufoff) + ldsw + _i * 8192), 16, 0, 0); } while (0)
; #define PG8_LDA(dst, b, h) do { _Pragma("unroll") for (int m = 0; m < 4; ++m) _Pragma("unroll") for (int k = 0; k < 2; ++k) dst[m][k] = *(const LAS bf16x8*)(pA + PG8_SA(b, h) + m * 2048 + k * 1024); } while (0)
; #define PG8_LDB(dst, b, h) do { _Pragma("unroll") for (int n = 0; n < 2; ++n) _Pragma("unroll") for (int k = 0; k < 2; ++k) dst[n][k] = *(const LAS bf16x8*)(pB + (PG8_SB(b, h) - 4 * HTB) + n * 2048 + k * 1024); } while (0)
; #define PG8_MMA(ai, bj, At, Bt) do { __builtin_amdgcn_s_setprio(1); _Pragma("unroll") for (int m = 0; m < 4; ++m) _Pragma("unroll") for (int n = 0; n < 2; ++n) _Pragma("unroll") for (int k = 0; k < 2; ++k) \
;         acc[ai][bj][m][n] = __builtin_amdgcn_mfma_f32_16x16x32_bf16(Bt[n][k], At[m][k], acc[ai][bj][m][n], 0, 0, 0); __builtin_amdgcn_s_setprio(0); } while (0)
; #define PG8_WAIT_V(n) asm volatile("s_waitcnt vmcnt(" #n ")" ::: "memory")
; #define PG8_BAR __builtin_amdgcn_s_barrier()
; template <class Desc, class Epi, bool ALIGN_EPI>
; __device__ __forceinline__ void gemm_phase(LAS unsigned char* lds, const Desc& D, const Epi& E, int G, int c) {
;     ...
;         for (int t = 0; t < nt; t += 2) {
;             const bool last = (t == nt - 2);
;             if (last && has_next) PG8_AWAIT(nxt);
;             const char* a1 = cA + (size_t)(t + 1) * kstep;
;             const char* a2 = last ? nA : cA + (size_t)(t + 2) * kstep; const char* b2 = last ? nB : cB + (size_t)(t + 2) * kstep;
;             const char* a3 = a2 + kstep; const char* b3 = b2 + kstep;
;             PG8_LDB(B0, 0, 0); PG8_LDB(B1, 0, 1); PG8_SCHED; PG8_LDA(At, 0, 0); PG8_STAGE(PG8_SA(1, 1), a1 + hstepA, voffA);
;             PG8_WAIT_V(8); PG8_WAIT_L(0); PG8_BAR; PG8_MMA(0, 0, At, B0); PG8_MMA(0, 1, At, B1); PG8_BAR; PG8_SCHED;
;             PG8_LDA(At, 0, 1); PG8_STAGE(PG8_SB(0, 0), b2, voffB); PG8_STAGE(PG8_SB(0, 1), b2 + hstepB, voffB); PG8_STAGE(PG8_SA(0, 0), a2, voffA);
;             PG8_WAIT_V(8); PG8_WAIT_L(0); PG8_BAR; PG8_MMA(1, 0, At, B0); PG8_MMA(1, 1, At, B1); PG8_BAR; PG8_SCHED;
.LBB0_1324:
	ds_read_b128 v[144:147], v149
	ds_read_b128 v[152:155], v149 offset:1024
	ds_read_b128 v[156:159], v149 offset:2048
	ds_read_b128 v[160:163], v149 offset:3072
	ds_read_b128 v[164:167], v149 offset:16384
	ds_read_b128 v[168:171], v149 offset:17408
	ds_read_b128 v[172:175], v149 offset:18432
	ds_read_b128 v[176:179], v149 offset:19456
	s_add_i32 s50, s18, 2
	s_add_u32 s19, s16, 0xfff00080
	s_addc_u32 s20, s17, -1
	s_cmp_eq_u32 s9, s18
	s_cselect_b32 s18, s12, s48
	s_cselect_b32 s21, s11, s20
	s_cselect_b32 s20, s10, s19
	s_cselect_b32 s19, s13, s49
	v_lshl_add_u64 v[212:213], s[16:17], 0, v[140:141]
	s_add_i32 m0, s24, 0xc000
	ds_read_b128 v[180:183], v148
	ds_read_b128 v[184:187], v148 offset:1024
	ds_read_b128 v[188:191], v148 offset:2048
	ds_read_b128 v[192:195], v148 offset:3072
	ds_read_b128 v[196:199], v148 offset:4096
	ds_read_b128 v[200:203], v148 offset:5120
	ds_read_b128 v[204:207], v148 offset:6144
	ds_read_b128 v[208:211], v148 offset:7168
	global_load_lds_dwordx4 v[212:213], off
	v_lshl_add_u64 v[212:213], s[16:17], 0, v[142:143]
	s_add_i32 m0, s24, 0xe000
	s_nop 0
	global_load_lds_dwordx4 v[212:213], off
	s_waitcnt vmcnt(8)
	s_waitcnt lgkmcnt(0)
	s_barrier
	v_mfma_f32_16x16x32_bf16 v[128:131], v[144:147], v[180:183], v[128:131]
	v_mfma_f32_16x16x32_bf16 v[128:131], v[152:155], v[184:187], v[128:131]
	v_mfma_f32_16x16x32_bf16 v[120:123], v[152:155], v[192:195], v[120:123]
	v_mfma_f32_16x16x32_bf16 v[120:123], v[144:147], v[188:191], v[120:123]
	v_mfma_f32_16x16x32_bf16 v[104:107], v[144:147], v[196:199], v[104:107]
	v_mfma_f32_16x16x32_bf16 v[104:107], v[152:155], v[200:203], v[104:107]
	v_mfma_f32_16x16x32_bf16 v[88:91], v[152:155], v[208:211], v[88:91]
	v_mfma_f32_16x16x32_bf16 v[88:91], v[144:147], v[204:207], v[88:91]
	v_mfma_f32_16x16x32_bf16 v[80:83], v[156:159], v[204:207], v[80:83]
	v_mfma_f32_16x16x32_bf16 v[80:83], v[160:163], v[208:211], v[80:83]
	v_mfma_f32_16x16x32_bf16 v[96:99], v[160:163], v[200:203], v[96:99]
	v_mfma_f32_16x16x32_bf16 v[96:99], v[156:159], v[196:199], v[96:99]
	v_mfma_f32_16x16x32_bf16 v[112:115], v[156:159], v[188:191], v[112:115]
	v_mfma_f32_16x16x32_bf16 v[112:115], v[160:163], v[192:195], v[112:115]
	v_mfma_f32_16x16x32_bf16 v[124:127], v[160:163], v[184:187], v[124:127]
	v_mfma_f32_16x16x32_bf16 v[124:127], v[156:159], v[180:183], v[124:127]
	v_mfma_f32_16x16x32_bf16 v[116:119], v[164:167], v[180:183], v[116:119]
	v_mfma_f32_16x16x32_bf16 v[116:119], v[168:171], v[184:187], v[116:119]
	v_mfma_f32_16x16x32_bf16 v[100:103], v[168:171], v[192:195], v[100:103]
	v_mfma_f32_16x16x32_bf16 v[100:103], v[164:167], v[188:191], v[100:103]
	v_mfma_f32_16x16x32_bf16 v[84:87], v[164:167], v[196:199], v[84:87]
	v_mfma_f32_16x16x32_bf16 v[84:87], v[168:171], v[200:203], v[84:87]
	v_mfma_f32_16x16x32_bf16 v[72:75], v[168:171], v[208:211], v[72:75]
	v_mfma_f32_16x16x32_bf16 v[72:75], v[164:167], v[204:207], v[72:75]
	v_mfma_f32_16x16x32_bf16 v[68:71], v[172:175], v[204:207], v[68:71]
	v_mfma_f32_16x16x32_bf16 v[68:71], v[176:179], v[208:211], v[68:71]
	v_mfma_f32_16x16x32_bf16 v[76:79], v[176:179], v[200:203], v[76:79]
	v_mfma_f32_16x16x32_bf16 v[76:79], v[172:175], v[196:199], v[76:79]
	v_mfma_f32_16x16x32_bf16 v[92:95], v[172:175], v[188:191], v[92:95]
	v_mfma_f32_16x16x32_bf16 v[92:95], v[176:179], v[192:195], v[92:95]
	v_mfma_f32_16x16x32_bf16 v[108:111], v[176:179], v[184:187], v[108:111]
	v_mfma_f32_16x16x32_bf16 v[108:111], v[172:175], v[180:183], v[108:111]
	s_barrier
	s_mov_b32 m0, s25
	v_lshl_add_u64 v[212:213], s[18:19], 0, v[136:137]
	s_add_u32 s52, s18, 0x100000
	ds_read_b128 v[180:183], v148 offset:16384
	ds_read_b128 v[184:187], v148 offset:17408
	ds_read_b128 v[188:191], v148 offset:18432
	ds_read_b128 v[192:195], v148 offset:19456
	ds_read_b128 v[196:199], v148 offset:20480
	ds_read_b128 v[200:203], v148 offset:21504
	ds_read_b128 v[204:207], v148 offset:22528
	ds_read_b128 v[208:211], v148 offset:23552
	global_load_lds_dwordx4 v[212:213], off
	v_lshl_add_u64 v[214:215], s[18:19], 0, v[132:133]
	s_mov_b32 m0, s26
	s_addc_u32 s53, s19, 0
	global_load_lds_dwordx4 v[214:215], off
	v_lshl_add_u64 v[216:217], s[52:53], 0, v[136:137]
	s_mov_b32 m0, s27
	v_lshl_add_u64 v[218:219], s[20:21], 0, v[134:135]
	global_load_lds_dwordx4 v[216:217], off
	v_lshl_add_u64 v[216:217], s[52:53], 0, v[132:133]
	s_mov_b32 m0, s30
	s_nop 0
	global_load_lds_dwordx4 v[216:217], off
	v_lshl_add_u64 v[216:217], s[20:21], 0, v[138:139]
	s_mov_b32 m0, s24
	s_nop 0
	global_load_lds_dwordx4 v[216:217], off
	s_mov_b32 m0, s31
	s_nop 0
	global_load_lds_dwordx4 v[218:219], off
	s_waitcnt vmcnt(8)
	s_waitcnt lgkmcnt(0)
	s_barrier
; #define PG8_STAGE(bufoff, gbase, voff) do { _Pragma("unroll") for (int _i = 0; _i < 2; ++_i) \
;         __builtin_amdgcn_global_load_lds((const unsigned*)((const char*)(gbase) + (voff)[_i]), (LAS unsigned*)(lds + (bufoff) + ldsw + _i * 8192), 16, 0, 0); } while (0)
; #define PG8_LDA(dst, b, h) do { _Pragma("unroll") for (int m = 0; m < 4; ++m) _Pragma("unroll") for (int k = 0; k < 2; ++k) dst[m][k] = *(const LAS bf16x8*)(pA + PG8_SA(b, h) + m * 2048 + k * 1024); } while (0)
; #define PG8_LDB(dst, b, h) do { _Pragma("unroll") for (int n = 0; n < 2; ++n) _Pragma("unroll") for (int k = 0; k < 2; ++k) dst[n][k] = *(const LAS bf16x8*)(pB + (PG8_SB(b, h) - 4 * HTB) + n * 2048 + k * 1024); } while (0)
; #define PG8_MMA(ai, bj, At, Bt) do { __builtin_amdgcn_s_setprio(1); _Pragma("unroll") for (int m = 0; m < 4; ++m) _Pragma("unroll") for (int n = 0; n < 2; ++n) _Pragma("unroll") for (int k = 0; k < 2; ++k) \
;         acc[ai][bj][m][n] = __builtin_amdgcn_mfma_f32_16x16x32_bf16(Bt[n][k], At[m][k], acc[ai][bj][m][n], 0, 0, 0); __builtin_amdgcn_s_setprio(0); } while (0)
; #define PG8_WAIT_V(n) asm volatile("s_waitcnt vmcnt(" #n ")" ::: "memory")
; #define PG8_WAIT_L(n) asm volatile("s_waitcnt lgkmcnt(" #n ")" ::: "memory")
; #define PG8_BAR __builtin_amdgcn_s_barrier()
; #define PG8_SCHED __builtin_amdgcn_sched_barrier(0)
; template <class Desc, class Epi, bool ALIGN_EPI>
; __device__ __forceinline__ void gemm_phase(LAS unsigned char* lds, const Desc& D, const Epi& E, int G, int c) {
;     ...
;             PG8_WAIT_V(8); PG8_WAIT_L(0); PG8_BAR; PG8_MMA(1, 0, At, B0); PG8_MMA(1, 1, At, B1); PG8_BAR; PG8_SCHED;
;             PG8_LDB(B0, 1, 0); PG8_LDB(B1, 1, 1); PG8_SCHED; PG8_LDA(At, 1, 0); PG8_STAGE(PG8_SA(0, 1), a2 + hstepA, voffA);
;             PG8_WAIT_V(8); PG8_WAIT_L(0); PG8_BAR; PG8_MMA(0, 0, At, B0); PG8_MMA(0, 1, At, B1); PG8_BAR; PG8_SCHED;
	v_mfma_f32_16x16x32_bf16 v[64:67], v[144:147], v[180:183], v[64:67]
	v_mfma_f32_16x16x32_bf16 v[64:67], v[152:155], v[184:187], v[64:67]
	v_mfma_f32_16x16x32_bf16 v[56:59], v[152:155], v[192:195], v[56:59]
	v_mfma_f32_16x16x32_bf16 v[56:59], v[144:147], v[188:191], v[56:59]
	v_mfma_f32_16x16x32_bf16 v[40:43], v[144:147], v[196:199], v[40:43]
	v_mfma_f32_16x16x32_bf16 v[40:43], v[152:155], v[200:203], v[40:43]
	v_mfma_f32_16x16x32_bf16 v[24:27], v[152:155], v[208:211], v[24:27]
	v_mfma_f32_16x16x32_bf16 v[24:27], v[144:147], v[204:207], v[24:27]
	v_mfma_f32_16x16x32_bf16 v[16:19], v[156:159], v[204:207], v[16:19]
	v_mfma_f32_16x16x32_bf16 v[16:19], v[160:163], v[208:211], v[16:19]
	v_mfma_f32_16x16x32_bf16 v[32:35], v[160:163], v[200:203], v[32:35]
	v_mfma_f32_16x16x32_bf16 v[32:35], v[156:159], v[196:199], v[32:35]
	v_mfma_f32_16x16x32_bf16 v[48:51], v[156:159], v[188:191], v[48:51]
	v_mfma_f32_16x16x32_bf16 v[48:51], v[160:163], v[192:195], v[48:51]
	v_mfma_f32_16x16x32_bf16 v[60:63], v[160:163], v[184:187], v[60:63]
	v_mfma_f32_16x16x32_bf16 v[60:63], v[156:159], v[180:183], v[60:63]
	v_mfma_f32_16x16x32_bf16 v[52:55], v[164:167], v[180:183], v[52:55]
	v_mfma_f32_16x16x32_bf16 v[52:55], v[168:171], v[184:187], v[52:55]
	v_mfma_f32_16x16x32_bf16 v[36:39], v[168:171], v[192:195], v[36:39]
	v_mfma_f32_16x16x32_bf16 v[36:39], v[164:167], v[188:191], v[36:39]
	v_mfma_f32_16x16x32_bf16 v[20:23], v[164:167], v[196:199], v[20:23]
	v_mfma_f32_16x16x32_bf16 v[20:23], v[168:171], v[200:203], v[20:23]
	v_mfma_f32_16x16x32_bf16 v[8:11], v[168:171], v[208:211], v[8:11]
	v_mfma_f32_16x16x32_bf16 v[8:11], v[164:167], v[204:207], v[8:11]
	v_mfma_f32_16x16x32_bf16 v[4:7], v[172:175], v[204:207], v[4:7]
	v_mfma_f32_16x16x32_bf16 v[4:7], v[176:179], v[208:211], v[4:7]
	v_mfma_f32_16x16x32_bf16 v[12:15], v[176:179], v[200:203], v[12:15]
	v_mfma_f32_16x16x32_bf16 v[12:15], v[172:175], v[196:199], v[12:15]
	v_mfma_f32_16x16x32_bf16 v[28:31], v[172:175], v[188:191], v[28:31]
	v_mfma_f32_16x16x32_bf16 v[28:31], v[176:179], v[192:195], v[28:31]
	v_mfma_f32_16x16x32_bf16 v[44:47], v[176:179], v[184:187], v[44:47]
	v_mfma_f32_16x16x32_bf16 v[44:47], v[172:175], v[180:183], v[44:47]
	s_barrier
	ds_read_b128 v[144:147], v149 offset:32768
	ds_read_b128 v[152:155], v149 offset:33792
	ds_read_b128 v[156:159], v149 offset:34816
	ds_read_b128 v[160:163], v149 offset:35840
	ds_read_b128 v[164:167], v149 offset:49152
	ds_read_b128 v[168:171], v149 offset:50176
	ds_read_b128 v[172:175], v149 offset:51200
	ds_read_b128 v[176:179], v149 offset:52224
	s_add_u32 s20, s20, 0x100000
	s_addc_u32 s21, s21, 0
	s_mov_b32 m0, s33
	v_lshl_add_u64 v[220:221], s[20:21], 0, v[138:139]
	ds_read_b128 v[180:183], v148 offset:32768
	ds_read_b128 v[184:187], v148 offset:33792
	ds_read_b128 v[188:191], v148 offset:34816
	ds_read_b128 v[192:195], v148 offset:35840
	ds_read_b128 v[196:199], v148 offset:36864
	ds_read_b128 v[200:203], v148 offset:37888
	ds_read_b128 v[204:207], v148 offset:38912
	ds_read_b128 v[208:211], v148 offset:39936
	global_load_lds_dwordx4 v[220:221], off
	v_lshl_add_u64 v[220:221], s[20:21], 0, v[134:135]
	s_mov_b32 m0, s34
	s_nop 0
	global_load_lds_dwordx4 v[220:221], off
	s_waitcnt vmcnt(8)
	s_waitcnt lgkmcnt(0)
	s_barrier
	v_mfma_f32_16x16x32_bf16 v[128:131], v[144:147], v[180:183], v[128:131]
	v_mfma_f32_16x16x32_bf16 v[128:131], v[152:155], v[184:187], v[128:131]
	v_mfma_f32_16x16x32_bf16 v[120:123], v[152:155], v[192:195], v[120:123]
	v_mfma_f32_16x16x32_bf16 v[120:123], v[144:147], v[188:191], v[120:123]
	v_mfma_f32_16x16x32_bf16 v[104:107], v[144:147], v[196:199], v[104:107]
	v_mfma_f32_16x16x32_bf16 v[104:107], v[152:155], v[200:203], v[104:107]
	v_mfma_f32_16x16x32_bf16 v[88:91], v[152:155], v[208:211], v[88:91]
	v_mfma_f32_16x16x32_bf16 v[88:91], v[144:147], v[204:207], v[88:91]
	v_mfma_f32_16x16x32_bf16 v[80:83], v[156:159], v[204:207], v[80:83]
	v_mfma_f32_16x16x32_bf16 v[80:83], v[160:163], v[208:211], v[80:83]
	v_mfma_f32_16x16x32_bf16 v[96:99], v[160:163], v[200:203], v[96:99]
	v_mfma_f32_16x16x32_bf16 v[96:99], v[156:159], v[196:199], v[96:99]
	v_mfma_f32_16x16x32_bf16 v[112:115], v[156:159], v[188:191], v[112:115]
	v_mfma_f32_16x16x32_bf16 v[112:115], v[160:163], v[192:195], v[112:115]
	v_mfma_f32_16x16x32_bf16 v[124:127], v[160:163], v[184:187], v[124:127]
	v_mfma_f32_16x16x32_bf16 v[124:127], v[156:159], v[180:183], v[124:127]
	v_mfma_f32_16x16x32_bf16 v[116:119], v[164:167], v[180:183], v[116:119]
	v_mfma_f32_16x16x32_bf16 v[116:119], v[168:171], v[184:187], v[116:119]
	v_mfma_f32_16x16x32_bf16 v[100:103], v[168:171], v[192:195], v[100:103]
	v_mfma_f32_16x16x32_bf16 v[100:103], v[164:167], v[188:191], v[100:103]
	v_mfma_f32_16x16x32_bf16 v[84:87], v[164:167], v[196:199], v[84:87]
	v_mfma_f32_16x16x32_bf16 v[84:87], v[168:171], v[200:203], v[84:87]
	v_mfma_f32_16x16x32_bf16 v[72:75], v[168:171], v[208:211], v[72:75]
	v_mfma_f32_16x16x32_bf16 v[72:75], v[164:167], v[204:207], v[72:75]
	v_mfma_f32_16x16x32_bf16 v[68:71], v[172:175], v[204:207], v[68:71]
	v_mfma_f32_16x16x32_bf16 v[68:71], v[176:179], v[208:211], v[68:71]
	v_mfma_f32_16x16x32_bf16 v[76:79], v[176:179], v[200:203], v[76:79]
	v_mfma_f32_16x16x32_bf16 v[76:79], v[172:175], v[196:199], v[76:79]
	v_mfma_f32_16x16x32_bf16 v[92:95], v[172:175], v[188:191], v[92:95]
	v_mfma_f32_16x16x32_bf16 v[92:95], v[176:179], v[192:195], v[92:95]
	v_mfma_f32_16x16x32_bf16 v[108:111], v[176:179], v[184:187], v[108:111]
	v_mfma_f32_16x16x32_bf16 v[108:111], v[172:175], v[180:183], v[108:111]
	s_barrier
; #define PG8_STAGE(bufoff, gbase, voff) do { _Pragma("unroll") for (int _i = 0; _i < 2; ++_i) \
;         __builtin_amdgcn_global_load_lds((const unsigned*)((const char*)(gbase) + (voff)[_i]), (LAS unsigned*)(lds + (bufoff) + ldsw + _i * 8192), 16, 0, 0); } while (0)
; #define PG8_LDA(dst, b, h) do { _Pragma("unroll") for (int m = 0; m < 4; ++m) _Pragma("unroll") for (int k = 0; k < 2; ++k) dst[m][k] = *(const LAS bf16x8*)(pA + PG8_SA(b, h) + m * 2048 + k * 1024); } while (0)
; #define PG8_MMA(ai, bj, At, Bt) do { __builtin_amdgcn_s_setprio(1); _Pragma("unroll") for (int m = 0; m < 4; ++m) _Pragma("unroll") for (int n = 0; n < 2; ++n) _Pragma("unroll") for (int k = 0; k < 2; ++k) \
;         acc[ai][bj][m][n] = __builtin_amdgcn_mfma_f32_16x16x32_bf16(Bt[n][k], At[m][k], acc[ai][bj][m][n], 0, 0, 0); __builtin_amdgcn_s_setprio(0); } while (0)
; #define PG8_WAIT_V(n) asm volatile("s_waitcnt vmcnt(" #n ")" ::: "memory")
; #define PG8_WAIT_L(n) asm volatile("s_waitcnt lgkmcnt(" #n ")" ::: "memory")
; #define PG8_BAR __builtin_amdgcn_s_barrier()
; #define PG8_SCHED __builtin_amdgcn_sched_barrier(0)
; template <class Desc, class Epi, bool ALIGN_EPI>
; __device__ __forceinline__ void gemm_phase(LAS unsigned char* lds, const Desc& D, const Epi& E, int G, int c) {
;     ...
;             PG8_LDA(At, 1, 1); PG8_STAGE(PG8_SB(1, 0), b3, voffB); PG8_STAGE(PG8_SB(1, 1), b3 + hstepB, voffB); PG8_STAGE(PG8_SA(1, 0), a3, voffA);
;             PG8_WAIT_V(8); PG8_WAIT_L(0); PG8_BAR; PG8_MMA(1, 0, At, B0); PG8_MMA(1, 1, At, B1); PG8_BAR; PG8_SCHED;
;         }
;         if constexpr (ALIGN_EPI) { if (wr == 0) PG8_BAR; }
	s_mov_b32 m0, s35
	v_lshl_add_u64 v[212:213], v[212:213], 0, s[76:77]
	s_add_u32 s18, s18, 0x100080
	ds_read_b128 v[180:183], v148 offset:49152
	ds_read_b128 v[184:187], v148 offset:50176
	ds_read_b128 v[188:191], v148 offset:51200
	ds_read_b128 v[192:195], v148 offset:52224
	ds_read_b128 v[196:199], v148 offset:53248
	ds_read_b128 v[200:203], v148 offset:54272
	ds_read_b128 v[204:207], v148 offset:55296
	ds_read_b128 v[208:211], v148 offset:56320
	global_load_lds_dwordx4 v[212:213], off
	v_lshl_add_u64 v[212:213], v[214:215], 0, s[76:77]
	s_mov_b32 m0, s38
	s_addc_u32 s19, s19, 0
	global_load_lds_dwordx4 v[212:213], off
	v_lshl_add_u64 v[212:213], s[18:19], 0, v[136:137]
	s_mov_b32 m0, s41
	s_nop 0
	global_load_lds_dwordx4 v[212:213], off
	v_lshl_add_u64 v[212:213], s[18:19], 0, v[132:133]
	s_mov_b32 m0, s42
	s_nop 0
	global_load_lds_dwordx4 v[212:213], off
	v_lshl_add_u64 v[212:213], v[216:217], 0, s[76:77]
	s_mov_b32 m0, s39
	s_nop 0
	global_load_lds_dwordx4 v[212:213], off
	v_lshl_add_u64 v[212:213], v[218:219], 0, s[76:77]
	s_mov_b32 m0, s40
	s_nop 0
	global_load_lds_dwordx4 v[212:213], off
	s_waitcnt vmcnt(8)
	s_waitcnt lgkmcnt(0)
	s_barrier
	v_mfma_f32_16x16x32_bf16 v[64:67], v[144:147], v[180:183], v[64:67]
	v_mfma_f32_16x16x32_bf16 v[64:67], v[152:155], v[184:187], v[64:67]
	v_mfma_f32_16x16x32_bf16 v[56:59], v[152:155], v[192:195], v[56:59]
	v_mfma_f32_16x16x32_bf16 v[56:59], v[144:147], v[188:191], v[56:59]
	v_mfma_f32_16x16x32_bf16 v[40:43], v[144:147], v[196:199], v[40:43]
	v_mfma_f32_16x16x32_bf16 v[40:43], v[152:155], v[200:203], v[40:43]
	v_mfma_f32_16x16x32_bf16 v[24:27], v[152:155], v[208:211], v[24:27]
	v_mfma_f32_16x16x32_bf16 v[24:27], v[144:147], v[204:207], v[24:27]
	v_mfma_f32_16x16x32_bf16 v[16:19], v[156:159], v[204:207], v[16:19]
	v_mfma_f32_16x16x32_bf16 v[16:19], v[160:163], v[208:211], v[16:19]
	v_mfma_f32_16x16x32_bf16 v[32:35], v[160:163], v[200:203], v[32:35]
	v_mfma_f32_16x16x32_bf16 v[32:35], v[156:159], v[196:199], v[32:35]
	v_mfma_f32_16x16x32_bf16 v[48:51], v[156:159], v[188:191], v[48:51]
	v_mfma_f32_16x16x32_bf16 v[48:51], v[160:163], v[192:195], v[48:51]
	v_mfma_f32_16x16x32_bf16 v[60:63], v[160:163], v[184:187], v[60:63]
	v_mfma_f32_16x16x32_bf16 v[60:63], v[156:159], v[180:183], v[60:63]
	v_mfma_f32_16x16x32_bf16 v[52:55], v[164:167], v[180:183], v[52:55]
	v_mfma_f32_16x16x32_bf16 v[52:55], v[168:171], v[184:187], v[52:55]
	v_mfma_f32_16x16x32_bf16 v[36:39], v[168:171], v[192:195], v[36:39]
	v_mfma_f32_16x16x32_bf16 v[36:39], v[164:167], v[188:191], v[36:39]
	v_mfma_f32_16x16x32_bf16 v[20:23], v[164:167], v[196:199], v[20:23]
	v_mfma_f32_16x16x32_bf16 v[20:23], v[168:171], v[200:203], v[20:23]
	v_mfma_f32_16x16x32_bf16 v[8:11], v[168:171], v[208:211], v[8:11]
	v_mfma_f32_16x16x32_bf16 v[8:11], v[164:167], v[204:207], v[8:11]
	v_mfma_f32_16x16x32_bf16 v[4:7], v[172:175], v[204:207], v[4:7]
	v_mfma_f32_16x16x32_bf16 v[4:7], v[176:179], v[208:211], v[4:7]
	v_mfma_f32_16x16x32_bf16 v[12:15], v[176:179], v[200:203], v[12:15]
	v_mfma_f32_16x16x32_bf16 v[12:15], v[172:175], v[196:199], v[12:15]
	v_mfma_f32_16x16x32_bf16 v[28:31], v[172:175], v[188:191], v[28:31]
	v_mfma_f32_16x16x32_bf16 v[28:31], v[176:179], v[192:195], v[28:31]
	v_mfma_f32_16x16x32_bf16 v[44:47], v[176:179], v[184:187], v[44:47]
	v_mfma_f32_16x16x32_bf16 v[44:47], v[172:175], v[180:183], v[44:47]
	s_barrier
	s_add_u32 s16, s16, 0x100
	s_addc_u32 s17, s17, 0
	s_add_u32 s48, s48, 0x100
	s_addc_u32 s49, s49, 0
	s_cmp_ge_u32 s50, s46
	s_mov_b32 s18, s50
	s_cbranch_scc0 .LBB0_1324
	s_and_b64 vcc, exec, s[6:7]
	s_cbranch_vccz .LBB0_1327
	s_barrier

;     __device__ __forceinline__ int nt(const Unit& u) const { return (u.pn >> 1) < 2 ? 22 : 20; }
; #define PG8_STAGE(bufoff, gbase, voff) do { _Pragma("unroll") for (int _i = 0; _i < 2; ++_i) \
;         __builtin_amdgcn_global_load_lds((const unsigned*)((const char*)(gbase) + (voff)[_i]), (LAS unsigned*)(lds + (bufoff) + ldsw + _i * 8192), 16, 0, 0); } while (0)
; #define PG8_LDA(dst, b, h) do { _Pragma("unroll") for (int m = 0; m < 4; ++m) _Pragma("unroll") for (int k = 0; k < 2; ++k) dst[m][k] = *(const LAS bf16x8*)(pA + PG8_SA(b, h) + m * 2048 + k * 1024); } while (0)
; #define PG8_LDB(dst, b, h) do { _Pragma("unroll") for (int n = 0; n < 2; ++n) _Pragma("unroll") for (int k = 0; k < 2; ++k) dst[n][k] = *(const LAS bf16x8*)(pB + (PG8_SB(b, h) - 4 * HTB) + n * 2048 + k * 1024); } while (0)
; #define PG8_MMA(ai, bj, At, Bt) do { __builtin_amdgcn_s_setprio(1); _Pragma("unroll") for (int m = 0; m < 4; ++m) _Pragma("unroll") for (int n = 0; n < 2; ++n) _Pragma("unroll") for (int k = 0; k < 2; ++k) \
;         acc[ai][bj][m][n] = __builtin_amdgcn_mfma_f32_16x16x32_bf16(Bt[n][k], At[m][k], acc[ai][bj][m][n], 0, 0, 0); __builtin_amdgcn_s_setprio(0); } while (0)
; #define PG8_WAIT_V(n) asm volatile("s_waitcnt vmcnt(" #n ")" ::: "memory")
; #define PG8_BAR __builtin_amdgcn_s_barrier()
; template <class Desc, class Epi, bool ALIGN_EPI>
; __device__ __forceinline__ void gemm_phase(LAS unsigned char* lds, const Desc& D, const Epi& E, int G, int c) {
;     ...
;         for (int t = 0; t < nt; t += 2) {
;             const bool last = (t == nt - 2);
;             if (last && has_next) PG8_AWAIT(nxt);
;             const char* a1 = cA + (size_t)(t + 1) * kstep;
;             const char* a2 = last ? nA : cA + (size_t)(t + 2) * kstep; const char* b2 = last ? nB : cB + (size_t)(t + 2) * kstep;
;             const char* a3 = a2 + kstep; const char* b3 = b2 + kstep;
;             PG8_LDB(B0, 0, 0); PG8_LDB(B1, 0, 1); PG8_SCHED; PG8_LDA(At, 0, 0); PG8_STAGE(PG8_SA(1, 1), a1 + hstepA, voffA);
;             PG8_WAIT_V(8); PG8_WAIT_L(0); PG8_BAR; PG8_MMA(0, 0, At, B0); PG8_MMA(0, 1, At, B1); PG8_BAR; PG8_SCHED;
;             PG8_LDA(At, 0, 1); PG8_STAGE(PG8_SB(0, 0), b2, voffB); PG8_STAGE(PG8_SB(0, 1), b2 + hstepB, voffB); PG8_STAGE(PG8_SA(0, 0), a2, voffA);
;             PG8_WAIT_V(8); PG8_WAIT_L(0); PG8_BAR; PG8_MMA(1, 0, At, B0); PG8_MMA(1, 1, At, B1); PG8_BAR; PG8_SCHED;
.LBB0_1479:
	ds_read_b128 v[116:119], v225
	ds_read_b128 v[128:131], v225 offset:1024
	ds_read_b128 v[132:135], v225 offset:2048
	ds_read_b128 v[136:139], v225 offset:3072
	ds_read_b128 v[140:143], v225 offset:16384
	ds_read_b128 v[144:147], v225 offset:17408
	ds_read_b128 v[148:151], v225 offset:18432
	ds_read_b128 v[152:155], v225 offset:19456
	s_add_u32 s12, s0, 0xfffe0080
	s_addc_u32 s13, s1, -1
	s_cmp_eq_u32 s52, 4
	s_cselect_b32 s17, s37, s13
	s_cselect_b32 s16, s36, s12
	s_cselect_b32 s13, s21, s33
	s_cselect_b32 s12, s24, s27
	v_lshl_add_u64 v[208:209], s[0:1], 0, v[200:201]
	s_add_i32 m0, s31, 0xc000
	ds_read_b128 v[164:167], v224
	ds_read_b128 v[168:171], v224 offset:1024
	ds_read_b128 v[172:175], v224 offset:2048
	ds_read_b128 v[176:179], v224 offset:3072
	ds_read_b128 v[180:183], v224 offset:4096
	ds_read_b128 v[184:187], v224 offset:5120
	ds_read_b128 v[188:191], v224 offset:6144
	ds_read_b128 v[204:207], v224 offset:7168
	global_load_lds_dwordx4 v[208:209], off
	v_lshl_add_u64 v[208:209], s[0:1], 0, v[202:203]
	s_add_i32 m0, s31, 0xe000
	s_nop 0
	global_load_lds_dwordx4 v[208:209], off
	s_waitcnt vmcnt(8)
	s_waitcnt lgkmcnt(0)
	s_barrier
	v_mfma_f32_16x16x32_bf16 v[160:163], v[116:119], v[164:167], v[160:163]
	v_mfma_f32_16x16x32_bf16 v[160:163], v[128:131], v[168:171], v[160:163]
	v_mfma_f32_16x16x32_bf16 v[112:115], v[128:131], v[176:179], v[112:115]
	v_mfma_f32_16x16x32_bf16 v[112:115], v[116:119], v[172:175], v[112:115]
	v_mfma_f32_16x16x32_bf16 v[96:99], v[116:119], v[180:183], v[96:99]
	v_mfma_f32_16x16x32_bf16 v[96:99], v[128:131], v[184:187], v[96:99]
	v_mfma_f32_16x16x32_bf16 v[80:83], v[128:131], v[204:207], v[80:83]
	v_mfma_f32_16x16x32_bf16 v[80:83], v[116:119], v[188:191], v[80:83]
	v_mfma_f32_16x16x32_bf16 v[76:79], v[132:135], v[188:191], v[76:79]
	v_mfma_f32_16x16x32_bf16 v[76:79], v[136:139], v[204:207], v[76:79]
	v_mfma_f32_16x16x32_bf16 v[92:95], v[136:139], v[184:187], v[92:95]
	v_mfma_f32_16x16x32_bf16 v[92:95], v[132:135], v[180:183], v[92:95]
	v_mfma_f32_16x16x32_bf16 v[108:111], v[132:135], v[172:175], v[108:111]
	v_mfma_f32_16x16x32_bf16 v[108:111], v[136:139], v[176:179], v[108:111]
	v_mfma_f32_16x16x32_bf16 v[156:159], v[136:139], v[168:171], v[156:159]
	v_mfma_f32_16x16x32_bf16 v[156:159], v[132:135], v[164:167], v[156:159]
	v_mfma_f32_16x16x32_bf16 v[124:127], v[140:143], v[164:167], v[124:127]
	v_mfma_f32_16x16x32_bf16 v[124:127], v[144:147], v[168:171], v[124:127]
	v_mfma_f32_16x16x32_bf16 v[104:107], v[144:147], v[176:179], v[104:107]
	v_mfma_f32_16x16x32_bf16 v[104:107], v[140:143], v[172:175], v[104:107]
	v_mfma_f32_16x16x32_bf16 v[88:91], v[140:143], v[180:183], v[88:91]
	v_mfma_f32_16x16x32_bf16 v[88:91], v[144:147], v[184:187], v[88:91]
	v_mfma_f32_16x16x32_bf16 v[72:75], v[144:147], v[204:207], v[72:75]
	v_mfma_f32_16x16x32_bf16 v[72:75], v[140:143], v[188:191], v[72:75]
	v_mfma_f32_16x16x32_bf16 v[68:71], v[148:151], v[188:191], v[68:71]
	v_mfma_f32_16x16x32_bf16 v[68:71], v[152:155], v[204:207], v[68:71]
	v_mfma_f32_16x16x32_bf16 v[84:87], v[152:155], v[184:187], v[84:87]
	v_mfma_f32_16x16x32_bf16 v[84:87], v[148:151], v[180:183], v[84:87]
	v_mfma_f32_16x16x32_bf16 v[100:103], v[148:151], v[172:175], v[100:103]
	v_mfma_f32_16x16x32_bf16 v[100:103], v[152:155], v[176:179], v[100:103]
	v_mfma_f32_16x16x32_bf16 v[120:123], v[152:155], v[168:171], v[120:123]
	v_mfma_f32_16x16x32_bf16 v[120:123], v[148:151], v[164:167], v[120:123]
	s_barrier
	s_mov_b32 m0, s34
	v_lshl_add_u64 v[208:209], s[12:13], 0, v[196:197]
	s_add_u32 s54, s12, 0x20000
	ds_read_b128 v[164:167], v224 offset:16384
	ds_read_b128 v[168:171], v224 offset:17408
	ds_read_b128 v[172:175], v224 offset:18432
	ds_read_b128 v[176:179], v224 offset:19456
	ds_read_b128 v[180:183], v224 offset:20480
	ds_read_b128 v[184:187], v224 offset:21504
	ds_read_b128 v[188:191], v224 offset:22528
	ds_read_b128 v[204:207], v224 offset:23552
	global_load_lds_dwordx4 v[208:209], off
	v_lshl_add_u64 v[210:211], s[12:13], 0, v[192:193]
	s_mov_b32 m0, s35
	s_addc_u32 s55, s13, 0
	global_load_lds_dwordx4 v[210:211], off
	v_lshl_add_u64 v[212:213], s[54:55], 0, v[196:197]
	s_mov_b32 m0, s40
	v_lshl_add_u64 v[214:215], s[16:17], 0, v[194:195]
	global_load_lds_dwordx4 v[212:213], off
	v_lshl_add_u64 v[212:213], s[54:55], 0, v[192:193]
	s_mov_b32 m0, s41
	s_nop 0
	global_load_lds_dwordx4 v[212:213], off
	v_lshl_add_u64 v[212:213], s[16:17], 0, v[198:199]
	s_mov_b32 m0, s31
	s_nop 0
	global_load_lds_dwordx4 v[212:213], off
	s_mov_b32 m0, s42
	s_nop 0
	global_load_lds_dwordx4 v[214:215], off
	s_waitcnt vmcnt(8)
	s_waitcnt lgkmcnt(0)
	s_barrier
; #define PG8_STAGE(bufoff, gbase, voff) do { _Pragma("unroll") for (int _i = 0; _i < 2; ++_i) \
;         __builtin_amdgcn_global_load_lds((const unsigned*)((const char*)(gbase) + (voff)[_i]), (LAS unsigned*)(lds + (bufoff) + ldsw + _i * 8192), 16, 0, 0); } while (0)
; #define PG8_LDA(dst, b, h) do { _Pragma("unroll") for (int m = 0; m < 4; ++m) _Pragma("unroll") for (int k = 0; k < 2; ++k) dst[m][k] = *(const LAS bf16x8*)(pA + PG8_SA(b, h) + m * 2048 + k * 1024); } while (0)
; #define PG8_LDB(dst, b, h) do { _Pragma("unroll") for (int n = 0; n < 2; ++n) _Pragma("unroll") for (int k = 0; k < 2; ++k) dst[n][k] = *(const LAS bf16x8*)(pB + (PG8_SB(b, h) - 4 * HTB) + n * 2048 + k * 1024); } while (0)
; #define PG8_MMA(ai, bj, At, Bt) do { __builtin_amdgcn_s_setprio(1); _Pragma("unroll") for (int m = 0; m < 4; ++m) _Pragma("unroll") for (int n = 0; n < 2; ++n) _Pragma("unroll") for (int k = 0; k < 2; ++k) \
;         acc[ai][bj][m][n] = __builtin_amdgcn_mfma_f32_16x16x32_bf16(Bt[n][k], At[m][k], acc[ai][bj][m][n], 0, 0, 0); __builtin_amdgcn_s_setprio(0); } while (0)
; #define PG8_WAIT_V(n) asm volatile("s_waitcnt vmcnt(" #n ")" ::: "memory")
; #define PG8_WAIT_L(n) asm volatile("s_waitcnt lgkmcnt(" #n ")" ::: "memory")
; #define PG8_BAR __builtin_amdgcn_s_barrier()
; #define PG8_SCHED __builtin_amdgcn_sched_barrier(0)
; template <class Desc, class Epi, bool ALIGN_EPI>
; __device__ __forceinline__ void gemm_phase(LAS unsigned char* lds, const Desc& D, const Epi& E, int G, int c) {
;     ...
;             PG8_WAIT_V(8); PG8_WAIT_L(0); PG8_BAR; PG8_MMA(1, 0, At, B0); PG8_MMA(1, 1, At, B1); PG8_BAR; PG8_SCHED;
;             PG8_LDB(B0, 1, 0); PG8_LDB(B1, 1, 1); PG8_SCHED; PG8_LDA(At, 1, 0); PG8_STAGE(PG8_SA(0, 1), a2 + hstepA, voffA);
;             PG8_WAIT_V(8); PG8_WAIT_L(0); PG8_BAR; PG8_MMA(0, 0, At, B0); PG8_MMA(0, 1, At, B1); PG8_BAR; PG8_SCHED;
	v_mfma_f32_16x16x32_bf16 v[64:67], v[116:119], v[164:167], v[64:67]
	v_mfma_f32_16x16x32_bf16 v[64:67], v[128:131], v[168:171], v[64:67]
	v_mfma_f32_16x16x32_bf16 v[48:51], v[128:131], v[176:179], v[48:51]
	v_mfma_f32_16x16x32_bf16 v[48:51], v[116:119], v[172:175], v[48:51]
	v_mfma_f32_16x16x32_bf16 v[32:35], v[116:119], v[180:183], v[32:35]
	v_mfma_f32_16x16x32_bf16 v[32:35], v[128:131], v[184:187], v[32:35]
	v_mfma_f32_16x16x32_bf16 v[16:19], v[128:131], v[204:207], v[16:19]
	v_mfma_f32_16x16x32_bf16 v[16:19], v[116:119], v[188:191], v[16:19]
	v_mfma_f32_16x16x32_bf16 v[12:15], v[132:135], v[188:191], v[12:15]
	v_mfma_f32_16x16x32_bf16 v[12:15], v[136:139], v[204:207], v[12:15]
	v_mfma_f32_16x16x32_bf16 v[28:31], v[136:139], v[184:187], v[28:31]
	v_mfma_f32_16x16x32_bf16 v[28:31], v[132:135], v[180:183], v[28:31]
	v_mfma_f32_16x16x32_bf16 v[44:47], v[132:135], v[172:175], v[44:47]
	v_mfma_f32_16x16x32_bf16 v[44:47], v[136:139], v[176:179], v[44:47]
	v_mfma_f32_16x16x32_bf16 v[60:63], v[136:139], v[168:171], v[60:63]
	v_mfma_f32_16x16x32_bf16 v[60:63], v[132:135], v[164:167], v[60:63]
	v_mfma_f32_16x16x32_bf16 v[56:59], v[140:143], v[164:167], v[56:59]
	v_mfma_f32_16x16x32_bf16 v[56:59], v[144:147], v[168:171], v[56:59]
	v_mfma_f32_16x16x32_bf16 v[40:43], v[144:147], v[176:179], v[40:43]
	v_mfma_f32_16x16x32_bf16 v[40:43], v[140:143], v[172:175], v[40:43]
	v_mfma_f32_16x16x32_bf16 v[24:27], v[140:143], v[180:183], v[24:27]
	v_mfma_f32_16x16x32_bf16 v[24:27], v[144:147], v[184:187], v[24:27]
	v_mfma_f32_16x16x32_bf16 v[8:11], v[144:147], v[204:207], v[8:11]
	v_mfma_f32_16x16x32_bf16 v[8:11], v[140:143], v[188:191], v[8:11]
	v_mfma_f32_16x16x32_bf16 v[4:7], v[148:151], v[188:191], v[4:7]
	v_mfma_f32_16x16x32_bf16 v[4:7], v[152:155], v[204:207], v[4:7]
	v_mfma_f32_16x16x32_bf16 v[20:23], v[152:155], v[184:187], v[20:23]
	v_mfma_f32_16x16x32_bf16 v[20:23], v[148:151], v[180:183], v[20:23]
	v_mfma_f32_16x16x32_bf16 v[36:39], v[148:151], v[172:175], v[36:39]
	v_mfma_f32_16x16x32_bf16 v[36:39], v[152:155], v[176:179], v[36:39]
	v_mfma_f32_16x16x32_bf16 v[52:55], v[152:155], v[168:171], v[52:55]
	v_mfma_f32_16x16x32_bf16 v[52:55], v[148:151], v[164:167], v[52:55]
	s_barrier
	ds_read_b128 v[116:119], v225 offset:32768
	ds_read_b128 v[128:131], v225 offset:33792
	ds_read_b128 v[132:135], v225 offset:34816
	ds_read_b128 v[136:139], v225 offset:35840
	ds_read_b128 v[140:143], v225 offset:49152
	ds_read_b128 v[144:147], v225 offset:50176
	ds_read_b128 v[148:151], v225 offset:51200
	ds_read_b128 v[152:155], v225 offset:52224
	s_add_u32 s16, s16, 0x20000
	s_addc_u32 s17, s17, 0
	s_mov_b32 m0, s43
	v_lshl_add_u64 v[216:217], s[16:17], 0, v[198:199]
	ds_read_b128 v[164:167], v224 offset:32768
	ds_read_b128 v[168:171], v224 offset:33792
	ds_read_b128 v[172:175], v224 offset:34816
	ds_read_b128 v[176:179], v224 offset:35840
	ds_read_b128 v[180:183], v224 offset:36864
	ds_read_b128 v[184:187], v224 offset:37888
	ds_read_b128 v[188:191], v224 offset:38912
	ds_read_b128 v[204:207], v224 offset:39936
	global_load_lds_dwordx4 v[216:217], off
	v_lshl_add_u64 v[216:217], s[16:17], 0, v[194:195]
	s_mov_b32 m0, s44
	s_nop 0
	global_load_lds_dwordx4 v[216:217], off
	s_waitcnt vmcnt(8)
	s_waitcnt lgkmcnt(0)
	s_barrier
	v_mfma_f32_16x16x32_bf16 v[160:163], v[116:119], v[164:167], v[160:163]
	v_mfma_f32_16x16x32_bf16 v[160:163], v[128:131], v[168:171], v[160:163]
	v_mfma_f32_16x16x32_bf16 v[112:115], v[128:131], v[176:179], v[112:115]
	v_mfma_f32_16x16x32_bf16 v[112:115], v[116:119], v[172:175], v[112:115]
	v_mfma_f32_16x16x32_bf16 v[96:99], v[116:119], v[180:183], v[96:99]
	v_mfma_f32_16x16x32_bf16 v[96:99], v[128:131], v[184:187], v[96:99]
	v_mfma_f32_16x16x32_bf16 v[80:83], v[128:131], v[204:207], v[80:83]
	v_mfma_f32_16x16x32_bf16 v[80:83], v[116:119], v[188:191], v[80:83]
	v_mfma_f32_16x16x32_bf16 v[76:79], v[132:135], v[188:191], v[76:79]
	v_mfma_f32_16x16x32_bf16 v[76:79], v[136:139], v[204:207], v[76:79]
	v_mfma_f32_16x16x32_bf16 v[92:95], v[136:139], v[184:187], v[92:95]
	v_mfma_f32_16x16x32_bf16 v[92:95], v[132:135], v[180:183], v[92:95]
	v_mfma_f32_16x16x32_bf16 v[108:111], v[132:135], v[172:175], v[108:111]
	v_mfma_f32_16x16x32_bf16 v[108:111], v[136:139], v[176:179], v[108:111]
	v_mfma_f32_16x16x32_bf16 v[156:159], v[136:139], v[168:171], v[156:159]
	v_mfma_f32_16x16x32_bf16 v[156:159], v[132:135], v[164:167], v[156:159]
	v_mfma_f32_16x16x32_bf16 v[124:127], v[140:143], v[164:167], v[124:127]
	v_mfma_f32_16x16x32_bf16 v[124:127], v[144:147], v[168:171], v[124:127]
	v_mfma_f32_16x16x32_bf16 v[104:107], v[144:147], v[176:179], v[104:107]
	v_mfma_f32_16x16x32_bf16 v[104:107], v[140:143], v[172:175], v[104:107]
	v_mfma_f32_16x16x32_bf16 v[88:91], v[140:143], v[180:183], v[88:91]
	v_mfma_f32_16x16x32_bf16 v[88:91], v[144:147], v[184:187], v[88:91]
	v_mfma_f32_16x16x32_bf16 v[72:75], v[144:147], v[204:207], v[72:75]
	v_mfma_f32_16x16x32_bf16 v[72:75], v[140:143], v[188:191], v[72:75]
	v_mfma_f32_16x16x32_bf16 v[68:71], v[148:151], v[188:191], v[68:71]
	v_mfma_f32_16x16x32_bf16 v[68:71], v[152:155], v[204:207], v[68:71]
	v_mfma_f32_16x16x32_bf16 v[84:87], v[152:155], v[184:187], v[84:87]
	v_mfma_f32_16x16x32_bf16 v[84:87], v[148:151], v[180:183], v[84:87]
	v_mfma_f32_16x16x32_bf16 v[100:103], v[148:151], v[172:175], v[100:103]
	v_mfma_f32_16x16x32_bf16 v[100:103], v[152:155], v[176:179], v[100:103]
	v_mfma_f32_16x16x32_bf16 v[120:123], v[152:155], v[168:171], v[120:123]
	v_mfma_f32_16x16x32_bf16 v[120:123], v[148:151], v[164:167], v[120:123]
	s_barrier
; #define PG8_STAGE(bufoff, gbase, voff) do { _Pragma("unroll") for (int _i = 0; _i < 2; ++_i) \
;         __builtin_amdgcn_global_load_lds((const unsigned*)((const char*)(gbase) + (voff)[_i]), (LAS unsigned*)(lds + (bufoff) + ldsw + _i * 8192), 16, 0, 0); } while (0)
; #define PG8_LDA(dst, b, h) do { _Pragma("unroll") for (int m = 0; m < 4; ++m) _Pragma("unroll") for (int k = 0; k < 2; ++k) dst[m][k] = *(const LAS bf16x8*)(pA + PG8_SA(b, h) + m * 2048 + k * 1024); } while (0)
; #define PG8_MMA(ai, bj, At, Bt) do { __builtin_amdgcn_s_setprio(1); _Pragma("unroll") for (int m = 0; m < 4; ++m) _Pragma("unroll") for (int n = 0; n < 2; ++n) _Pragma("unroll") for (int k = 0; k < 2; ++k) \
;         acc[ai][bj][m][n] = __builtin_amdgcn_mfma_f32_16x16x32_bf16(Bt[n][k], At[m][k], acc[ai][bj][m][n], 0, 0, 0); __builtin_amdgcn_s_setprio(0); } while (0)
; #define PG8_WAIT_V(n) asm volatile("s_waitcnt vmcnt(" #n ")" ::: "memory")
; #define PG8_WAIT_L(n) asm volatile("s_waitcnt lgkmcnt(" #n ")" ::: "memory")
; #define PG8_BAR __builtin_amdgcn_s_barrier()
; #define PG8_SCHED __builtin_amdgcn_sched_barrier(0)
; template <class Desc, class Epi, bool ALIGN_EPI>
; __device__ __forceinline__ void gemm_phase(LAS unsigned char* lds, const Desc& D, const Epi& E, int G, int c) {
;     ...
;             PG8_LDA(At, 1, 1); PG8_STAGE(PG8_SB(1, 0), b3, voffB); PG8_STAGE(PG8_SB(1, 1), b3 + hstepB, voffB); PG8_STAGE(PG8_SA(1, 0), a3, voffA);
;             PG8_WAIT_V(8); PG8_WAIT_L(0); PG8_BAR; PG8_MMA(1, 0, At, B0); PG8_MMA(1, 1, At, B1); PG8_BAR; PG8_SCHED;
;         }
;         if constexpr (ALIGN_EPI) { if (wr == 0) PG8_BAR; }
	s_mov_b32 m0, s45
	v_lshl_add_u64 v[208:209], v[208:209], 0, s[76:77]
	s_add_u32 s12, s12, 0x20080
	ds_read_b128 v[164:167], v224 offset:49152
	ds_read_b128 v[168:171], v224 offset:50176
	ds_read_b128 v[172:175], v224 offset:51200
	ds_read_b128 v[176:179], v224 offset:52224
	ds_read_b128 v[180:183], v224 offset:53248
	ds_read_b128 v[184:187], v224 offset:54272
	ds_read_b128 v[188:191], v224 offset:55296
	ds_read_b128 v[204:207], v224 offset:56320
	global_load_lds_dwordx4 v[208:209], off
	v_lshl_add_u64 v[208:209], v[210:211], 0, s[76:77]
	s_mov_b32 m0, s46
	s_addc_u32 s13, s13, 0
	global_load_lds_dwordx4 v[208:209], off
	v_lshl_add_u64 v[208:209], s[12:13], 0, v[196:197]
	s_mov_b32 m0, s49
	s_nop 0
	global_load_lds_dwordx4 v[208:209], off
	v_lshl_add_u64 v[208:209], s[12:13], 0, v[192:193]
	s_mov_b32 m0, s50
	s_nop 0
	global_load_lds_dwordx4 v[208:209], off
	v_lshl_add_u64 v[208:209], v[212:213], 0, s[76:77]
	s_mov_b32 m0, s47
	s_nop 0
	global_load_lds_dwordx4 v[208:209], off
	v_lshl_add_u64 v[208:209], v[214:215], 0, s[76:77]
	s_mov_b32 m0, s48
	s_nop 0
	global_load_lds_dwordx4 v[208:209], off
	s_waitcnt vmcnt(8)
	s_waitcnt lgkmcnt(0)
	s_barrier
	v_mfma_f32_16x16x32_bf16 v[64:67], v[116:119], v[164:167], v[64:67]
	v_mfma_f32_16x16x32_bf16 v[64:67], v[128:131], v[168:171], v[64:67]
	v_mfma_f32_16x16x32_bf16 v[48:51], v[128:131], v[176:179], v[48:51]
	v_mfma_f32_16x16x32_bf16 v[48:51], v[116:119], v[172:175], v[48:51]
	v_mfma_f32_16x16x32_bf16 v[32:35], v[116:119], v[180:183], v[32:35]
	v_mfma_f32_16x16x32_bf16 v[32:35], v[128:131], v[184:187], v[32:35]
	v_mfma_f32_16x16x32_bf16 v[16:19], v[128:131], v[204:207], v[16:19]
	v_mfma_f32_16x16x32_bf16 v[16:19], v[116:119], v[188:191], v[16:19]
	v_mfma_f32_16x16x32_bf16 v[12:15], v[132:135], v[188:191], v[12:15]
	v_mfma_f32_16x16x32_bf16 v[12:15], v[136:139], v[204:207], v[12:15]
	v_mfma_f32_16x16x32_bf16 v[28:31], v[136:139], v[184:187], v[28:31]
	v_mfma_f32_16x16x32_bf16 v[28:31], v[132:135], v[180:183], v[28:31]
	v_mfma_f32_16x16x32_bf16 v[44:47], v[132:135], v[172:175], v[44:47]
	v_mfma_f32_16x16x32_bf16 v[44:47], v[136:139], v[176:179], v[44:47]
	v_mfma_f32_16x16x32_bf16 v[60:63], v[136:139], v[168:171], v[60:63]
	v_mfma_f32_16x16x32_bf16 v[60:63], v[132:135], v[164:167], v[60:63]
	v_mfma_f32_16x16x32_bf16 v[56:59], v[140:143], v[164:167], v[56:59]
	v_mfma_f32_16x16x32_bf16 v[56:59], v[144:147], v[168:171], v[56:59]
	v_mfma_f32_16x16x32_bf16 v[40:43], v[144:147], v[176:179], v[40:43]
	v_mfma_f32_16x16x32_bf16 v[40:43], v[140:143], v[172:175], v[40:43]
	v_mfma_f32_16x16x32_bf16 v[24:27], v[140:143], v[180:183], v[24:27]
	v_mfma_f32_16x16x32_bf16 v[24:27], v[144:147], v[184:187], v[24:27]
	v_mfma_f32_16x16x32_bf16 v[8:11], v[144:147], v[204:207], v[8:11]
	v_mfma_f32_16x16x32_bf16 v[8:11], v[140:143], v[188:191], v[8:11]
	v_mfma_f32_16x16x32_bf16 v[4:7], v[148:151], v[188:191], v[4:7]
	v_mfma_f32_16x16x32_bf16 v[4:7], v[152:155], v[204:207], v[4:7]
	v_mfma_f32_16x16x32_bf16 v[20:23], v[152:155], v[184:187], v[20:23]
	v_mfma_f32_16x16x32_bf16 v[20:23], v[148:151], v[180:183], v[20:23]
	v_mfma_f32_16x16x32_bf16 v[36:39], v[148:151], v[172:175], v[36:39]
	v_mfma_f32_16x16x32_bf16 v[36:39], v[152:155], v[176:179], v[36:39]
	v_mfma_f32_16x16x32_bf16 v[52:55], v[152:155], v[168:171], v[52:55]
	v_mfma_f32_16x16x32_bf16 v[52:55], v[148:151], v[164:167], v[52:55]
	s_barrier
	s_add_i32 s52, s52, 2
	s_add_u32 s0, s0, 0x100
	s_addc_u32 s1, s1, 0
	s_add_u32 s27, s27, 0x100
	s_addc_u32 s33, s33, 0
	s_cmp_gt_u32 s52, 5
	s_cbranch_scc0 .LBB0_1479
	s_and_b64 vcc, exec, s[8:9]
	s_cbranch_vccz .LBB0_1482
	s_barrier

;     __device__ __forceinline__ int nt(const Unit& u) const { return (u.pn >> 1) < 2 ? 22 : 20; }
; #define PG8_STAGE(bufoff, gbase, voff) do { _Pragma("unroll") for (int _i = 0; _i < 2; ++_i) \
;         __builtin_amdgcn_global_load_lds((const unsigned*)((const char*)(gbase) + (voff)[_i]), (LAS unsigned*)(lds + (bufoff) + ldsw + _i * 8192), 16, 0, 0); } while (0)
; #define PG8_LDA(dst, b, h) do { _Pragma("unroll") for (int m = 0; m < 4; ++m) _Pragma("unroll") for (int k = 0; k < 2; ++k) dst[m][k] = *(const LAS bf16x8*)(pA + PG8_SA(b, h) + m * 2048 + k * 1024); } while (0)
; #define PG8_LDB(dst, b, h) do { _Pragma("unroll") for (int n = 0; n < 2; ++n) _Pragma("unroll") for (int k = 0; k < 2; ++k) dst[n][k] = *(const LAS bf16x8*)(pB + (PG8_SB(b, h) - 4 * HTB) + n * 2048 + k * 1024); } while (0)
; #define PG8_MMA(ai, bj, At, Bt) do { __builtin_amdgcn_s_setprio(1); _Pragma("unroll") for (int m = 0; m < 4; ++m) _Pragma("unroll") for (int n = 0; n < 2; ++n) _Pragma("unroll") for (int k = 0; k < 2; ++k) \
;         acc[ai][bj][m][n] = __builtin_amdgcn_mfma_f32_16x16x32_bf16(Bt[n][k], At[m][k], acc[ai][bj][m][n], 0, 0, 0); __builtin_amdgcn_s_setprio(0); } while (0)
; #define PG8_WAIT_V(n) asm volatile("s_waitcnt vmcnt(" #n ")" ::: "memory")
; #define PG8_BAR __builtin_amdgcn_s_barrier()
; template <class Desc, class Epi, bool ALIGN_EPI>
; __device__ __forceinline__ void gemm_phase(LAS unsigned char* lds, const Desc& D, const Epi& E, int G, int c) {
;     ...
;         for (int t = 0; t < nt; t += 2) {
;             const bool last = (t == nt - 2);
;             if (last && has_next) PG8_AWAIT(nxt);
;             const char* a1 = cA + (size_t)(t + 1) * kstep;
;             const char* a2 = last ? nA : cA + (size_t)(t + 2) * kstep; const char* b2 = last ? nB : cB + (size_t)(t + 2) * kstep;
;             const char* a3 = a2 + kstep; const char* b3 = b2 + kstep;
;             PG8_LDB(B0, 0, 0); PG8_LDB(B1, 0, 1); PG8_SCHED; PG8_LDA(At, 0, 0); PG8_STAGE(PG8_SA(1, 1), a1 + hstepA, voffA);
;             PG8_WAIT_V(8); PG8_WAIT_L(0); PG8_BAR; PG8_MMA(0, 0, At, B0); PG8_MMA(0, 1, At, B1); PG8_BAR; PG8_SCHED;
;             PG8_LDA(At, 0, 1); PG8_STAGE(PG8_SB(0, 0), b2, voffB); PG8_STAGE(PG8_SB(0, 1), b2 + hstepB, voffB); PG8_STAGE(PG8_SA(0, 0), a2, voffA);
;             PG8_WAIT_V(8); PG8_WAIT_L(0); PG8_BAR; PG8_MMA(1, 0, At, B0); PG8_MMA(1, 1, At, B1); PG8_BAR; PG8_SCHED;
.LBB0_1517:
	ds_read_b128 v[116:119], v225
	ds_read_b128 v[128:131], v225 offset:1024
	ds_read_b128 v[132:135], v225 offset:2048
	ds_read_b128 v[136:139], v225 offset:3072
	ds_read_b128 v[140:143], v225 offset:16384
	ds_read_b128 v[144:147], v225 offset:17408
	ds_read_b128 v[148:151], v225 offset:18432
	ds_read_b128 v[152:155], v225 offset:19456
	s_add_u32 s12, s0, 0xfffe0080
	s_addc_u32 s13, s1, -1
	s_cmp_eq_u32 s54, 4
	s_cselect_b32 s17, s37, s13
	s_cselect_b32 s16, s36, s12
	s_cselect_b32 s13, s21, s33
	s_cselect_b32 s12, s24, s27
	v_lshl_add_u64 v[208:209], s[0:1], 0, v[200:201]
	s_add_i32 m0, s31, 0xc000
	ds_read_b128 v[164:167], v224
	ds_read_b128 v[168:171], v224 offset:1024
	ds_read_b128 v[172:175], v224 offset:2048
	ds_read_b128 v[176:179], v224 offset:3072
	ds_read_b128 v[180:183], v224 offset:4096
	ds_read_b128 v[184:187], v224 offset:5120
	ds_read_b128 v[188:191], v224 offset:6144
	ds_read_b128 v[204:207], v224 offset:7168
	global_load_lds_dwordx4 v[208:209], off
	v_lshl_add_u64 v[208:209], s[0:1], 0, v[202:203]
	s_add_i32 m0, s31, 0xe000
	s_nop 0
	global_load_lds_dwordx4 v[208:209], off
	s_waitcnt vmcnt(8)
	s_waitcnt lgkmcnt(0)
	s_barrier
	v_mfma_f32_16x16x32_bf16 v[160:163], v[116:119], v[164:167], v[160:163]
	v_mfma_f32_16x16x32_bf16 v[160:163], v[128:131], v[168:171], v[160:163]
	v_mfma_f32_16x16x32_bf16 v[112:115], v[128:131], v[176:179], v[112:115]
	v_mfma_f32_16x16x32_bf16 v[112:115], v[116:119], v[172:175], v[112:115]
	v_mfma_f32_16x16x32_bf16 v[96:99], v[116:119], v[180:183], v[96:99]
	v_mfma_f32_16x16x32_bf16 v[96:99], v[128:131], v[184:187], v[96:99]
	v_mfma_f32_16x16x32_bf16 v[80:83], v[128:131], v[204:207], v[80:83]
	v_mfma_f32_16x16x32_bf16 v[80:83], v[116:119], v[188:191], v[80:83]
	v_mfma_f32_16x16x32_bf16 v[76:79], v[132:135], v[188:191], v[76:79]
	v_mfma_f32_16x16x32_bf16 v[76:79], v[136:139], v[204:207], v[76:79]
	v_mfma_f32_16x16x32_bf16 v[92:95], v[136:139], v[184:187], v[92:95]
	v_mfma_f32_16x16x32_bf16 v[92:95], v[132:135], v[180:183], v[92:95]
	v_mfma_f32_16x16x32_bf16 v[108:111], v[132:135], v[172:175], v[108:111]
	v_mfma_f32_16x16x32_bf16 v[108:111], v[136:139], v[176:179], v[108:111]
	v_mfma_f32_16x16x32_bf16 v[156:159], v[136:139], v[168:171], v[156:159]
	v_mfma_f32_16x16x32_bf16 v[156:159], v[132:135], v[164:167], v[156:159]
	v_mfma_f32_16x16x32_bf16 v[124:127], v[140:143], v[164:167], v[124:127]
	v_mfma_f32_16x16x32_bf16 v[124:127], v[144:147], v[168:171], v[124:127]
	v_mfma_f32_16x16x32_bf16 v[104:107], v[144:147], v[176:179], v[104:107]
	v_mfma_f32_16x16x32_bf16 v[104:107], v[140:143], v[172:175], v[104:107]
	v_mfma_f32_16x16x32_bf16 v[88:91], v[140:143], v[180:183], v[88:91]
	v_mfma_f32_16x16x32_bf16 v[88:91], v[144:147], v[184:187], v[88:91]
	v_mfma_f32_16x16x32_bf16 v[72:75], v[144:147], v[204:207], v[72:75]
	v_mfma_f32_16x16x32_bf16 v[72:75], v[140:143], v[188:191], v[72:75]
	v_mfma_f32_16x16x32_bf16 v[68:71], v[148:151], v[188:191], v[68:71]
	v_mfma_f32_16x16x32_bf16 v[68:71], v[152:155], v[204:207], v[68:71]
	v_mfma_f32_16x16x32_bf16 v[84:87], v[152:155], v[184:187], v[84:87]
	v_mfma_f32_16x16x32_bf16 v[84:87], v[148:151], v[180:183], v[84:87]
	v_mfma_f32_16x16x32_bf16 v[100:103], v[148:151], v[172:175], v[100:103]
	v_mfma_f32_16x16x32_bf16 v[100:103], v[152:155], v[176:179], v[100:103]
	v_mfma_f32_16x16x32_bf16 v[120:123], v[152:155], v[168:171], v[120:123]
	v_mfma_f32_16x16x32_bf16 v[120:123], v[148:151], v[164:167], v[120:123]
	s_barrier
	s_mov_b32 m0, s34
	v_lshl_add_u64 v[208:209], s[12:13], 0, v[196:197]
	s_add_u32 s56, s12, 0x20000
	ds_read_b128 v[164:167], v224 offset:16384
	ds_read_b128 v[168:171], v224 offset:17408
	ds_read_b128 v[172:175], v224 offset:18432
	ds_read_b128 v[176:179], v224 offset:19456
	ds_read_b128 v[180:183], v224 offset:20480
	ds_read_b128 v[184:187], v224 offset:21504
	ds_read_b128 v[188:191], v224 offset:22528
	ds_read_b128 v[204:207], v224 offset:23552
	global_load_lds_dwordx4 v[208:209], off
	v_lshl_add_u64 v[210:211], s[12:13], 0, v[192:193]
	s_mov_b32 m0, s35
	s_addc_u32 s57, s13, 0
	global_load_lds_dwordx4 v[210:211], off
	v_lshl_add_u64 v[212:213], s[56:57], 0, v[196:197]
	s_mov_b32 m0, s42
	v_lshl_add_u64 v[214:215], s[16:17], 0, v[194:195]
	global_load_lds_dwordx4 v[212:213], off
	v_lshl_add_u64 v[212:213], s[56:57], 0, v[192:193]
	s_mov_b32 m0, s43
	s_nop 0
	global_load_lds_dwordx4 v[212:213], off
	v_lshl_add_u64 v[212:213], s[16:17], 0, v[198:199]
	s_mov_b32 m0, s31
	s_nop 0
	global_load_lds_dwordx4 v[212:213], off
	s_mov_b32 m0, s44
	s_nop 0
	global_load_lds_dwordx4 v[214:215], off
	s_waitcnt vmcnt(8)
	s_waitcnt lgkmcnt(0)
	s_barrier
; #define PG8_STAGE(bufoff, gbase, voff) do { _Pragma("unroll") for (int _i = 0; _i < 2; ++_i) \
;         __builtin_amdgcn_global_load_lds((const unsigned*)((const char*)(gbase) + (voff)[_i]), (LAS unsigned*)(lds + (bufoff) + ldsw + _i * 8192), 16, 0, 0); } while (0)
; #define PG8_LDA(dst, b, h) do { _Pragma("unroll") for (int m = 0; m < 4; ++m) _Pragma("unroll") for (int k = 0; k < 2; ++k) dst[m][k] = *(const LAS bf16x8*)(pA + PG8_SA(b, h) + m * 2048 + k * 1024); } while (0)
; #define PG8_LDB(dst, b, h) do { _Pragma("unroll") for (int n = 0; n < 2; ++n) _Pragma("unroll") for (int k = 0; k < 2; ++k) dst[n][k] = *(const LAS bf16x8*)(pB + (PG8_SB(b, h) - 4 * HTB) + n * 2048 + k * 1024); } while (0)
; #define PG8_MMA(ai, bj, At, Bt) do { __builtin_amdgcn_s_setprio(1); _Pragma("unroll") for (int m = 0; m < 4; ++m) _Pragma("unroll") for (int n = 0; n < 2; ++n) _Pragma("unroll") for (int k = 0; k < 2; ++k) \
;         acc[ai][bj][m][n] = __builtin_amdgcn_mfma_f32_16x16x32_bf16(Bt[n][k], At[m][k], acc[ai][bj][m][n], 0, 0, 0); __builtin_amdgcn_s_setprio(0); } while (0)
; #define PG8_WAIT_V(n) asm volatile("s_waitcnt vmcnt(" #n ")" ::: "memory")
; #define PG8_WAIT_L(n) asm volatile("s_waitcnt lgkmcnt(" #n ")" ::: "memory")
; #define PG8_BAR __builtin_amdgcn_s_barrier()
; #define PG8_SCHED __builtin_amdgcn_sched_barrier(0)
; template <class Desc, class Epi, bool ALIGN_EPI>
; __device__ __forceinline__ void gemm_phase(LAS unsigned char* lds, const Desc& D, const Epi& E, int G, int c) {
;     ...
;             PG8_WAIT_V(8); PG8_WAIT_L(0); PG8_BAR; PG8_MMA(1, 0, At, B0); PG8_MMA(1, 1, At, B1); PG8_BAR; PG8_SCHED;
;             PG8_LDB(B0, 1, 0); PG8_LDB(B1, 1, 1); PG8_SCHED; PG8_LDA(At, 1, 0); PG8_STAGE(PG8_SA(0, 1), a2 + hstepA, voffA);
;             PG8_WAIT_V(8); PG8_WAIT_L(0); PG8_BAR; PG8_MMA(0, 0, At, B0); PG8_MMA(0, 1, At, B1); PG8_BAR; PG8_SCHED;
	v_mfma_f32_16x16x32_bf16 v[64:67], v[116:119], v[164:167], v[64:67]
	v_mfma_f32_16x16x32_bf16 v[64:67], v[128:131], v[168:171], v[64:67]
	v_mfma_f32_16x16x32_bf16 v[48:51], v[128:131], v[176:179], v[48:51]
	v_mfma_f32_16x16x32_bf16 v[48:51], v[116:119], v[172:175], v[48:51]
	v_mfma_f32_16x16x32_bf16 v[32:35], v[116:119], v[180:183], v[32:35]
	v_mfma_f32_16x16x32_bf16 v[32:35], v[128:131], v[184:187], v[32:35]
	v_mfma_f32_16x16x32_bf16 v[16:19], v[128:131], v[204:207], v[16:19]
	v_mfma_f32_16x16x32_bf16 v[16:19], v[116:119], v[188:191], v[16:19]
	v_mfma_f32_16x16x32_bf16 v[12:15], v[132:135], v[188:191], v[12:15]
	v_mfma_f32_16x16x32_bf16 v[12:15], v[136:139], v[204:207], v[12:15]
	v_mfma_f32_16x16x32_bf16 v[28:31], v[136:139], v[184:187], v[28:31]
	v_mfma_f32_16x16x32_bf16 v[28:31], v[132:135], v[180:183], v[28:31]
	v_mfma_f32_16x16x32_bf16 v[44:47], v[132:135], v[172:175], v[44:47]
	v_mfma_f32_16x16x32_bf16 v[44:47], v[136:139], v[176:179], v[44:47]
	v_mfma_f32_16x16x32_bf16 v[60:63], v[136:139], v[168:171], v[60:63]
	v_mfma_f32_16x16x32_bf16 v[60:63], v[132:135], v[164:167], v[60:63]
	v_mfma_f32_16x16x32_bf16 v[56:59], v[140:143], v[164:167], v[56:59]
	v_mfma_f32_16x16x32_bf16 v[56:59], v[144:147], v[168:171], v[56:59]
	v_mfma_f32_16x16x32_bf16 v[40:43], v[144:147], v[176:179], v[40:43]
	v_mfma_f32_16x16x32_bf16 v[40:43], v[140:143], v[172:175], v[40:43]
	v_mfma_f32_16x16x32_bf16 v[24:27], v[140:143], v[180:183], v[24:27]
	v_mfma_f32_16x16x32_bf16 v[24:27], v[144:147], v[184:187], v[24:27]
	v_mfma_f32_16x16x32_bf16 v[8:11], v[144:147], v[204:207], v[8:11]
	v_mfma_f32_16x16x32_bf16 v[8:11], v[140:143], v[188:191], v[8:11]
	v_mfma_f32_16x16x32_bf16 v[4:7], v[148:151], v[188:191], v[4:7]
	v_mfma_f32_16x16x32_bf16 v[4:7], v[152:155], v[204:207], v[4:7]
	v_mfma_f32_16x16x32_bf16 v[20:23], v[152:155], v[184:187], v[20:23]
	v_mfma_f32_16x16x32_bf16 v[20:23], v[148:151], v[180:183], v[20:23]
	v_mfma_f32_16x16x32_bf16 v[36:39], v[148:151], v[172:175], v[36:39]
	v_mfma_f32_16x16x32_bf16 v[36:39], v[152:155], v[176:179], v[36:39]
	v_mfma_f32_16x16x32_bf16 v[52:55], v[152:155], v[168:171], v[52:55]
	v_mfma_f32_16x16x32_bf16 v[52:55], v[148:151], v[164:167], v[52:55]
	s_barrier
	ds_read_b128 v[116:119], v225 offset:32768
	ds_read_b128 v[128:131], v225 offset:33792
	ds_read_b128 v[132:135], v225 offset:34816
	ds_read_b128 v[136:139], v225 offset:35840
	ds_read_b128 v[140:143], v225 offset:49152
	ds_read_b128 v[144:147], v225 offset:50176
	ds_read_b128 v[148:151], v225 offset:51200
	ds_read_b128 v[152:155], v225 offset:52224
	s_add_u32 s16, s16, 0x20000
	s_addc_u32 s17, s17, 0
	s_mov_b32 m0, s45
	v_lshl_add_u64 v[216:217], s[16:17], 0, v[198:199]
	ds_read_b128 v[164:167], v224 offset:32768
	ds_read_b128 v[168:171], v224 offset:33792
	ds_read_b128 v[172:175], v224 offset:34816
	ds_read_b128 v[176:179], v224 offset:35840
	ds_read_b128 v[180:183], v224 offset:36864
	ds_read_b128 v[184:187], v224 offset:37888
	ds_read_b128 v[188:191], v224 offset:38912
	ds_read_b128 v[204:207], v224 offset:39936
	global_load_lds_dwordx4 v[216:217], off
	v_lshl_add_u64 v[216:217], s[16:17], 0, v[194:195]
	s_mov_b32 m0, s46
	s_nop 0
	global_load_lds_dwordx4 v[216:217], off
	s_waitcnt vmcnt(8)
	s_waitcnt lgkmcnt(0)
	s_barrier
	v_mfma_f32_16x16x32_bf16 v[160:163], v[116:119], v[164:167], v[160:163]
	v_mfma_f32_16x16x32_bf16 v[160:163], v[128:131], v[168:171], v[160:163]
	v_mfma_f32_16x16x32_bf16 v[112:115], v[128:131], v[176:179], v[112:115]
	v_mfma_f32_16x16x32_bf16 v[112:115], v[116:119], v[172:175], v[112:115]
	v_mfma_f32_16x16x32_bf16 v[96:99], v[116:119], v[180:183], v[96:99]
	v_mfma_f32_16x16x32_bf16 v[96:99], v[128:131], v[184:187], v[96:99]
	v_mfma_f32_16x16x32_bf16 v[80:83], v[128:131], v[204:207], v[80:83]
	v_mfma_f32_16x16x32_bf16 v[80:83], v[116:119], v[188:191], v[80:83]
	v_mfma_f32_16x16x32_bf16 v[76:79], v[132:135], v[188:191], v[76:79]
	v_mfma_f32_16x16x32_bf16 v[76:79], v[136:139], v[204:207], v[76:79]
	v_mfma_f32_16x16x32_bf16 v[92:95], v[136:139], v[184:187], v[92:95]
	v_mfma_f32_16x16x32_bf16 v[92:95], v[132:135], v[180:183], v[92:95]
	v_mfma_f32_16x16x32_bf16 v[108:111], v[132:135], v[172:175], v[108:111]
	v_mfma_f32_16x16x32_bf16 v[108:111], v[136:139], v[176:179], v[108:111]
	v_mfma_f32_16x16x32_bf16 v[156:159], v[136:139], v[168:171], v[156:159]
	v_mfma_f32_16x16x32_bf16 v[156:159], v[132:135], v[164:167], v[156:159]
	v_mfma_f32_16x16x32_bf16 v[124:127], v[140:143], v[164:167], v[124:127]
	v_mfma_f32_16x16x32_bf16 v[124:127], v[144:147], v[168:171], v[124:127]
	v_mfma_f32_16x16x32_bf16 v[104:107], v[144:147], v[176:179], v[104:107]
	v_mfma_f32_16x16x32_bf16 v[104:107], v[140:143], v[172:175], v[104:107]
	v_mfma_f32_16x16x32_bf16 v[88:91], v[140:143], v[180:183], v[88:91]
	v_mfma_f32_16x16x32_bf16 v[88:91], v[144:147], v[184:187], v[88:91]
	v_mfma_f32_16x16x32_bf16 v[72:75], v[144:147], v[204:207], v[72:75]
	v_mfma_f32_16x16x32_bf16 v[72:75], v[140:143], v[188:191], v[72:75]
	v_mfma_f32_16x16x32_bf16 v[68:71], v[148:151], v[188:191], v[68:71]
	v_mfma_f32_16x16x32_bf16 v[68:71], v[152:155], v[204:207], v[68:71]
	v_mfma_f32_16x16x32_bf16 v[84:87], v[152:155], v[184:187], v[84:87]
	v_mfma_f32_16x16x32_bf16 v[84:87], v[148:151], v[180:183], v[84:87]
	v_mfma_f32_16x16x32_bf16 v[100:103], v[148:151], v[172:175], v[100:103]
	v_mfma_f32_16x16x32_bf16 v[100:103], v[152:155], v[176:179], v[100:103]
	v_mfma_f32_16x16x32_bf16 v[120:123], v[152:155], v[168:171], v[120:123]
	v_mfma_f32_16x16x32_bf16 v[120:123], v[148:151], v[164:167], v[120:123]
	s_barrier
; #define PG8_STAGE(bufoff, gbase, voff) do { _Pragma("unroll") for (int _i = 0; _i < 2; ++_i) \
;         __builtin_amdgcn_global_load_lds((const unsigned*)((const char*)(gbase) + (voff)[_i]), (LAS unsigned*)(lds + (bufoff) + ldsw + _i * 8192), 16, 0, 0); } while (0)
; #define PG8_LDA(dst, b, h) do { _Pragma("unroll") for (int m = 0; m < 4; ++m) _Pragma("unroll") for (int k = 0; k < 2; ++k) dst[m][k] = *(const LAS bf16x8*)(pA + PG8_SA(b, h) + m * 2048 + k * 1024); } while (0)
; #define PG8_MMA(ai, bj, At, Bt) do { __builtin_amdgcn_s_setprio(1); _Pragma("unroll") for (int m = 0; m < 4; ++m) _Pragma("unroll") for (int n = 0; n < 2; ++n) _Pragma("unroll") for (int k = 0; k < 2; ++k) \
;         acc[ai][bj][m][n] = __builtin_amdgcn_mfma_f32_16x16x32_bf16(Bt[n][k], At[m][k], acc[ai][bj][m][n], 0, 0, 0); __builtin_amdgcn_s_setprio(0); } while (0)
; #define PG8_WAIT_V(n) asm volatile("s_waitcnt vmcnt(" #n ")" ::: "memory")
; #define PG8_WAIT_L(n) asm volatile("s_waitcnt lgkmcnt(" #n ")" ::: "memory")
; #define PG8_BAR __builtin_amdgcn_s_barrier()
; #define PG8_SCHED __builtin_amdgcn_sched_barrier(0)
; template <class Desc, class Epi, bool ALIGN_EPI>
; __device__ __forceinline__ void gemm_phase(LAS unsigned char* lds, const Desc& D, const Epi& E, int G, int c) {
;     ...
;             PG8_LDA(At, 1, 1); PG8_STAGE(PG8_SB(1, 0), b3, voffB); PG8_STAGE(PG8_SB(1, 1), b3 + hstepB, voffB); PG8_STAGE(PG8_SA(1, 0), a3, voffA);
;             PG8_WAIT_V(8); PG8_WAIT_L(0); PG8_BAR; PG8_MMA(1, 0, At, B0); PG8_MMA(1, 1, At, B1); PG8_BAR; PG8_SCHED;
;         }
;         if constexpr (ALIGN_EPI) { if (wr == 0) PG8_BAR; }
	s_mov_b32 m0, s47
	v_lshl_add_u64 v[208:209], v[208:209], 0, s[76:77]
	s_add_u32 s12, s12, 0x20080
	ds_read_b128 v[164:167], v224 offset:49152
	ds_read_b128 v[168:171], v224 offset:50176
	ds_read_b128 v[172:175], v224 offset:51200
	ds_read_b128 v[176:179], v224 offset:52224
	ds_read_b128 v[180:183], v224 offset:53248
	ds_read_b128 v[184:187], v224 offset:54272
	ds_read_b128 v[188:191], v224 offset:55296
	ds_read_b128 v[204:207], v224 offset:56320
	global_load_lds_dwordx4 v[208:209], off
	v_lshl_add_u64 v[208:209], v[210:211], 0, s[76:77]
	s_mov_b32 m0, s48
	s_addc_u32 s13, s13, 0
	global_load_lds_dwordx4 v[208:209], off
	v_lshl_add_u64 v[208:209], s[12:13], 0, v[196:197]
	s_mov_b32 m0, s51
	s_nop 0
	global_load_lds_dwordx4 v[208:209], off
	v_lshl_add_u64 v[208:209], s[12:13], 0, v[192:193]
	s_mov_b32 m0, s52
	s_nop 0
	global_load_lds_dwordx4 v[208:209], off
	v_lshl_add_u64 v[208:209], v[212:213], 0, s[76:77]
	s_mov_b32 m0, s49
	s_nop 0
	global_load_lds_dwordx4 v[208:209], off
	v_lshl_add_u64 v[208:209], v[214:215], 0, s[76:77]
	s_mov_b32 m0, s50
	s_nop 0
	global_load_lds_dwordx4 v[208:209], off
	s_waitcnt vmcnt(8)
	s_waitcnt lgkmcnt(0)
	s_barrier
	v_mfma_f32_16x16x32_bf16 v[64:67], v[116:119], v[164:167], v[64:67]
	v_mfma_f32_16x16x32_bf16 v[64:67], v[128:131], v[168:171], v[64:67]
	v_mfma_f32_16x16x32_bf16 v[48:51], v[128:131], v[176:179], v[48:51]
	v_mfma_f32_16x16x32_bf16 v[48:51], v[116:119], v[172:175], v[48:51]
	v_mfma_f32_16x16x32_bf16 v[32:35], v[116:119], v[180:183], v[32:35]
	v_mfma_f32_16x16x32_bf16 v[32:35], v[128:131], v[184:187], v[32:35]
	v_mfma_f32_16x16x32_bf16 v[16:19], v[128:131], v[204:207], v[16:19]
	v_mfma_f32_16x16x32_bf16 v[16:19], v[116:119], v[188:191], v[16:19]
	v_mfma_f32_16x16x32_bf16 v[12:15], v[132:135], v[188:191], v[12:15]
	v_mfma_f32_16x16x32_bf16 v[12:15], v[136:139], v[204:207], v[12:15]
	v_mfma_f32_16x16x32_bf16 v[28:31], v[136:139], v[184:187], v[28:31]
	v_mfma_f32_16x16x32_bf16 v[28:31], v[132:135], v[180:183], v[28:31]
	v_mfma_f32_16x16x32_bf16 v[44:47], v[132:135], v[172:175], v[44:47]
	v_mfma_f32_16x16x32_bf16 v[44:47], v[136:139], v[176:179], v[44:47]
	v_mfma_f32_16x16x32_bf16 v[60:63], v[136:139], v[168:171], v[60:63]
	v_mfma_f32_16x16x32_bf16 v[60:63], v[132:135], v[164:167], v[60:63]
	v_mfma_f32_16x16x32_bf16 v[56:59], v[140:143], v[164:167], v[56:59]
	v_mfma_f32_16x16x32_bf16 v[56:59], v[144:147], v[168:171], v[56:59]
	v_mfma_f32_16x16x32_bf16 v[40:43], v[144:147], v[176:179], v[40:43]
	v_mfma_f32_16x16x32_bf16 v[40:43], v[140:143], v[172:175], v[40:43]
	v_mfma_f32_16x16x32_bf16 v[24:27], v[140:143], v[180:183], v[24:27]
	v_mfma_f32_16x16x32_bf16 v[24:27], v[144:147], v[184:187], v[24:27]
	v_mfma_f32_16x16x32_bf16 v[8:11], v[144:147], v[204:207], v[8:11]
	v_mfma_f32_16x16x32_bf16 v[8:11], v[140:143], v[188:191], v[8:11]
	v_mfma_f32_16x16x32_bf16 v[4:7], v[148:151], v[188:191], v[4:7]
	v_mfma_f32_16x16x32_bf16 v[4:7], v[152:155], v[204:207], v[4:7]
	v_mfma_f32_16x16x32_bf16 v[20:23], v[152:155], v[184:187], v[20:23]
	v_mfma_f32_16x16x32_bf16 v[20:23], v[148:151], v[180:183], v[20:23]
	v_mfma_f32_16x16x32_bf16 v[36:39], v[148:151], v[172:175], v[36:39]
	v_mfma_f32_16x16x32_bf16 v[36:39], v[152:155], v[176:179], v[36:39]
	v_mfma_f32_16x16x32_bf16 v[52:55], v[152:155], v[168:171], v[52:55]
	v_mfma_f32_16x16x32_bf16 v[52:55], v[148:151], v[164:167], v[52:55]
	s_barrier
	s_add_i32 s54, s54, 2
	s_add_u32 s0, s0, 0x100
	s_addc_u32 s1, s1, 0
	s_add_u32 s27, s27, 0x100
	s_addc_u32 s33, s33, 0
	s_cmp_gt_u32 s54, 5
	s_cbranch_scc0 .LBB0_1517
	s_and_b64 vcc, exec, s[10:11]
	s_cbranch_vccz .LBB0_1520
	s_barrier

;     __device__ __forceinline__ int nt(const Unit& u) const { return (u.pn >> 1) < 2 ? 22 : 20; }
; #define PG8_STAGE(bufoff, gbase, voff) do { _Pragma("unroll") for (int _i = 0; _i < 2; ++_i) \
;         __builtin_amdgcn_global_load_lds((const unsigned*)((const char*)(gbase) + (voff)[_i]), (LAS unsigned*)(lds + (bufoff) + ldsw + _i * 8192), 16, 0, 0); } while (0)
; #define PG8_LDA(dst, b, h) do { _Pragma("unroll") for (int m = 0; m < 4; ++m) _Pragma("unroll") for (int k = 0; k < 2; ++k) dst[m][k] = *(const LAS bf16x8*)(pA + PG8_SA(b, h) + m * 2048 + k * 1024); } while (0)
; #define PG8_LDB(dst, b, h) do { _Pragma("unroll") for (int n = 0; n < 2; ++n) _Pragma("unroll") for (int k = 0; k < 2; ++k) dst[n][k] = *(const LAS bf16x8*)(pB + (PG8_SB(b, h) - 4 * HTB) + n * 2048 + k * 1024); } while (0)
; #define PG8_MMA(ai, bj, At, Bt) do { __builtin_amdgcn_s_setprio(1); _Pragma("unroll") for (int m = 0; m < 4; ++m) _Pragma("unroll") for (int n = 0; n < 2; ++n) _Pragma("unroll") for (int k = 0; k < 2; ++k) \
;         acc[ai][bj][m][n] = __builtin_amdgcn_mfma_f32_16x16x32_bf16(Bt[n][k], At[m][k], acc[ai][bj][m][n], 0, 0, 0); __builtin_amdgcn_s_setprio(0); } while (0)
; #define PG8_WAIT_V(n) asm volatile("s_waitcnt vmcnt(" #n ")" ::: "memory")
; #define PG8_BAR __builtin_amdgcn_s_barrier()
; template <class Desc, class Epi, bool ALIGN_EPI>
; __device__ __forceinline__ void gemm_phase(LAS unsigned char* lds, const Desc& D, const Epi& E, int G, int c) {
;     ...
;         for (int t = 0; t < nt; t += 2) {
;             const bool last = (t == nt - 2);
;             if (last && has_next) PG8_AWAIT(nxt);
;             const char* a1 = cA + (size_t)(t + 1) * kstep;
;             const char* a2 = last ? nA : cA + (size_t)(t + 2) * kstep; const char* b2 = last ? nB : cB + (size_t)(t + 2) * kstep;
;             const char* a3 = a2 + kstep; const char* b3 = b2 + kstep;
;             PG8_LDB(B0, 0, 0); PG8_LDB(B1, 0, 1); PG8_SCHED; PG8_LDA(At, 0, 0); PG8_STAGE(PG8_SA(1, 1), a1 + hstepA, voffA);
;             PG8_WAIT_V(8); PG8_WAIT_L(0); PG8_BAR; PG8_MMA(0, 0, At, B0); PG8_MMA(0, 1, At, B1); PG8_BAR; PG8_SCHED;
;             PG8_LDA(At, 0, 1); PG8_STAGE(PG8_SB(0, 0), b2, voffB); PG8_STAGE(PG8_SB(0, 1), b2 + hstepB, voffB); PG8_STAGE(PG8_SA(0, 0), a2, voffA);
;             PG8_WAIT_V(8); PG8_WAIT_L(0); PG8_BAR; PG8_MMA(1, 0, At, B0); PG8_MMA(1, 1, At, B1); PG8_BAR; PG8_SCHED;
.LBB0_1580:
	s_or_b32 s14, s30, 1
	s_add_i32 s30, s30, 2
	s_mov_b32 s31, s15
	s_lshl_b64 s[72:73], s[14:15], 7
	s_lshl_b64 s[74:75], s[30:31], 7
	s_add_u32 s14, s18, s74
	ds_read_b128 v[140:143], v163
	ds_read_b128 v[144:147], v163 offset:1024
	ds_read_b128 v[148:151], v163 offset:2048
	ds_read_b128 v[152:155], v163 offset:3072
	ds_read_b128 v[156:159], v163 offset:16384
	ds_read_b128 v[166:169], v163 offset:17408
	ds_read_b128 v[170:173], v163 offset:18432
	ds_read_b128 v[174:177], v163 offset:19456
	s_addc_u32 s31, s19, s75
	s_and_b64 s[46:47], s[34:35], exec
	s_cselect_b32 s47, s43, s31
	s_cselect_b32 s46, s42, s14
	s_add_u32 s14, s20, s74
	s_addc_u32 s31, s21, s75
	s_and_b64 s[34:35], s[34:35], exec
	s_cselect_b32 s35, s3, s31
	s_cselect_b32 s34, s13, s14
	s_add_u32 s14, s18, s72
	s_addc_u32 s31, s19, s73
	s_add_u32 s72, s14, 0x100000
	s_addc_u32 s73, s31, 0
	s_add_i32 m0, s52, 0xc000
	ds_read_b128 v[178:181], v162
	ds_read_b128 v[182:185], v162 offset:1024
	ds_read_b128 v[186:189], v162 offset:2048
	ds_read_b128 v[190:193], v162 offset:3072
	ds_read_b128 v[194:197], v162 offset:4096
	ds_read_b128 v[198:201], v162 offset:5120
	ds_read_b128 v[202:205], v162 offset:6144
	ds_read_b128 v[206:209], v162 offset:7168
	global_load_lds_dwordx4 v132, s[72:73]
	s_add_i32 m0, s52, 0xe000
	s_nop 0
	global_load_lds_dwordx4 v136, s[72:73]
	s_waitcnt vmcnt(8)
	s_waitcnt lgkmcnt(0)
	s_barrier
	v_mfma_f32_16x16x32_bf16 v[128:131], v[140:143], v[178:181], v[128:131]
	v_mfma_f32_16x16x32_bf16 v[128:131], v[144:147], v[182:185], v[128:131]
	v_mfma_f32_16x16x32_bf16 v[120:123], v[144:147], v[190:193], v[120:123]
	v_mfma_f32_16x16x32_bf16 v[120:123], v[140:143], v[186:189], v[120:123]
	v_mfma_f32_16x16x32_bf16 v[112:115], v[140:143], v[194:197], v[112:115]
	v_mfma_f32_16x16x32_bf16 v[112:115], v[144:147], v[198:201], v[112:115]
	v_mfma_f32_16x16x32_bf16 v[104:107], v[144:147], v[206:209], v[104:107]
	v_mfma_f32_16x16x32_bf16 v[104:107], v[140:143], v[202:205], v[104:107]
	v_mfma_f32_16x16x32_bf16 v[100:103], v[148:151], v[202:205], v[100:103]
	v_mfma_f32_16x16x32_bf16 v[100:103], v[152:155], v[206:209], v[100:103]
	v_mfma_f32_16x16x32_bf16 v[108:111], v[152:155], v[198:201], v[108:111]
	v_mfma_f32_16x16x32_bf16 v[108:111], v[148:151], v[194:197], v[108:111]
	v_mfma_f32_16x16x32_bf16 v[116:119], v[148:151], v[186:189], v[116:119]
	v_mfma_f32_16x16x32_bf16 v[116:119], v[152:155], v[190:193], v[116:119]
	v_mfma_f32_16x16x32_bf16 v[124:127], v[152:155], v[182:185], v[124:127]
	v_mfma_f32_16x16x32_bf16 v[124:127], v[148:151], v[178:181], v[124:127]
	v_mfma_f32_16x16x32_bf16 v[96:99], v[156:159], v[178:181], v[96:99]
	v_mfma_f32_16x16x32_bf16 v[96:99], v[166:169], v[182:185], v[96:99]
	v_mfma_f32_16x16x32_bf16 v[88:91], v[166:169], v[190:193], v[88:91]
	v_mfma_f32_16x16x32_bf16 v[88:91], v[156:159], v[186:189], v[88:91]
	v_mfma_f32_16x16x32_bf16 v[80:83], v[156:159], v[194:197], v[80:83]
	v_mfma_f32_16x16x32_bf16 v[80:83], v[166:169], v[198:201], v[80:83]
	v_mfma_f32_16x16x32_bf16 v[72:75], v[166:169], v[206:209], v[72:75]
	v_mfma_f32_16x16x32_bf16 v[72:75], v[156:159], v[202:205], v[72:75]
	v_mfma_f32_16x16x32_bf16 v[68:71], v[170:173], v[202:205], v[68:71]
	v_mfma_f32_16x16x32_bf16 v[68:71], v[174:177], v[206:209], v[68:71]
	v_mfma_f32_16x16x32_bf16 v[76:79], v[174:177], v[198:201], v[76:79]
	v_mfma_f32_16x16x32_bf16 v[76:79], v[170:173], v[194:197], v[76:79]
	v_mfma_f32_16x16x32_bf16 v[84:87], v[170:173], v[186:189], v[84:87]
	v_mfma_f32_16x16x32_bf16 v[84:87], v[174:177], v[190:193], v[84:87]
	v_mfma_f32_16x16x32_bf16 v[92:95], v[174:177], v[182:185], v[92:95]
	v_mfma_f32_16x16x32_bf16 v[92:95], v[170:173], v[178:181], v[92:95]
	s_barrier
	s_mov_b32 m0, s53
	s_add_u32 s72, s34, 0x100000
	s_addc_u32 s73, s35, 0
	ds_read_b128 v[178:181], v162 offset:16384
	ds_read_b128 v[182:185], v162 offset:17408
	ds_read_b128 v[186:189], v162 offset:18432
	ds_read_b128 v[190:193], v162 offset:19456
	ds_read_b128 v[194:197], v162 offset:20480
	ds_read_b128 v[198:201], v162 offset:21504
	ds_read_b128 v[202:205], v162 offset:22528
	ds_read_b128 v[206:209], v162 offset:23552
	global_load_lds_dwordx4 v134, s[34:35]
	s_mov_b32 m0, s54
	s_nop 0
	global_load_lds_dwordx4 v138, s[34:35]
	s_mov_b32 m0, s55
	s_nop 0
	global_load_lds_dwordx4 v134, s[72:73]
	s_mov_b32 m0, s56
	s_nop 0
	global_load_lds_dwordx4 v138, s[72:73]
	s_mov_b32 m0, s52
	s_nop 0
	global_load_lds_dwordx4 v132, s[46:47]
	s_mov_b32 m0, s57
	s_nop 0
	global_load_lds_dwordx4 v136, s[46:47]
	s_waitcnt vmcnt(8)
	s_waitcnt lgkmcnt(0)
	s_barrier
; #define PG8_STAGE(bufoff, gbase, voff) do { _Pragma("unroll") for (int _i = 0; _i < 2; ++_i) \
;         __builtin_amdgcn_global_load_lds((const unsigned*)((const char*)(gbase) + (voff)[_i]), (LAS unsigned*)(lds + (bufoff) + ldsw + _i * 8192), 16, 0, 0); } while (0)
; #define PG8_LDA(dst, b, h) do { _Pragma("unroll") for (int m = 0; m < 4; ++m) _Pragma("unroll") for (int k = 0; k < 2; ++k) dst[m][k] = *(const LAS bf16x8*)(pA + PG8_SA(b, h) + m * 2048 + k * 1024); } while (0)
; #define PG8_LDB(dst, b, h) do { _Pragma("unroll") for (int n = 0; n < 2; ++n) _Pragma("unroll") for (int k = 0; k < 2; ++k) dst[n][k] = *(const LAS bf16x8*)(pB + (PG8_SB(b, h) - 4 * HTB) + n * 2048 + k * 1024); } while (0)
; #define PG8_MMA(ai, bj, At, Bt) do { __builtin_amdgcn_s_setprio(1); _Pragma("unroll") for (int m = 0; m < 4; ++m) _Pragma("unroll") for (int n = 0; n < 2; ++n) _Pragma("unroll") for (int k = 0; k < 2; ++k) \
;         acc[ai][bj][m][n] = __builtin_amdgcn_mfma_f32_16x16x32_bf16(Bt[n][k], At[m][k], acc[ai][bj][m][n], 0, 0, 0); __builtin_amdgcn_s_setprio(0); } while (0)
; #define PG8_WAIT_V(n) asm volatile("s_waitcnt vmcnt(" #n ")" ::: "memory")
; #define PG8_WAIT_L(n) asm volatile("s_waitcnt lgkmcnt(" #n ")" ::: "memory")
; #define PG8_BAR __builtin_amdgcn_s_barrier()
; #define PG8_SCHED __builtin_amdgcn_sched_barrier(0)
; template <class Desc, class Epi, bool ALIGN_EPI>
; __device__ __forceinline__ void gemm_phase(LAS unsigned char* lds, const Desc& D, const Epi& E, int G, int c) {
;     ...
;             PG8_WAIT_V(8); PG8_WAIT_L(0); PG8_BAR; PG8_MMA(1, 0, At, B0); PG8_MMA(1, 1, At, B1); PG8_BAR; PG8_SCHED;
;             PG8_LDB(B0, 1, 0); PG8_LDB(B1, 1, 1); PG8_SCHED; PG8_LDA(At, 1, 0); PG8_STAGE(PG8_SA(0, 1), a2 + hstepA, voffA);
;             PG8_WAIT_V(8); PG8_WAIT_L(0); PG8_BAR; PG8_MMA(0, 0, At, B0); PG8_MMA(0, 1, At, B1); PG8_BAR; PG8_SCHED;
	v_mfma_f32_16x16x32_bf16 v[64:67], v[140:143], v[178:181], v[64:67]
	v_mfma_f32_16x16x32_bf16 v[64:67], v[144:147], v[182:185], v[64:67]
	v_mfma_f32_16x16x32_bf16 v[32:35], v[144:147], v[190:193], v[32:35]
	v_mfma_f32_16x16x32_bf16 v[32:35], v[140:143], v[186:189], v[32:35]
	v_mfma_f32_16x16x32_bf16 v[16:19], v[140:143], v[194:197], v[16:19]
	v_mfma_f32_16x16x32_bf16 v[16:19], v[144:147], v[198:201], v[16:19]
	v_mfma_f32_16x16x32_bf16 v[8:11], v[144:147], v[206:209], v[8:11]
	v_mfma_f32_16x16x32_bf16 v[8:11], v[140:143], v[202:205], v[8:11]
	v_mfma_f32_16x16x32_bf16 v[4:7], v[148:151], v[202:205], v[4:7]
	v_mfma_f32_16x16x32_bf16 v[4:7], v[152:155], v[206:209], v[4:7]
	v_mfma_f32_16x16x32_bf16 v[12:15], v[152:155], v[198:201], v[12:15]
	v_mfma_f32_16x16x32_bf16 v[12:15], v[148:151], v[194:197], v[12:15]
	v_mfma_f32_16x16x32_bf16 v[20:23], v[148:151], v[186:189], v[20:23]
	v_mfma_f32_16x16x32_bf16 v[20:23], v[152:155], v[190:193], v[20:23]
	v_mfma_f32_16x16x32_bf16 v[52:55], v[152:155], v[182:185], v[52:55]
	v_mfma_f32_16x16x32_bf16 v[52:55], v[148:151], v[178:181], v[52:55]
	v_mfma_f32_16x16x32_bf16 v[60:63], v[156:159], v[178:181], v[60:63]
	v_mfma_f32_16x16x32_bf16 v[60:63], v[166:169], v[182:185], v[60:63]
	v_mfma_f32_16x16x32_bf16 v[48:51], v[166:169], v[190:193], v[48:51]
	v_mfma_f32_16x16x32_bf16 v[48:51], v[156:159], v[186:189], v[48:51]
	v_mfma_f32_16x16x32_bf16 v[40:43], v[156:159], v[194:197], v[40:43]
	v_mfma_f32_16x16x32_bf16 v[40:43], v[166:169], v[198:201], v[40:43]
	v_mfma_f32_16x16x32_bf16 v[28:31], v[166:169], v[206:209], v[28:31]
	v_mfma_f32_16x16x32_bf16 v[28:31], v[156:159], v[202:205], v[28:31]
	v_mfma_f32_16x16x32_bf16 v[24:27], v[170:173], v[202:205], v[24:27]
	v_mfma_f32_16x16x32_bf16 v[24:27], v[174:177], v[206:209], v[24:27]
	v_mfma_f32_16x16x32_bf16 v[36:39], v[174:177], v[198:201], v[36:39]
	v_mfma_f32_16x16x32_bf16 v[36:39], v[170:173], v[194:197], v[36:39]
	v_mfma_f32_16x16x32_bf16 v[44:47], v[170:173], v[186:189], v[44:47]
	v_mfma_f32_16x16x32_bf16 v[44:47], v[174:177], v[190:193], v[44:47]
	v_mfma_f32_16x16x32_bf16 v[56:59], v[174:177], v[182:185], v[56:59]
	v_mfma_f32_16x16x32_bf16 v[56:59], v[170:173], v[178:181], v[56:59]
	s_barrier
	ds_read_b128 v[140:143], v163 offset:32768
	ds_read_b128 v[144:147], v163 offset:33792
	ds_read_b128 v[148:151], v163 offset:34816
	ds_read_b128 v[152:155], v163 offset:35840
	ds_read_b128 v[156:159], v163 offset:49152
	ds_read_b128 v[166:169], v163 offset:50176
	ds_read_b128 v[170:173], v163 offset:51200
	ds_read_b128 v[174:177], v163 offset:52224
	s_add_u32 s46, s46, 0x100000
	s_addc_u32 s47, s47, 0
	s_mov_b32 m0, s58
	ds_read_b128 v[178:181], v162 offset:32768
	ds_read_b128 v[182:185], v162 offset:33792
	ds_read_b128 v[186:189], v162 offset:34816
	ds_read_b128 v[190:193], v162 offset:35840
	ds_read_b128 v[194:197], v162 offset:36864
	ds_read_b128 v[198:201], v162 offset:37888
	ds_read_b128 v[202:205], v162 offset:38912
	ds_read_b128 v[206:209], v162 offset:39936
	global_load_lds_dwordx4 v132, s[46:47]
	s_mov_b32 m0, s59
	s_nop 0
	global_load_lds_dwordx4 v136, s[46:47]
	s_waitcnt vmcnt(8)
	s_waitcnt lgkmcnt(0)
	s_barrier
	v_mfma_f32_16x16x32_bf16 v[128:131], v[140:143], v[178:181], v[128:131]
	v_mfma_f32_16x16x32_bf16 v[128:131], v[144:147], v[182:185], v[128:131]
	v_mfma_f32_16x16x32_bf16 v[120:123], v[144:147], v[190:193], v[120:123]
	v_mfma_f32_16x16x32_bf16 v[120:123], v[140:143], v[186:189], v[120:123]
	v_mfma_f32_16x16x32_bf16 v[112:115], v[140:143], v[194:197], v[112:115]
	v_mfma_f32_16x16x32_bf16 v[112:115], v[144:147], v[198:201], v[112:115]
	v_mfma_f32_16x16x32_bf16 v[104:107], v[144:147], v[206:209], v[104:107]
	v_mfma_f32_16x16x32_bf16 v[104:107], v[140:143], v[202:205], v[104:107]
	v_mfma_f32_16x16x32_bf16 v[100:103], v[148:151], v[202:205], v[100:103]
	v_mfma_f32_16x16x32_bf16 v[100:103], v[152:155], v[206:209], v[100:103]
	v_mfma_f32_16x16x32_bf16 v[108:111], v[152:155], v[198:201], v[108:111]
	v_mfma_f32_16x16x32_bf16 v[108:111], v[148:151], v[194:197], v[108:111]
	v_mfma_f32_16x16x32_bf16 v[116:119], v[148:151], v[186:189], v[116:119]
	v_mfma_f32_16x16x32_bf16 v[116:119], v[152:155], v[190:193], v[116:119]
	v_mfma_f32_16x16x32_bf16 v[124:127], v[152:155], v[182:185], v[124:127]
	v_mfma_f32_16x16x32_bf16 v[124:127], v[148:151], v[178:181], v[124:127]
	v_mfma_f32_16x16x32_bf16 v[96:99], v[156:159], v[178:181], v[96:99]
	v_mfma_f32_16x16x32_bf16 v[96:99], v[166:169], v[182:185], v[96:99]
	v_mfma_f32_16x16x32_bf16 v[88:91], v[166:169], v[190:193], v[88:91]
	v_mfma_f32_16x16x32_bf16 v[88:91], v[156:159], v[186:189], v[88:91]
	v_mfma_f32_16x16x32_bf16 v[80:83], v[156:159], v[194:197], v[80:83]
	v_mfma_f32_16x16x32_bf16 v[80:83], v[166:169], v[198:201], v[80:83]
	v_mfma_f32_16x16x32_bf16 v[72:75], v[166:169], v[206:209], v[72:75]
	v_mfma_f32_16x16x32_bf16 v[72:75], v[156:159], v[202:205], v[72:75]
	v_mfma_f32_16x16x32_bf16 v[68:71], v[170:173], v[202:205], v[68:71]
	v_mfma_f32_16x16x32_bf16 v[68:71], v[174:177], v[206:209], v[68:71]
	v_mfma_f32_16x16x32_bf16 v[76:79], v[174:177], v[198:201], v[76:79]
	v_mfma_f32_16x16x32_bf16 v[76:79], v[170:173], v[194:197], v[76:79]
	v_mfma_f32_16x16x32_bf16 v[84:87], v[170:173], v[186:189], v[84:87]
	v_mfma_f32_16x16x32_bf16 v[84:87], v[174:177], v[190:193], v[84:87]
	v_mfma_f32_16x16x32_bf16 v[92:95], v[174:177], v[182:185], v[92:95]
	v_mfma_f32_16x16x32_bf16 v[92:95], v[170:173], v[178:181], v[92:95]
	s_barrier
; #define PG8_STAGE(bufoff, gbase, voff) do { _Pragma("unroll") for (int _i = 0; _i < 2; ++_i) \
;         __builtin_amdgcn_global_load_lds((const unsigned*)((const char*)(gbase) + (voff)[_i]), (LAS unsigned*)(lds + (bufoff) + ldsw + _i * 8192), 16, 0, 0); } while (0)
; #define PG8_LDA(dst, b, h) do { _Pragma("unroll") for (int m = 0; m < 4; ++m) _Pragma("unroll") for (int k = 0; k < 2; ++k) dst[m][k] = *(const LAS bf16x8*)(pA + PG8_SA(b, h) + m * 2048 + k * 1024); } while (0)
; #define PG8_MMA(ai, bj, At, Bt) do { __builtin_amdgcn_s_setprio(1); _Pragma("unroll") for (int m = 0; m < 4; ++m) _Pragma("unroll") for (int n = 0; n < 2; ++n) _Pragma("unroll") for (int k = 0; k < 2; ++k) \
;         acc[ai][bj][m][n] = __builtin_amdgcn_mfma_f32_16x16x32_bf16(Bt[n][k], At[m][k], acc[ai][bj][m][n], 0, 0, 0); __builtin_amdgcn_s_setprio(0); } while (0)
; #define PG8_WAIT_V(n) asm volatile("s_waitcnt vmcnt(" #n ")" ::: "memory")
; #define PG8_WAIT_L(n) asm volatile("s_waitcnt lgkmcnt(" #n ")" ::: "memory")
; #define PG8_BAR __builtin_amdgcn_s_barrier()
; #define PG8_SCHED __builtin_amdgcn_sched_barrier(0)
; template <class Desc, class Epi, bool ALIGN_EPI>
; __device__ __forceinline__ void gemm_phase(LAS unsigned char* lds, const Desc& D, const Epi& E, int G, int c) {
;     ...
;             PG8_LDA(At, 1, 1); PG8_STAGE(PG8_SB(1, 0), b3, voffB); PG8_STAGE(PG8_SB(1, 1), b3 + hstepB, voffB); PG8_STAGE(PG8_SA(1, 0), a3, voffA);
;             PG8_WAIT_V(8); PG8_WAIT_L(0); PG8_BAR; PG8_MMA(1, 0, At, B0); PG8_MMA(1, 1, At, B1); PG8_BAR; PG8_SCHED;
;         }
	s_mov_b32 m0, s61
	s_add_u32 s74, s34, 0x80
	s_addc_u32 s75, s35, 0
	s_add_u32 s34, s34, 0x100080
	s_addc_u32 s35, s35, 0
	ds_read_b128 v[178:181], v162 offset:49152
	ds_read_b128 v[182:185], v162 offset:50176
	ds_read_b128 v[186:189], v162 offset:51200
	ds_read_b128 v[190:193], v162 offset:52224
	ds_read_b128 v[194:197], v162 offset:53248
	ds_read_b128 v[198:201], v162 offset:54272
	ds_read_b128 v[202:205], v162 offset:55296
	ds_read_b128 v[206:209], v162 offset:56320
	global_load_lds_dwordx4 v134, s[74:75]
	s_mov_b32 m0, s62
	s_nop 0
	global_load_lds_dwordx4 v138, s[74:75]
	s_mov_b32 m0, s65
	s_nop 0
	global_load_lds_dwordx4 v134, s[34:35]
	s_mov_b32 m0, s67
	s_nop 0
	global_load_lds_dwordx4 v138, s[34:35]
	s_sub_u32 s74, s46, 0xfff80
	s_subb_u32 s75, s47, 0
	s_mov_b32 m0, s63
	s_nop 0
	global_load_lds_dwordx4 v132, s[74:75]
	s_mov_b32 m0, s64
	s_nop 0
	global_load_lds_dwordx4 v136, s[74:75]
	s_waitcnt vmcnt(8)
	s_waitcnt lgkmcnt(0)
	s_barrier
	v_mfma_f32_16x16x32_bf16 v[64:67], v[140:143], v[178:181], v[64:67]
	v_mfma_f32_16x16x32_bf16 v[64:67], v[144:147], v[182:185], v[64:67]
	v_mfma_f32_16x16x32_bf16 v[32:35], v[144:147], v[190:193], v[32:35]
	v_mfma_f32_16x16x32_bf16 v[32:35], v[140:143], v[186:189], v[32:35]
	v_mfma_f32_16x16x32_bf16 v[16:19], v[140:143], v[194:197], v[16:19]
	v_mfma_f32_16x16x32_bf16 v[16:19], v[144:147], v[198:201], v[16:19]
	v_mfma_f32_16x16x32_bf16 v[8:11], v[144:147], v[206:209], v[8:11]
	v_mfma_f32_16x16x32_bf16 v[8:11], v[140:143], v[202:205], v[8:11]
	v_mfma_f32_16x16x32_bf16 v[4:7], v[148:151], v[202:205], v[4:7]
	v_mfma_f32_16x16x32_bf16 v[4:7], v[152:155], v[206:209], v[4:7]
	v_mfma_f32_16x16x32_bf16 v[12:15], v[152:155], v[198:201], v[12:15]
	v_mfma_f32_16x16x32_bf16 v[12:15], v[148:151], v[194:197], v[12:15]
	v_mfma_f32_16x16x32_bf16 v[20:23], v[148:151], v[186:189], v[20:23]
	v_mfma_f32_16x16x32_bf16 v[20:23], v[152:155], v[190:193], v[20:23]
	v_mfma_f32_16x16x32_bf16 v[52:55], v[152:155], v[182:185], v[52:55]
	v_mfma_f32_16x16x32_bf16 v[52:55], v[148:151], v[178:181], v[52:55]
	v_mfma_f32_16x16x32_bf16 v[60:63], v[156:159], v[178:181], v[60:63]
	v_mfma_f32_16x16x32_bf16 v[60:63], v[166:169], v[182:185], v[60:63]
	v_mfma_f32_16x16x32_bf16 v[48:51], v[166:169], v[190:193], v[48:51]
	v_mfma_f32_16x16x32_bf16 v[48:51], v[156:159], v[186:189], v[48:51]
	v_mfma_f32_16x16x32_bf16 v[40:43], v[156:159], v[194:197], v[40:43]
	v_mfma_f32_16x16x32_bf16 v[40:43], v[166:169], v[198:201], v[40:43]
	v_mfma_f32_16x16x32_bf16 v[28:31], v[166:169], v[206:209], v[28:31]
	v_mfma_f32_16x16x32_bf16 v[28:31], v[156:159], v[202:205], v[28:31]
	v_mfma_f32_16x16x32_bf16 v[24:27], v[170:173], v[202:205], v[24:27]
	v_mfma_f32_16x16x32_bf16 v[24:27], v[174:177], v[206:209], v[24:27]
	v_mfma_f32_16x16x32_bf16 v[36:39], v[174:177], v[198:201], v[36:39]
	v_mfma_f32_16x16x32_bf16 v[36:39], v[170:173], v[194:197], v[36:39]
	v_mfma_f32_16x16x32_bf16 v[44:47], v[170:173], v[186:189], v[44:47]
	v_mfma_f32_16x16x32_bf16 v[44:47], v[174:177], v[190:193], v[44:47]
	v_mfma_f32_16x16x32_bf16 v[56:59], v[174:177], v[182:185], v[56:59]
	v_mfma_f32_16x16x32_bf16 v[56:59], v[170:173], v[178:181], v[56:59]
	s_barrier
	s_cmp_ge_u32 s30, s2
	s_cbranch_scc1 .LBB0_1591

;     __device__ __forceinline__ int nt(const Unit& u) const { return (u.pn >> 1) < 2 ? 22 : 20; }
; #define PG8_STAGE(bufoff, gbase, voff) do { _Pragma("unroll") for (int _i = 0; _i < 2; ++_i) \
;         __builtin_amdgcn_global_load_lds((const unsigned*)((const char*)(gbase) + (voff)[_i]), (LAS unsigned*)(lds + (bufoff) + ldsw + _i * 8192), 16, 0, 0); } while (0)
; #define PG8_LDA(dst, b, h) do { _Pragma("unroll") for (int m = 0; m < 4; ++m) _Pragma("unroll") for (int k = 0; k < 2; ++k) dst[m][k] = *(const LAS bf16x8*)(pA + PG8_SA(b, h) + m * 2048 + k * 1024); } while (0)
; #define PG8_LDB(dst, b, h) do { _Pragma("unroll") for (int n = 0; n < 2; ++n) _Pragma("unroll") for (int k = 0; k < 2; ++k) dst[n][k] = *(const LAS bf16x8*)(pB + (PG8_SB(b, h) - 4 * HTB) + n * 2048 + k * 1024); } while (0)
; #define PG8_MMA(ai, bj, At, Bt) do { __builtin_amdgcn_s_setprio(1); _Pragma("unroll") for (int m = 0; m < 4; ++m) _Pragma("unroll") for (int n = 0; n < 2; ++n) _Pragma("unroll") for (int k = 0; k < 2; ++k) \
;         acc[ai][bj][m][n] = __builtin_amdgcn_mfma_f32_16x16x32_bf16(Bt[n][k], At[m][k], acc[ai][bj][m][n], 0, 0, 0); __builtin_amdgcn_s_setprio(0); } while (0)
; #define PG8_WAIT_V(n) asm volatile("s_waitcnt vmcnt(" #n ")" ::: "memory")
; #define PG8_BAR __builtin_amdgcn_s_barrier()
; template <class Desc, class Epi, bool ALIGN_EPI>
; __device__ __forceinline__ void gemm_phase(LAS unsigned char* lds, const Desc& D, const Epi& E, int G, int c) {
;     ...
;         for (int t = 0; t < nt; t += 2) {
;             const bool last = (t == nt - 2);
;             if (last && has_next) PG8_AWAIT(nxt);
;             const char* a1 = cA + (size_t)(t + 1) * kstep;
;             const char* a2 = last ? nA : cA + (size_t)(t + 2) * kstep; const char* b2 = last ? nB : cB + (size_t)(t + 2) * kstep;
;             const char* a3 = a2 + kstep; const char* b3 = b2 + kstep;
;             PG8_LDB(B0, 0, 0); PG8_LDB(B1, 0, 1); PG8_SCHED; PG8_LDA(At, 0, 0); PG8_STAGE(PG8_SA(1, 1), a1 + hstepA, voffA);
;             PG8_WAIT_V(8); PG8_WAIT_L(0); PG8_BAR; PG8_MMA(0, 0, At, B0); PG8_MMA(0, 1, At, B1); PG8_BAR; PG8_SCHED;
;             PG8_LDA(At, 0, 1); PG8_STAGE(PG8_SB(0, 0), b2, voffB); PG8_STAGE(PG8_SB(0, 1), b2 + hstepB, voffB); PG8_STAGE(PG8_SA(0, 0), a2, voffA);
;             PG8_WAIT_V(8); PG8_WAIT_L(0); PG8_BAR; PG8_MMA(1, 0, At, B0); PG8_MMA(1, 1, At, B1); PG8_BAR; PG8_SCHED;
.LBB0_1765:
	s_or_b32 s14, s39, 1
	s_lshl_b64 s[40:41], s[14:15], 7
	s_add_i32 s14, s39, 2
	s_lshl_b64 s[42:43], s[14:15], 7
	s_add_u32 s39, s12, s42
	s_waitcnt lgkmcnt(0)
	ds_read_b128 v[132:135], v248
	ds_read_b128 v[136:139], v248 offset:1024
	ds_read_b128 v[140:143], v248 offset:2048
	ds_read_b128 v[144:147], v248 offset:3072
	ds_read_b128 v[148:151], v248 offset:16384
	ds_read_b128 v[152:155], v248 offset:17408
	ds_read_b128 v[156:159], v248 offset:18432
	ds_read_b128 v[160:163], v248 offset:19456
	s_addc_u32 s78, s13, s43
	s_and_b64 s[30:31], s[20:21], exec
	s_cselect_b32 s31, s49, s78
	s_cselect_b32 s30, s48, s39
	s_add_u32 s39, s16, s42
	s_addc_u32 s42, s17, s43
	s_and_b64 s[20:21], s[20:21], exec
	s_cselect_b32 s21, s51, s42
	s_cselect_b32 s20, s50, s39
	s_add_u32 s39, s12, s40
	s_addc_u32 s41, s13, s41
	s_add_u32 s40, s39, 0x2b0000
	s_addc_u32 s41, s41, 0
	v_lshl_add_u64 v[196:197], s[40:41], 0, v[200:201]
	s_add_i32 m0, s56, 0xc000
	ds_read_b128 v[164:167], v247
	ds_read_b128 v[168:171], v247 offset:1024
	ds_read_b128 v[172:175], v247 offset:2048
	ds_read_b128 v[176:179], v247 offset:3072
	ds_read_b128 v[180:183], v247 offset:4096
	ds_read_b128 v[184:187], v247 offset:5120
	ds_read_b128 v[188:191], v247 offset:6144
	ds_read_b128 v[192:195], v247 offset:7168
	global_load_lds_dwordx4 v[196:197], off
	v_lshl_add_u64 v[196:197], s[40:41], 0, v[204:205]
	s_add_i32 m0, s56, 0xe000
	s_nop 0
	global_load_lds_dwordx4 v[196:197], off
	s_waitcnt vmcnt(8)
	s_waitcnt lgkmcnt(0)
	s_barrier
	v_mfma_f32_16x16x32_bf16 v[128:131], v[132:135], v[164:167], v[128:131]
	v_mfma_f32_16x16x32_bf16 v[128:131], v[136:139], v[168:171], v[128:131]
	v_mfma_f32_16x16x32_bf16 v[120:123], v[136:139], v[176:179], v[120:123]
	v_mfma_f32_16x16x32_bf16 v[120:123], v[132:135], v[172:175], v[120:123]
	v_mfma_f32_16x16x32_bf16 v[112:115], v[132:135], v[180:183], v[112:115]
	v_mfma_f32_16x16x32_bf16 v[112:115], v[136:139], v[184:187], v[112:115]
	v_mfma_f32_16x16x32_bf16 v[104:107], v[136:139], v[192:195], v[104:107]
	v_mfma_f32_16x16x32_bf16 v[104:107], v[132:135], v[188:191], v[104:107]
	v_mfma_f32_16x16x32_bf16 v[100:103], v[140:143], v[188:191], v[100:103]
	v_mfma_f32_16x16x32_bf16 v[100:103], v[144:147], v[192:195], v[100:103]
	v_mfma_f32_16x16x32_bf16 v[108:111], v[144:147], v[184:187], v[108:111]
	v_mfma_f32_16x16x32_bf16 v[108:111], v[140:143], v[180:183], v[108:111]
	v_mfma_f32_16x16x32_bf16 v[116:119], v[140:143], v[172:175], v[116:119]
	v_mfma_f32_16x16x32_bf16 v[116:119], v[144:147], v[176:179], v[116:119]
	v_mfma_f32_16x16x32_bf16 v[124:127], v[144:147], v[168:171], v[124:127]
	v_mfma_f32_16x16x32_bf16 v[124:127], v[140:143], v[164:167], v[124:127]
	v_mfma_f32_16x16x32_bf16 v[96:99], v[148:151], v[164:167], v[96:99]
	v_mfma_f32_16x16x32_bf16 v[96:99], v[152:155], v[168:171], v[96:99]
	v_mfma_f32_16x16x32_bf16 v[88:91], v[152:155], v[176:179], v[88:91]
	v_mfma_f32_16x16x32_bf16 v[88:91], v[148:151], v[172:175], v[88:91]
	v_mfma_f32_16x16x32_bf16 v[64:67], v[148:151], v[180:183], v[64:67]
	v_mfma_f32_16x16x32_bf16 v[64:67], v[152:155], v[184:187], v[64:67]
	v_mfma_f32_16x16x32_bf16 v[32:35], v[152:155], v[192:195], v[32:35]
	v_mfma_f32_16x16x32_bf16 v[32:35], v[148:151], v[188:191], v[32:35]
	v_mfma_f32_16x16x32_bf16 v[20:23], v[156:159], v[188:191], v[20:23]
	v_mfma_f32_16x16x32_bf16 v[20:23], v[160:163], v[192:195], v[20:23]
	v_mfma_f32_16x16x32_bf16 v[52:55], v[160:163], v[184:187], v[52:55]
	v_mfma_f32_16x16x32_bf16 v[52:55], v[156:159], v[180:183], v[52:55]
	v_mfma_f32_16x16x32_bf16 v[80:83], v[156:159], v[172:175], v[80:83]
	v_mfma_f32_16x16x32_bf16 v[80:83], v[160:163], v[176:179], v[80:83]
	v_mfma_f32_16x16x32_bf16 v[92:95], v[160:163], v[168:171], v[92:95]
	v_mfma_f32_16x16x32_bf16 v[92:95], v[156:159], v[164:167], v[92:95]
	s_barrier
	s_mov_b32 m0, s57
	v_lshl_add_u64 v[196:197], s[20:21], 0, v[202:203]
	s_add_u32 s40, s20, 0x2b0000
	ds_read_b128 v[164:167], v247 offset:16384
	ds_read_b128 v[168:171], v247 offset:17408
	ds_read_b128 v[172:175], v247 offset:18432
	ds_read_b128 v[176:179], v247 offset:19456
	ds_read_b128 v[180:183], v247 offset:20480
	ds_read_b128 v[184:187], v247 offset:21504
	ds_read_b128 v[188:191], v247 offset:22528
	ds_read_b128 v[192:195], v247 offset:23552
	global_load_lds_dwordx4 v[196:197], off
	v_lshl_add_u64 v[198:199], s[20:21], 0, v[206:207]
	s_mov_b32 m0, s58
	s_addc_u32 s41, s21, 0
	global_load_lds_dwordx4 v[198:199], off
	v_lshl_add_u64 v[208:209], s[40:41], 0, v[202:203]
	s_mov_b32 m0, s59
	v_lshl_add_u64 v[210:211], s[30:31], 0, v[204:205]
	global_load_lds_dwordx4 v[208:209], off
	v_lshl_add_u64 v[208:209], s[40:41], 0, v[206:207]
	s_mov_b32 m0, s60
	s_nop 0
	global_load_lds_dwordx4 v[208:209], off
	v_lshl_add_u64 v[208:209], s[30:31], 0, v[200:201]
	s_mov_b32 m0, s56
	s_nop 0
	global_load_lds_dwordx4 v[208:209], off
	s_mov_b32 m0, s61
	s_nop 0
	global_load_lds_dwordx4 v[210:211], off
	s_waitcnt vmcnt(8)
	s_waitcnt lgkmcnt(0)
	s_barrier
; #define PG8_STAGE(bufoff, gbase, voff) do { _Pragma("unroll") for (int _i = 0; _i < 2; ++_i) \
;         __builtin_amdgcn_global_load_lds((const unsigned*)((const char*)(gbase) + (voff)[_i]), (LAS unsigned*)(lds + (bufoff) + ldsw + _i * 8192), 16, 0, 0); } while (0)
; #define PG8_LDA(dst, b, h) do { _Pragma("unroll") for (int m = 0; m < 4; ++m) _Pragma("unroll") for (int k = 0; k < 2; ++k) dst[m][k] = *(const LAS bf16x8*)(pA + PG8_SA(b, h) + m * 2048 + k * 1024); } while (0)
; #define PG8_LDB(dst, b, h) do { _Pragma("unroll") for (int n = 0; n < 2; ++n) _Pragma("unroll") for (int k = 0; k < 2; ++k) dst[n][k] = *(const LAS bf16x8*)(pB + (PG8_SB(b, h) - 4 * HTB) + n * 2048 + k * 1024); } while (0)
; #define PG8_MMA(ai, bj, At, Bt) do { __builtin_amdgcn_s_setprio(1); _Pragma("unroll") for (int m = 0; m < 4; ++m) _Pragma("unroll") for (int n = 0; n < 2; ++n) _Pragma("unroll") for (int k = 0; k < 2; ++k) \
;         acc[ai][bj][m][n] = __builtin_amdgcn_mfma_f32_16x16x32_bf16(Bt[n][k], At[m][k], acc[ai][bj][m][n], 0, 0, 0); __builtin_amdgcn_s_setprio(0); } while (0)
; #define PG8_WAIT_V(n) asm volatile("s_waitcnt vmcnt(" #n ")" ::: "memory")
; #define PG8_WAIT_L(n) asm volatile("s_waitcnt lgkmcnt(" #n ")" ::: "memory")
; #define PG8_BAR __builtin_amdgcn_s_barrier()
; #define PG8_SCHED __builtin_amdgcn_sched_barrier(0)
; template <class Desc, class Epi, bool ALIGN_EPI>
; __device__ __forceinline__ void gemm_phase(LAS unsigned char* lds, const Desc& D, const Epi& E, int G, int c) {
;     ...
;             PG8_WAIT_V(8); PG8_WAIT_L(0); PG8_BAR; PG8_MMA(1, 0, At, B0); PG8_MMA(1, 1, At, B1); PG8_BAR; PG8_SCHED;
;             PG8_LDB(B0, 1, 0); PG8_LDB(B1, 1, 1); PG8_SCHED; PG8_LDA(At, 1, 0); PG8_STAGE(PG8_SA(0, 1), a2 + hstepA, voffA);
;             PG8_WAIT_V(8); PG8_WAIT_L(0); PG8_BAR; PG8_MMA(0, 0, At, B0); PG8_MMA(0, 1, At, B1); PG8_BAR; PG8_SCHED;
	v_mfma_f32_16x16x32_bf16 v[84:87], v[132:135], v[164:167], v[84:87]
	v_mfma_f32_16x16x32_bf16 v[84:87], v[136:139], v[168:171], v[84:87]
	v_mfma_f32_16x16x32_bf16 v[72:75], v[136:139], v[176:179], v[72:75]
	v_mfma_f32_16x16x32_bf16 v[72:75], v[132:135], v[172:175], v[72:75]
	v_mfma_f32_16x16x32_bf16 v[60:63], v[132:135], v[180:183], v[60:63]
	v_mfma_f32_16x16x32_bf16 v[60:63], v[136:139], v[184:187], v[60:63]
	v_mfma_f32_16x16x32_bf16 v[48:51], v[136:139], v[192:195], v[48:51]
	v_mfma_f32_16x16x32_bf16 v[48:51], v[132:135], v[188:191], v[48:51]
	v_mfma_f32_16x16x32_bf16 v[44:47], v[140:143], v[188:191], v[44:47]
	v_mfma_f32_16x16x32_bf16 v[44:47], v[144:147], v[192:195], v[44:47]
	v_mfma_f32_16x16x32_bf16 v[56:59], v[144:147], v[184:187], v[56:59]
	v_mfma_f32_16x16x32_bf16 v[56:59], v[140:143], v[180:183], v[56:59]
	v_mfma_f32_16x16x32_bf16 v[68:71], v[140:143], v[172:175], v[68:71]
	v_mfma_f32_16x16x32_bf16 v[68:71], v[144:147], v[176:179], v[68:71]
	v_mfma_f32_16x16x32_bf16 v[76:79], v[144:147], v[168:171], v[76:79]
	v_mfma_f32_16x16x32_bf16 v[76:79], v[140:143], v[164:167], v[76:79]
	v_mfma_f32_16x16x32_bf16 v[40:43], v[148:151], v[164:167], v[40:43]
	v_mfma_f32_16x16x32_bf16 v[40:43], v[152:155], v[168:171], v[40:43]
	v_mfma_f32_16x16x32_bf16 v[28:31], v[152:155], v[176:179], v[28:31]
	v_mfma_f32_16x16x32_bf16 v[28:31], v[148:151], v[172:175], v[28:31]
	v_mfma_f32_16x16x32_bf16 v[16:19], v[148:151], v[180:183], v[16:19]
	v_mfma_f32_16x16x32_bf16 v[16:19], v[152:155], v[184:187], v[16:19]
	v_mfma_f32_16x16x32_bf16 v[8:11], v[152:155], v[192:195], v[8:11]
	v_mfma_f32_16x16x32_bf16 v[8:11], v[148:151], v[188:191], v[8:11]
	v_mfma_f32_16x16x32_bf16 v[4:7], v[156:159], v[188:191], v[4:7]
	v_mfma_f32_16x16x32_bf16 v[4:7], v[160:163], v[192:195], v[4:7]
	v_mfma_f32_16x16x32_bf16 v[12:15], v[160:163], v[184:187], v[12:15]
	v_mfma_f32_16x16x32_bf16 v[12:15], v[156:159], v[180:183], v[12:15]
	v_mfma_f32_16x16x32_bf16 v[24:27], v[156:159], v[172:175], v[24:27]
	v_mfma_f32_16x16x32_bf16 v[24:27], v[160:163], v[176:179], v[24:27]
	v_mfma_f32_16x16x32_bf16 v[36:39], v[160:163], v[168:171], v[36:39]
	v_mfma_f32_16x16x32_bf16 v[36:39], v[156:159], v[164:167], v[36:39]
	s_barrier
	ds_read_b128 v[132:135], v248 offset:32768
	ds_read_b128 v[136:139], v248 offset:33792
	ds_read_b128 v[140:143], v248 offset:34816
	ds_read_b128 v[144:147], v248 offset:35840
	ds_read_b128 v[148:151], v248 offset:49152
	ds_read_b128 v[152:155], v248 offset:50176
	ds_read_b128 v[156:159], v248 offset:51200
	ds_read_b128 v[160:163], v248 offset:52224
	s_add_u32 s30, s30, 0x2b0000
	s_addc_u32 s31, s31, 0
	s_mov_b32 m0, s62
	v_lshl_add_u64 v[212:213], s[30:31], 0, v[200:201]
	ds_read_b128 v[164:167], v247 offset:32768
	ds_read_b128 v[168:171], v247 offset:33792
	ds_read_b128 v[172:175], v247 offset:34816
	ds_read_b128 v[176:179], v247 offset:35840
	ds_read_b128 v[180:183], v247 offset:36864
	ds_read_b128 v[184:187], v247 offset:37888
	ds_read_b128 v[188:191], v247 offset:38912
	ds_read_b128 v[192:195], v247 offset:39936
	global_load_lds_dwordx4 v[212:213], off
	v_lshl_add_u64 v[212:213], s[30:31], 0, v[204:205]
	s_mov_b32 m0, s63
	s_nop 0
	global_load_lds_dwordx4 v[212:213], off
	s_waitcnt vmcnt(8)
	s_waitcnt lgkmcnt(0)
	s_barrier
	v_mfma_f32_16x16x32_bf16 v[128:131], v[132:135], v[164:167], v[128:131]
	v_mfma_f32_16x16x32_bf16 v[128:131], v[136:139], v[168:171], v[128:131]
	v_mfma_f32_16x16x32_bf16 v[120:123], v[136:139], v[176:179], v[120:123]
	v_mfma_f32_16x16x32_bf16 v[120:123], v[132:135], v[172:175], v[120:123]
	v_mfma_f32_16x16x32_bf16 v[112:115], v[132:135], v[180:183], v[112:115]
	v_mfma_f32_16x16x32_bf16 v[112:115], v[136:139], v[184:187], v[112:115]
	v_mfma_f32_16x16x32_bf16 v[104:107], v[136:139], v[192:195], v[104:107]
	v_mfma_f32_16x16x32_bf16 v[104:107], v[132:135], v[188:191], v[104:107]
	v_mfma_f32_16x16x32_bf16 v[100:103], v[140:143], v[188:191], v[100:103]
	v_mfma_f32_16x16x32_bf16 v[100:103], v[144:147], v[192:195], v[100:103]
	v_mfma_f32_16x16x32_bf16 v[108:111], v[144:147], v[184:187], v[108:111]
	v_mfma_f32_16x16x32_bf16 v[108:111], v[140:143], v[180:183], v[108:111]
	v_mfma_f32_16x16x32_bf16 v[116:119], v[140:143], v[172:175], v[116:119]
	v_mfma_f32_16x16x32_bf16 v[116:119], v[144:147], v[176:179], v[116:119]
	v_mfma_f32_16x16x32_bf16 v[124:127], v[144:147], v[168:171], v[124:127]
	v_mfma_f32_16x16x32_bf16 v[124:127], v[140:143], v[164:167], v[124:127]
	v_mfma_f32_16x16x32_bf16 v[96:99], v[148:151], v[164:167], v[96:99]
	v_mfma_f32_16x16x32_bf16 v[96:99], v[152:155], v[168:171], v[96:99]
	v_mfma_f32_16x16x32_bf16 v[88:91], v[152:155], v[176:179], v[88:91]
	v_mfma_f32_16x16x32_bf16 v[88:91], v[148:151], v[172:175], v[88:91]
	v_mfma_f32_16x16x32_bf16 v[64:67], v[148:151], v[180:183], v[64:67]
	v_mfma_f32_16x16x32_bf16 v[64:67], v[152:155], v[184:187], v[64:67]
	v_mfma_f32_16x16x32_bf16 v[32:35], v[152:155], v[192:195], v[32:35]
	v_mfma_f32_16x16x32_bf16 v[32:35], v[148:151], v[188:191], v[32:35]
	v_mfma_f32_16x16x32_bf16 v[20:23], v[156:159], v[188:191], v[20:23]
	v_mfma_f32_16x16x32_bf16 v[20:23], v[160:163], v[192:195], v[20:23]
	v_mfma_f32_16x16x32_bf16 v[52:55], v[160:163], v[184:187], v[52:55]
	v_mfma_f32_16x16x32_bf16 v[52:55], v[156:159], v[180:183], v[52:55]
	v_mfma_f32_16x16x32_bf16 v[80:83], v[156:159], v[172:175], v[80:83]
	v_mfma_f32_16x16x32_bf16 v[80:83], v[160:163], v[176:179], v[80:83]
	v_mfma_f32_16x16x32_bf16 v[92:95], v[160:163], v[168:171], v[92:95]
	v_mfma_f32_16x16x32_bf16 v[92:95], v[156:159], v[164:167], v[92:95]
	s_barrier
; #define PG8_STAGE(bufoff, gbase, voff) do { _Pragma("unroll") for (int _i = 0; _i < 2; ++_i) \
;         __builtin_amdgcn_global_load_lds((const unsigned*)((const char*)(gbase) + (voff)[_i]), (LAS unsigned*)(lds + (bufoff) + ldsw + _i * 8192), 16, 0, 0); } while (0)
; #define PG8_LDA(dst, b, h) do { _Pragma("unroll") for (int m = 0; m < 4; ++m) _Pragma("unroll") for (int k = 0; k < 2; ++k) dst[m][k] = *(const LAS bf16x8*)(pA + PG8_SA(b, h) + m * 2048 + k * 1024); } while (0)
; #define PG8_MMA(ai, bj, At, Bt) do { __builtin_amdgcn_s_setprio(1); _Pragma("unroll") for (int m = 0; m < 4; ++m) _Pragma("unroll") for (int n = 0; n < 2; ++n) _Pragma("unroll") for (int k = 0; k < 2; ++k) \
;         acc[ai][bj][m][n] = __builtin_amdgcn_mfma_f32_16x16x32_bf16(Bt[n][k], At[m][k], acc[ai][bj][m][n], 0, 0, 0); __builtin_amdgcn_s_setprio(0); } while (0)
; #define PG8_WAIT_V(n) asm volatile("s_waitcnt vmcnt(" #n ")" ::: "memory")
; #define PG8_WAIT_L(n) asm volatile("s_waitcnt lgkmcnt(" #n ")" ::: "memory")
; #define PG8_BAR __builtin_amdgcn_s_barrier()
; #define PG8_SCHED __builtin_amdgcn_sched_barrier(0)
; template <class Desc, class Epi, bool ALIGN_EPI>
; __device__ __forceinline__ void gemm_phase(LAS unsigned char* lds, const Desc& D, const Epi& E, int G, int c) {
;     ...
;             PG8_LDA(At, 1, 1); PG8_STAGE(PG8_SB(1, 0), b3, voffB); PG8_STAGE(PG8_SB(1, 1), b3 + hstepB, voffB); PG8_STAGE(PG8_SA(1, 0), a3, voffA);
;             PG8_WAIT_V(8); PG8_WAIT_L(0); PG8_BAR; PG8_MMA(1, 0, At, B0); PG8_MMA(1, 1, At, B1); PG8_BAR; PG8_SCHED;
;         }
	s_mov_b32 m0, s64
	v_lshl_add_u64 v[196:197], v[196:197], 0, s[76:77]
	s_add_u32 s20, s20, 0x2b0080
	ds_read_b128 v[164:167], v247 offset:49152
	ds_read_b128 v[168:171], v247 offset:50176
	ds_read_b128 v[172:175], v247 offset:51200
	ds_read_b128 v[176:179], v247 offset:52224
	ds_read_b128 v[180:183], v247 offset:53248
	ds_read_b128 v[184:187], v247 offset:54272
	ds_read_b128 v[188:191], v247 offset:55296
	ds_read_b128 v[192:195], v247 offset:56320
	global_load_lds_dwordx4 v[196:197], off
	v_lshl_add_u64 v[196:197], v[198:199], 0, s[76:77]
	s_mov_b32 m0, s65
	s_addc_u32 s21, s21, 0
	global_load_lds_dwordx4 v[196:197], off
	v_lshl_add_u64 v[196:197], s[20:21], 0, v[202:203]
	s_mov_b32 m0, s69
	s_nop 0
	global_load_lds_dwordx4 v[196:197], off
	v_lshl_add_u64 v[196:197], s[20:21], 0, v[206:207]
	s_mov_b32 m0, s70
	s_nop 0
	global_load_lds_dwordx4 v[196:197], off
	v_lshl_add_u64 v[196:197], v[208:209], 0, s[76:77]
	s_mov_b32 m0, s66
	s_nop 0
	global_load_lds_dwordx4 v[196:197], off
	v_lshl_add_u64 v[196:197], v[210:211], 0, s[76:77]
	s_mov_b32 m0, s67
	s_nop 0
	global_load_lds_dwordx4 v[196:197], off
	s_waitcnt vmcnt(8)
	s_waitcnt lgkmcnt(0)
	s_barrier
	v_mfma_f32_16x16x32_bf16 v[84:87], v[132:135], v[164:167], v[84:87]
	v_mfma_f32_16x16x32_bf16 v[84:87], v[136:139], v[168:171], v[84:87]
	v_mfma_f32_16x16x32_bf16 v[72:75], v[136:139], v[176:179], v[72:75]
	v_mfma_f32_16x16x32_bf16 v[72:75], v[132:135], v[172:175], v[72:75]
	v_mfma_f32_16x16x32_bf16 v[60:63], v[132:135], v[180:183], v[60:63]
	v_mfma_f32_16x16x32_bf16 v[60:63], v[136:139], v[184:187], v[60:63]
	v_mfma_f32_16x16x32_bf16 v[48:51], v[136:139], v[192:195], v[48:51]
	v_mfma_f32_16x16x32_bf16 v[48:51], v[132:135], v[188:191], v[48:51]
	v_mfma_f32_16x16x32_bf16 v[44:47], v[140:143], v[188:191], v[44:47]
	v_mfma_f32_16x16x32_bf16 v[44:47], v[144:147], v[192:195], v[44:47]
	v_mfma_f32_16x16x32_bf16 v[56:59], v[144:147], v[184:187], v[56:59]
	v_mfma_f32_16x16x32_bf16 v[56:59], v[140:143], v[180:183], v[56:59]
	v_mfma_f32_16x16x32_bf16 v[68:71], v[140:143], v[172:175], v[68:71]
	v_mfma_f32_16x16x32_bf16 v[68:71], v[144:147], v[176:179], v[68:71]
	v_mfma_f32_16x16x32_bf16 v[76:79], v[144:147], v[168:171], v[76:79]
	v_mfma_f32_16x16x32_bf16 v[76:79], v[140:143], v[164:167], v[76:79]
	v_mfma_f32_16x16x32_bf16 v[40:43], v[148:151], v[164:167], v[40:43]
	v_mfma_f32_16x16x32_bf16 v[40:43], v[152:155], v[168:171], v[40:43]
	v_mfma_f32_16x16x32_bf16 v[28:31], v[152:155], v[176:179], v[28:31]
	v_mfma_f32_16x16x32_bf16 v[28:31], v[148:151], v[172:175], v[28:31]
	v_mfma_f32_16x16x32_bf16 v[16:19], v[148:151], v[180:183], v[16:19]
	v_mfma_f32_16x16x32_bf16 v[16:19], v[152:155], v[184:187], v[16:19]
	v_mfma_f32_16x16x32_bf16 v[8:11], v[152:155], v[192:195], v[8:11]
	v_mfma_f32_16x16x32_bf16 v[8:11], v[148:151], v[188:191], v[8:11]
	v_mfma_f32_16x16x32_bf16 v[4:7], v[156:159], v[188:191], v[4:7]
	v_mfma_f32_16x16x32_bf16 v[4:7], v[160:163], v[192:195], v[4:7]
	v_mfma_f32_16x16x32_bf16 v[12:15], v[160:163], v[184:187], v[12:15]
	v_mfma_f32_16x16x32_bf16 v[12:15], v[156:159], v[180:183], v[12:15]
	v_mfma_f32_16x16x32_bf16 v[24:27], v[156:159], v[172:175], v[24:27]
	v_mfma_f32_16x16x32_bf16 v[24:27], v[160:163], v[176:179], v[24:27]
	v_mfma_f32_16x16x32_bf16 v[36:39], v[160:163], v[168:171], v[36:39]
	v_mfma_f32_16x16x32_bf16 v[36:39], v[156:159], v[164:167], v[36:39]
	s_barrier
	s_cmp_ge_u32 s14, s24
	s_mov_b32 s39, s14
	s_cbranch_scc1 .LBB0_1776
